# GEMM K loops: at the two load-segment heads the twelve LDS fragment reads are issued back to back, the scalar pointer bookkeeping hipcc had placed between them moved behind (20 sites); on v092
# baseline (speedup 1.0000x reference)
.LBB0_177:
	s_ashr_i32 s45, s44, 31
	v_cmp_lt_i64_e32 vcc, s[46:47], v[144:145]
	s_lshl_b64 s[46:47], s[44:45], 19
	s_add_u32 s46, s68, s46
	s_addc_u32 s47, s69, s47
	s_and_b64 s[48:49], vcc, exec
	s_cselect_b32 s11, s47, s51
	s_cselect_b32 s13, s46, s50
	s_ashr_i32 s43, s42, 31
	s_lshl_b64 s[48:49], s[42:43], 19
	s_add_u32 s48, s26, s48
	s_addc_u32 s49, s27, s49
	s_and_b64 s[54:55], vcc, exec
	s_cselect_b32 s17, s49, s53
	s_cselect_b32 s43, s48, s52
	s_add_u32 s50, s50, 0x40080
	s_addc_u32 s51, s51, 0
	s_add_u32 s45, s52, 0x100
	s_addc_u32 s91, s53, 0
	s_mov_b32 s92, -2
	s_waitcnt lgkmcnt(0)
	ds_read_b128 v[148:151], v159
	ds_read_b128 v[152:155], v159 offset:1024
	ds_read_b128 v[164:167], v159 offset:2048
	ds_read_b128 v[168:171], v159 offset:3072
	ds_read_b128 v[172:175], v160
	ds_read_b128 v[176:179], v160 offset:1024
	ds_read_b128 v[180:183], v160 offset:2048
	ds_read_b128 v[184:187], v160 offset:3072
	ds_read_b128 v[188:191], v160 offset:4096
	ds_read_b128 v[196:199], v160 offset:5120
	ds_read_b128 v[200:203], v160 offset:6144
	ds_read_b128 v[204:207], v160 offset:7168
	s_add_u32 s52, s50, 0xfffc0080
	s_addc_u32 s53, s51, -1
	s_cmp_eq_u32 s92, 12
	s_cselect_b32 s55, s11, s53
	s_cselect_b32 s54, s13, s52
	s_cselect_b32 s53, s17, s91
	s_cselect_b32 s52, s43, s45
	v_lshl_add_u64 v[156:157], s[50:51], 0, v[140:141]
	s_add_i32 m0, s58, 0xc000
	global_load_lds_dwordx4 v[156:157], off
	v_lshl_add_u64 v[156:157], s[50:51], 0, v[142:143]
	s_add_i32 m0, s58, 0xe000
	s_nop 0
	global_load_lds_dwordx4 v[156:157], off
	s_waitcnt lgkmcnt(8)
	s_barrier
	s_waitcnt lgkmcnt(0)
	v_mfma_f32_16x16x32_bf16 v[124:127], v[148:151], v[172:175], 0
	v_mfma_f32_16x16x32_bf16 v[120:123], v[164:167], v[172:175], 0
	v_mfma_f32_16x16x32_bf16 v[108:111], v[148:151], v[180:183], 0
	v_mfma_f32_16x16x32_bf16 v[104:107], v[164:167], v[180:183], 0
	v_mfma_f32_16x16x32_bf16 v[92:95], v[148:151], v[188:191], 0
	v_mfma_f32_16x16x32_bf16 v[88:91], v[164:167], v[188:191], 0
	v_mfma_f32_16x16x32_bf16 v[76:79], v[148:151], v[200:203], 0
	v_mfma_f32_16x16x32_bf16 v[72:75], v[164:167], v[200:203], 0
	v_mfma_f32_16x16x32_bf16 v[124:127], v[152:155], v[176:179], v[124:127]
	v_mfma_f32_16x16x32_bf16 v[120:123], v[168:171], v[176:179], v[120:123]
	v_mfma_f32_16x16x32_bf16 v[108:111], v[152:155], v[184:187], v[108:111]
	v_mfma_f32_16x16x32_bf16 v[104:107], v[168:171], v[184:187], v[104:107]
	v_mfma_f32_16x16x32_bf16 v[92:95], v[152:155], v[196:199], v[92:95]
	v_mfma_f32_16x16x32_bf16 v[88:91], v[168:171], v[196:199], v[88:91]
	v_mfma_f32_16x16x32_bf16 v[76:79], v[152:155], v[204:207], v[76:79]
	v_mfma_f32_16x16x32_bf16 v[72:75], v[168:171], v[204:207], v[72:75]
	s_barrier
	s_add_i32 s93, s89, s57
	v_lshl_add_u64 v[156:157], s[52:53], 0, v[130:131]
	s_mov_b32 m0, s93
	ds_read_b128 v[208:211], v161
	ds_read_b128 v[212:215], v161 offset:1024
	ds_read_b128 v[216:219], v161 offset:2048
	ds_read_b128 v[220:223], v161 offset:3072
	global_load_lds_dwordx4 v[156:157], off
	v_lshl_add_u64 v[224:225], s[52:53], 0, v[134:135]
	s_add_i32 m0, s93, 0x2000
	s_nop 0
	global_load_lds_dwordx4 v[224:225], off
	s_barrier
	s_waitcnt lgkmcnt(0)
	v_mfma_f32_16x16x32_bf16 v[116:119], v[208:211], v[172:175], 0
	v_mfma_f32_16x16x32_bf16 v[112:115], v[216:219], v[172:175], 0
	v_mfma_f32_16x16x32_bf16 v[100:103], v[208:211], v[180:183], 0
	v_mfma_f32_16x16x32_bf16 v[96:99], v[216:219], v[180:183], 0
	v_mfma_f32_16x16x32_bf16 v[84:87], v[208:211], v[188:191], 0
	v_mfma_f32_16x16x32_bf16 v[80:83], v[216:219], v[188:191], 0
	v_mfma_f32_16x16x32_bf16 v[68:71], v[208:211], v[200:203], 0
	v_mfma_f32_16x16x32_bf16 v[64:67], v[216:219], v[200:203], 0
	v_mfma_f32_16x16x32_bf16 v[116:119], v[212:215], v[176:179], v[116:119]
	v_mfma_f32_16x16x32_bf16 v[112:115], v[220:223], v[176:179], v[112:115]
	v_mfma_f32_16x16x32_bf16 v[100:103], v[212:215], v[184:187], v[100:103]
	v_mfma_f32_16x16x32_bf16 v[96:99], v[220:223], v[184:187], v[96:99]
	v_mfma_f32_16x16x32_bf16 v[84:87], v[212:215], v[196:199], v[84:87]
	v_mfma_f32_16x16x32_bf16 v[80:83], v[220:223], v[196:199], v[80:83]
	v_mfma_f32_16x16x32_bf16 v[68:71], v[212:215], v[204:207], v[68:71]
	v_mfma_f32_16x16x32_bf16 v[64:67], v[220:223], v[204:207], v[64:67]
	s_mov_b32 m0, s58
	v_lshl_add_u64 v[226:227], s[54:55], 0, v[128:129]
	s_barrier
	ds_read_b128 v[172:175], v160 offset:16384
	ds_read_b128 v[176:179], v160 offset:17408
	ds_read_b128 v[180:183], v160 offset:18432
	ds_read_b128 v[184:187], v160 offset:19456
	ds_read_b128 v[188:191], v160 offset:20480
	ds_read_b128 v[196:199], v160 offset:21504
	ds_read_b128 v[200:203], v160 offset:22528
	ds_read_b128 v[204:207], v160 offset:23552
	global_load_lds_dwordx4 v[226:227], off
	v_lshl_add_u64 v[228:229], s[54:55], 0, v[132:133]
	s_mov_b32 m0, s59
	s_nop 0
	global_load_lds_dwordx4 v[228:229], off
	s_barrier
	s_waitcnt lgkmcnt(0)
	v_mfma_f32_16x16x32_bf16 v[60:63], v[148:151], v[172:175], 0
	v_mfma_f32_16x16x32_bf16 v[56:59], v[164:167], v[172:175], 0
	v_mfma_f32_16x16x32_bf16 v[44:47], v[148:151], v[180:183], 0
	v_mfma_f32_16x16x32_bf16 v[40:43], v[164:167], v[180:183], 0
	v_mfma_f32_16x16x32_bf16 v[28:31], v[148:151], v[188:191], 0
	v_mfma_f32_16x16x32_bf16 v[24:27], v[164:167], v[188:191], 0
	v_mfma_f32_16x16x32_bf16 v[12:15], v[148:151], v[200:203], 0
	v_mfma_f32_16x16x32_bf16 v[8:11], v[164:167], v[200:203], 0
	v_mfma_f32_16x16x32_bf16 v[60:63], v[152:155], v[176:179], v[60:63]
	v_mfma_f32_16x16x32_bf16 v[56:59], v[168:171], v[176:179], v[56:59]
	v_mfma_f32_16x16x32_bf16 v[44:47], v[152:155], v[184:187], v[44:47]
	v_mfma_f32_16x16x32_bf16 v[40:43], v[168:171], v[184:187], v[40:43]
	v_mfma_f32_16x16x32_bf16 v[28:31], v[152:155], v[196:199], v[28:31]
	v_mfma_f32_16x16x32_bf16 v[24:27], v[168:171], v[196:199], v[24:27]
	v_mfma_f32_16x16x32_bf16 v[12:15], v[152:155], v[204:207], v[12:15]
	v_mfma_f32_16x16x32_bf16 v[8:11], v[168:171], v[204:207], v[8:11]
	s_barrier
	s_add_u32 s94, s52, 0x10000
	s_addc_u32 s95, s53, 0
	s_add_i32 s93, s90, s57
	v_lshl_add_u64 v[148:149], s[94:95], 0, v[130:131]
	s_mov_b32 m0, s93
	s_nop 0
	global_load_lds_dwordx4 v[148:149], off
	v_lshl_add_u64 v[148:149], s[94:95], 0, v[134:135]
	s_add_i32 m0, s93, 0x2000
	s_nop 0
	global_load_lds_dwordx4 v[148:149], off
	s_cmp_eq_u32 s98, 0
	s_cbranch_scc1 .Lk1_w4n
	s_mov_b32 s98, 0
	s_waitcnt vmcnt(24)
	s_branch .Lk1_w4j

.Lk1_w4j:
	s_barrier
	v_mfma_f32_16x16x32_bf16 v[52:55], v[208:211], v[172:175], 0
	v_mfma_f32_16x16x32_bf16 v[48:51], v[216:219], v[172:175], 0
	v_mfma_f32_16x16x32_bf16 v[36:39], v[208:211], v[180:183], 0
	v_mfma_f32_16x16x32_bf16 v[32:35], v[216:219], v[180:183], 0
	v_mfma_f32_16x16x32_bf16 v[20:23], v[208:211], v[188:191], 0
	v_mfma_f32_16x16x32_bf16 v[16:19], v[216:219], v[188:191], 0
	v_mfma_f32_16x16x32_bf16 v[4:7], v[208:211], v[200:203], 0
	v_mfma_f32_16x16x32_bf16 v[0:3], v[216:219], v[200:203], 0
	v_mfma_f32_16x16x32_bf16 v[52:55], v[212:215], v[176:179], v[52:55]
	v_mfma_f32_16x16x32_bf16 v[48:51], v[220:223], v[176:179], v[48:51]
	v_mfma_f32_16x16x32_bf16 v[36:39], v[212:215], v[184:187], v[36:39]
	v_mfma_f32_16x16x32_bf16 v[32:35], v[220:223], v[184:187], v[32:35]
	v_mfma_f32_16x16x32_bf16 v[20:23], v[212:215], v[196:199], v[20:23]
	v_mfma_f32_16x16x32_bf16 v[16:19], v[220:223], v[196:199], v[16:19]
	v_mfma_f32_16x16x32_bf16 v[4:7], v[212:215], v[204:207], v[4:7]
	v_mfma_f32_16x16x32_bf16 v[0:3], v[220:223], v[204:207], v[0:3]
	s_add_i32 s93, 0, 0x18000
	v_add_u32_e32 v136, s93, v158
	s_barrier
	ds_read_b128 v[148:151], v136
	ds_read_b128 v[152:155], v136 offset:1024
	ds_read_b128 v[164:167], v136 offset:2048
	ds_read_b128 v[168:171], v136 offset:3072
	ds_read_b128 v[172:175], v160 offset:32768
	ds_read_b128 v[176:179], v160 offset:33792
	ds_read_b128 v[180:183], v160 offset:34816
	ds_read_b128 v[184:187], v160 offset:35840
	ds_read_b128 v[188:191], v160 offset:36864
	ds_read_b128 v[196:199], v160 offset:37888
	ds_read_b128 v[200:203], v160 offset:38912
	ds_read_b128 v[204:207], v160 offset:39936
	s_add_u32 s54, s54, 0x40000
	s_addc_u32 s55, s55, 0
	s_mov_b32 m0, s60
	v_lshl_add_u64 v[208:209], s[54:55], 0, v[128:129]
	global_load_lds_dwordx4 v[208:209], off
	v_lshl_add_u64 v[208:209], s[54:55], 0, v[132:133]
	s_mov_b32 m0, s61
	s_nop 0
	global_load_lds_dwordx4 v[208:209], off
	s_waitcnt lgkmcnt(8)
	s_barrier
	s_waitcnt lgkmcnt(0)
	v_mfma_f32_16x16x32_bf16 v[124:127], v[148:151], v[172:175], v[124:127]
	v_mfma_f32_16x16x32_bf16 v[120:123], v[164:167], v[172:175], v[120:123]
	v_mfma_f32_16x16x32_bf16 v[108:111], v[148:151], v[180:183], v[108:111]
	v_mfma_f32_16x16x32_bf16 v[104:107], v[164:167], v[180:183], v[104:107]
	v_mfma_f32_16x16x32_bf16 v[92:95], v[148:151], v[188:191], v[92:95]
	v_mfma_f32_16x16x32_bf16 v[88:91], v[164:167], v[188:191], v[88:91]
	v_mfma_f32_16x16x32_bf16 v[76:79], v[148:151], v[200:203], v[76:79]
	v_mfma_f32_16x16x32_bf16 v[72:75], v[164:167], v[200:203], v[72:75]
	v_mfma_f32_16x16x32_bf16 v[124:127], v[152:155], v[176:179], v[124:127]
	v_mfma_f32_16x16x32_bf16 v[120:123], v[168:171], v[176:179], v[120:123]
	v_mfma_f32_16x16x32_bf16 v[108:111], v[152:155], v[184:187], v[108:111]
	v_mfma_f32_16x16x32_bf16 v[104:107], v[168:171], v[184:187], v[104:107]
	v_mfma_f32_16x16x32_bf16 v[92:95], v[152:155], v[196:199], v[92:95]
	v_mfma_f32_16x16x32_bf16 v[88:91], v[168:171], v[196:199], v[88:91]
	v_mfma_f32_16x16x32_bf16 v[76:79], v[152:155], v[204:207], v[76:79]
	v_mfma_f32_16x16x32_bf16 v[72:75], v[168:171], v[204:207], v[72:75]
	s_barrier
	s_add_i32 s54, 0, 0x1c000
	s_add_i32 s55, s93, s57
	v_add_u32_e32 v136, s54, v158
	v_lshl_add_u64 v[156:157], v[156:157], 0, s[0:1]
	s_mov_b32 m0, s55
	ds_read_b128 v[208:211], v136
	ds_read_b128 v[212:215], v136 offset:1024
	ds_read_b128 v[216:219], v136 offset:2048
	ds_read_b128 v[220:223], v136 offset:3072
	global_load_lds_dwordx4 v[156:157], off
	v_lshl_add_u64 v[156:157], v[224:225], 0, s[0:1]
	s_add_i32 m0, s55, 0x2000
	s_nop 0
	global_load_lds_dwordx4 v[156:157], off
	s_barrier
	s_waitcnt lgkmcnt(0)
	v_mfma_f32_16x16x32_bf16 v[116:119], v[208:211], v[172:175], v[116:119]
	v_mfma_f32_16x16x32_bf16 v[112:115], v[216:219], v[172:175], v[112:115]
	v_mfma_f32_16x16x32_bf16 v[100:103], v[208:211], v[180:183], v[100:103]
	v_mfma_f32_16x16x32_bf16 v[96:99], v[216:219], v[180:183], v[96:99]
	v_mfma_f32_16x16x32_bf16 v[84:87], v[208:211], v[188:191], v[84:87]
	v_mfma_f32_16x16x32_bf16 v[80:83], v[216:219], v[188:191], v[80:83]
	v_mfma_f32_16x16x32_bf16 v[68:71], v[208:211], v[200:203], v[68:71]
	v_mfma_f32_16x16x32_bf16 v[64:67], v[216:219], v[200:203], v[64:67]
	v_mfma_f32_16x16x32_bf16 v[116:119], v[212:215], v[176:179], v[116:119]
	v_mfma_f32_16x16x32_bf16 v[112:115], v[220:223], v[176:179], v[112:115]
	v_mfma_f32_16x16x32_bf16 v[100:103], v[212:215], v[184:187], v[100:103]
	v_mfma_f32_16x16x32_bf16 v[96:99], v[220:223], v[184:187], v[96:99]
	v_mfma_f32_16x16x32_bf16 v[84:87], v[212:215], v[196:199], v[84:87]
	v_mfma_f32_16x16x32_bf16 v[80:83], v[220:223], v[196:199], v[80:83]
	v_mfma_f32_16x16x32_bf16 v[68:71], v[212:215], v[204:207], v[68:71]
	v_mfma_f32_16x16x32_bf16 v[64:67], v[220:223], v[204:207], v[64:67]
	s_mov_b32 m0, s65
	v_lshl_add_u64 v[156:157], v[226:227], 0, s[0:1]
	s_waitcnt vmcnt(10)
	s_barrier
	ds_read_b128 v[172:175], v160 offset:49152
	ds_read_b128 v[176:179], v160 offset:50176
	ds_read_b128 v[180:183], v160 offset:51200
	ds_read_b128 v[184:187], v160 offset:52224
	ds_read_b128 v[188:191], v160 offset:53248
	ds_read_b128 v[196:199], v160 offset:54272
	ds_read_b128 v[200:203], v160 offset:55296
	ds_read_b128 v[204:207], v160 offset:56320
	global_load_lds_dwordx4 v[156:157], off
	v_lshl_add_u64 v[156:157], v[228:229], 0, s[0:1]
	s_mov_b32 m0, s66
	s_nop 0
	global_load_lds_dwordx4 v[156:157], off
	s_barrier
	s_waitcnt lgkmcnt(0)
	v_mfma_f32_16x16x32_bf16 v[60:63], v[148:151], v[172:175], v[60:63]
	v_mfma_f32_16x16x32_bf16 v[56:59], v[164:167], v[172:175], v[56:59]
	v_mfma_f32_16x16x32_bf16 v[44:47], v[148:151], v[180:183], v[44:47]
	v_mfma_f32_16x16x32_bf16 v[40:43], v[164:167], v[180:183], v[40:43]
	v_mfma_f32_16x16x32_bf16 v[28:31], v[148:151], v[188:191], v[28:31]
	v_mfma_f32_16x16x32_bf16 v[24:27], v[164:167], v[188:191], v[24:27]
	v_mfma_f32_16x16x32_bf16 v[12:15], v[148:151], v[200:203], v[12:15]
	v_mfma_f32_16x16x32_bf16 v[8:11], v[164:167], v[200:203], v[8:11]
	v_mfma_f32_16x16x32_bf16 v[60:63], v[152:155], v[176:179], v[60:63]
	v_mfma_f32_16x16x32_bf16 v[56:59], v[168:171], v[176:179], v[56:59]
	v_mfma_f32_16x16x32_bf16 v[44:47], v[152:155], v[184:187], v[44:47]
	v_mfma_f32_16x16x32_bf16 v[40:43], v[168:171], v[184:187], v[40:43]
	v_mfma_f32_16x16x32_bf16 v[28:31], v[152:155], v[196:199], v[28:31]
	v_mfma_f32_16x16x32_bf16 v[24:27], v[168:171], v[196:199], v[24:27]
	v_mfma_f32_16x16x32_bf16 v[12:15], v[152:155], v[204:207], v[12:15]
	v_mfma_f32_16x16x32_bf16 v[8:11], v[168:171], v[204:207], v[8:11]
	s_barrier
	s_add_u32 s52, s52, 0x10080
	s_addc_u32 s53, s53, 0
	s_add_i32 s54, s54, s57
	v_lshl_add_u64 v[148:149], s[52:53], 0, v[130:131]
	s_mov_b32 m0, s54
	s_nop 0
	global_load_lds_dwordx4 v[148:149], off
	v_lshl_add_u64 v[148:149], s[52:53], 0, v[134:135]
	s_add_i32 m0, s54, 0x2000
	s_nop 0
	global_load_lds_dwordx4 v[148:149], off
	s_waitcnt vmcnt(6)
	s_barrier
	v_mfma_f32_16x16x32_bf16 v[52:55], v[208:211], v[172:175], v[52:55]
	v_mfma_f32_16x16x32_bf16 v[48:51], v[216:219], v[172:175], v[48:51]
	v_mfma_f32_16x16x32_bf16 v[36:39], v[208:211], v[180:183], v[36:39]
	v_mfma_f32_16x16x32_bf16 v[32:35], v[216:219], v[180:183], v[32:35]
	v_mfma_f32_16x16x32_bf16 v[20:23], v[208:211], v[188:191], v[20:23]
	v_mfma_f32_16x16x32_bf16 v[16:19], v[216:219], v[188:191], v[16:19]
	v_mfma_f32_16x16x32_bf16 v[4:7], v[208:211], v[200:203], v[4:7]
	v_mfma_f32_16x16x32_bf16 v[0:3], v[216:219], v[200:203], v[0:3]
	v_mfma_f32_16x16x32_bf16 v[52:55], v[212:215], v[176:179], v[52:55]
	v_mfma_f32_16x16x32_bf16 v[48:51], v[220:223], v[176:179], v[48:51]
	v_mfma_f32_16x16x32_bf16 v[36:39], v[212:215], v[184:187], v[36:39]
	v_mfma_f32_16x16x32_bf16 v[32:35], v[220:223], v[184:187], v[32:35]
	v_mfma_f32_16x16x32_bf16 v[20:23], v[212:215], v[196:199], v[20:23]
	v_mfma_f32_16x16x32_bf16 v[16:19], v[220:223], v[196:199], v[16:19]
	v_mfma_f32_16x16x32_bf16 v[4:7], v[212:215], v[204:207], v[4:7]
	v_mfma_f32_16x16x32_bf16 v[0:3], v[220:223], v[204:207], v[0:3]
	s_add_i32 s92, s92, 2
	s_add_u32 s50, s50, 0x100
	s_addc_u32 s51, s51, 0
	s_add_u32 s45, s45, 0x100
	s_addc_u32 s91, s91, 0
	s_cmp_gt_u32 s92, 13
	s_barrier
	s_cbranch_scc0 .LBB0_178
.LBB0_178:
	ds_read_b128 v[148:151], v159
	ds_read_b128 v[152:155], v159 offset:1024
	ds_read_b128 v[164:167], v159 offset:2048
	ds_read_b128 v[168:171], v159 offset:3072
	ds_read_b128 v[172:175], v160
	ds_read_b128 v[176:179], v160 offset:1024
	ds_read_b128 v[180:183], v160 offset:2048
	ds_read_b128 v[184:187], v160 offset:3072
	ds_read_b128 v[188:191], v160 offset:4096
	ds_read_b128 v[196:199], v160 offset:5120
	ds_read_b128 v[200:203], v160 offset:6144
	ds_read_b128 v[204:207], v160 offset:7168
	s_add_u32 s52, s50, 0xfffc0080
	s_addc_u32 s53, s51, -1
	s_cmp_eq_u32 s92, 12
	s_cselect_b32 s55, s11, s53
	s_cselect_b32 s54, s13, s52
	s_cselect_b32 s53, s17, s91
	s_cselect_b32 s52, s43, s45
	v_lshl_add_u64 v[156:157], s[50:51], 0, v[140:141]
	s_add_i32 m0, s58, 0xc000
	global_load_lds_dwordx4 v[156:157], off
	v_lshl_add_u64 v[156:157], s[50:51], 0, v[142:143]
	s_add_i32 m0, s58, 0xe000
	s_nop 0
	global_load_lds_dwordx4 v[156:157], off
	s_waitcnt lgkmcnt(8)
	s_barrier
	s_waitcnt lgkmcnt(0)
	v_mfma_f32_16x16x32_bf16 v[124:127], v[148:151], v[172:175], v[124:127]
	v_mfma_f32_16x16x32_bf16 v[120:123], v[164:167], v[172:175], v[120:123]
	v_mfma_f32_16x16x32_bf16 v[108:111], v[148:151], v[180:183], v[108:111]
	v_mfma_f32_16x16x32_bf16 v[104:107], v[164:167], v[180:183], v[104:107]
	v_mfma_f32_16x16x32_bf16 v[92:95], v[148:151], v[188:191], v[92:95]
	v_mfma_f32_16x16x32_bf16 v[88:91], v[164:167], v[188:191], v[88:91]
	v_mfma_f32_16x16x32_bf16 v[76:79], v[148:151], v[200:203], v[76:79]
	v_mfma_f32_16x16x32_bf16 v[72:75], v[164:167], v[200:203], v[72:75]
	v_mfma_f32_16x16x32_bf16 v[124:127], v[152:155], v[176:179], v[124:127]
	v_mfma_f32_16x16x32_bf16 v[120:123], v[168:171], v[176:179], v[120:123]
	v_mfma_f32_16x16x32_bf16 v[108:111], v[152:155], v[184:187], v[108:111]
	v_mfma_f32_16x16x32_bf16 v[104:107], v[168:171], v[184:187], v[104:107]
	v_mfma_f32_16x16x32_bf16 v[92:95], v[152:155], v[196:199], v[92:95]
	v_mfma_f32_16x16x32_bf16 v[88:91], v[168:171], v[196:199], v[88:91]
	v_mfma_f32_16x16x32_bf16 v[76:79], v[152:155], v[204:207], v[76:79]
	v_mfma_f32_16x16x32_bf16 v[72:75], v[168:171], v[204:207], v[72:75]
	s_barrier
	s_add_i32 s93, s89, s57
	v_lshl_add_u64 v[156:157], s[52:53], 0, v[130:131]
	s_mov_b32 m0, s93
	ds_read_b128 v[208:211], v161
	ds_read_b128 v[212:215], v161 offset:1024
	ds_read_b128 v[216:219], v161 offset:2048
	ds_read_b128 v[220:223], v161 offset:3072
	global_load_lds_dwordx4 v[156:157], off
	v_lshl_add_u64 v[224:225], s[52:53], 0, v[134:135]
	s_add_i32 m0, s93, 0x2000
	s_nop 0
	global_load_lds_dwordx4 v[224:225], off
	s_barrier
	s_waitcnt lgkmcnt(0)
	v_mfma_f32_16x16x32_bf16 v[116:119], v[208:211], v[172:175], v[116:119]
	v_mfma_f32_16x16x32_bf16 v[112:115], v[216:219], v[172:175], v[112:115]
	v_mfma_f32_16x16x32_bf16 v[100:103], v[208:211], v[180:183], v[100:103]
	v_mfma_f32_16x16x32_bf16 v[96:99], v[216:219], v[180:183], v[96:99]
	v_mfma_f32_16x16x32_bf16 v[84:87], v[208:211], v[188:191], v[84:87]
	v_mfma_f32_16x16x32_bf16 v[80:83], v[216:219], v[188:191], v[80:83]
	v_mfma_f32_16x16x32_bf16 v[68:71], v[208:211], v[200:203], v[68:71]
	v_mfma_f32_16x16x32_bf16 v[64:67], v[216:219], v[200:203], v[64:67]
	v_mfma_f32_16x16x32_bf16 v[116:119], v[212:215], v[176:179], v[116:119]
	v_mfma_f32_16x16x32_bf16 v[112:115], v[220:223], v[176:179], v[112:115]
	v_mfma_f32_16x16x32_bf16 v[100:103], v[212:215], v[184:187], v[100:103]
	v_mfma_f32_16x16x32_bf16 v[96:99], v[220:223], v[184:187], v[96:99]
	v_mfma_f32_16x16x32_bf16 v[84:87], v[212:215], v[196:199], v[84:87]
	v_mfma_f32_16x16x32_bf16 v[80:83], v[220:223], v[196:199], v[80:83]
	v_mfma_f32_16x16x32_bf16 v[68:71], v[212:215], v[204:207], v[68:71]
	v_mfma_f32_16x16x32_bf16 v[64:67], v[220:223], v[204:207], v[64:67]
	s_mov_b32 m0, s58
	v_lshl_add_u64 v[226:227], s[54:55], 0, v[128:129]
	s_barrier
	ds_read_b128 v[172:175], v160 offset:16384
	ds_read_b128 v[176:179], v160 offset:17408
	ds_read_b128 v[180:183], v160 offset:18432
	ds_read_b128 v[184:187], v160 offset:19456
	ds_read_b128 v[188:191], v160 offset:20480
	ds_read_b128 v[196:199], v160 offset:21504
	ds_read_b128 v[200:203], v160 offset:22528
	ds_read_b128 v[204:207], v160 offset:23552
	global_load_lds_dwordx4 v[226:227], off
	v_lshl_add_u64 v[228:229], s[54:55], 0, v[132:133]
	s_mov_b32 m0, s59
	s_nop 0
	global_load_lds_dwordx4 v[228:229], off
	s_barrier
	s_waitcnt lgkmcnt(0)
	v_mfma_f32_16x16x32_bf16 v[60:63], v[148:151], v[172:175], v[60:63]
	v_mfma_f32_16x16x32_bf16 v[56:59], v[164:167], v[172:175], v[56:59]
	v_mfma_f32_16x16x32_bf16 v[44:47], v[148:151], v[180:183], v[44:47]
	v_mfma_f32_16x16x32_bf16 v[40:43], v[164:167], v[180:183], v[40:43]
	v_mfma_f32_16x16x32_bf16 v[28:31], v[148:151], v[188:191], v[28:31]
	v_mfma_f32_16x16x32_bf16 v[24:27], v[164:167], v[188:191], v[24:27]
	v_mfma_f32_16x16x32_bf16 v[12:15], v[148:151], v[200:203], v[12:15]
	v_mfma_f32_16x16x32_bf16 v[8:11], v[164:167], v[200:203], v[8:11]
	v_mfma_f32_16x16x32_bf16 v[60:63], v[152:155], v[176:179], v[60:63]
	v_mfma_f32_16x16x32_bf16 v[56:59], v[168:171], v[176:179], v[56:59]
	v_mfma_f32_16x16x32_bf16 v[44:47], v[152:155], v[184:187], v[44:47]
	v_mfma_f32_16x16x32_bf16 v[40:43], v[168:171], v[184:187], v[40:43]
	v_mfma_f32_16x16x32_bf16 v[28:31], v[152:155], v[196:199], v[28:31]
	v_mfma_f32_16x16x32_bf16 v[24:27], v[168:171], v[196:199], v[24:27]
	v_mfma_f32_16x16x32_bf16 v[12:15], v[152:155], v[204:207], v[12:15]
	v_mfma_f32_16x16x32_bf16 v[8:11], v[168:171], v[204:207], v[8:11]
	s_barrier
	s_add_u32 s94, s52, 0x10000
	s_addc_u32 s95, s53, 0
	s_add_i32 s93, s90, s57
	v_lshl_add_u64 v[148:149], s[94:95], 0, v[130:131]
	s_mov_b32 m0, s93
	s_nop 0
	global_load_lds_dwordx4 v[148:149], off
	v_lshl_add_u64 v[148:149], s[94:95], 0, v[134:135]
	s_add_i32 m0, s93, 0x2000
	s_nop 0
	global_load_lds_dwordx4 v[148:149], off
	s_waitcnt vmcnt(6)
	s_barrier
	v_mfma_f32_16x16x32_bf16 v[52:55], v[208:211], v[172:175], v[52:55]
	v_mfma_f32_16x16x32_bf16 v[48:51], v[216:219], v[172:175], v[48:51]
	v_mfma_f32_16x16x32_bf16 v[36:39], v[208:211], v[180:183], v[36:39]
	v_mfma_f32_16x16x32_bf16 v[32:35], v[216:219], v[180:183], v[32:35]
	v_mfma_f32_16x16x32_bf16 v[20:23], v[208:211], v[188:191], v[20:23]
	v_mfma_f32_16x16x32_bf16 v[16:19], v[216:219], v[188:191], v[16:19]
	v_mfma_f32_16x16x32_bf16 v[4:7], v[208:211], v[200:203], v[4:7]
	v_mfma_f32_16x16x32_bf16 v[0:3], v[216:219], v[200:203], v[0:3]
	v_mfma_f32_16x16x32_bf16 v[52:55], v[212:215], v[176:179], v[52:55]
	v_mfma_f32_16x16x32_bf16 v[48:51], v[220:223], v[176:179], v[48:51]
	v_mfma_f32_16x16x32_bf16 v[36:39], v[212:215], v[184:187], v[36:39]
	v_mfma_f32_16x16x32_bf16 v[32:35], v[220:223], v[184:187], v[32:35]
	v_mfma_f32_16x16x32_bf16 v[20:23], v[212:215], v[196:199], v[20:23]
	v_mfma_f32_16x16x32_bf16 v[16:19], v[220:223], v[196:199], v[16:19]
	v_mfma_f32_16x16x32_bf16 v[4:7], v[212:215], v[204:207], v[4:7]
	v_mfma_f32_16x16x32_bf16 v[0:3], v[220:223], v[204:207], v[0:3]
	s_add_i32 s93, 0, 0x18000
	v_add_u32_e32 v136, s93, v158
	s_barrier
	ds_read_b128 v[148:151], v136
	ds_read_b128 v[152:155], v136 offset:1024
	ds_read_b128 v[164:167], v136 offset:2048
	ds_read_b128 v[168:171], v136 offset:3072
	ds_read_b128 v[172:175], v160 offset:32768
	ds_read_b128 v[176:179], v160 offset:33792
	ds_read_b128 v[180:183], v160 offset:34816
	ds_read_b128 v[184:187], v160 offset:35840
	ds_read_b128 v[188:191], v160 offset:36864
	ds_read_b128 v[196:199], v160 offset:37888
	ds_read_b128 v[200:203], v160 offset:38912
	ds_read_b128 v[204:207], v160 offset:39936
	s_add_u32 s54, s54, 0x40000
	s_addc_u32 s55, s55, 0
	s_mov_b32 m0, s60
	v_lshl_add_u64 v[208:209], s[54:55], 0, v[128:129]
	global_load_lds_dwordx4 v[208:209], off
	v_lshl_add_u64 v[208:209], s[54:55], 0, v[132:133]
	s_mov_b32 m0, s61
	s_nop 0
	global_load_lds_dwordx4 v[208:209], off
	s_waitcnt lgkmcnt(8)
	s_barrier
	s_waitcnt lgkmcnt(0)
	v_mfma_f32_16x16x32_bf16 v[124:127], v[148:151], v[172:175], v[124:127]
	v_mfma_f32_16x16x32_bf16 v[120:123], v[164:167], v[172:175], v[120:123]
	v_mfma_f32_16x16x32_bf16 v[108:111], v[148:151], v[180:183], v[108:111]
	v_mfma_f32_16x16x32_bf16 v[104:107], v[164:167], v[180:183], v[104:107]
	v_mfma_f32_16x16x32_bf16 v[92:95], v[148:151], v[188:191], v[92:95]
	v_mfma_f32_16x16x32_bf16 v[88:91], v[164:167], v[188:191], v[88:91]
	v_mfma_f32_16x16x32_bf16 v[76:79], v[148:151], v[200:203], v[76:79]
	v_mfma_f32_16x16x32_bf16 v[72:75], v[164:167], v[200:203], v[72:75]
	v_mfma_f32_16x16x32_bf16 v[124:127], v[152:155], v[176:179], v[124:127]
	v_mfma_f32_16x16x32_bf16 v[120:123], v[168:171], v[176:179], v[120:123]
	v_mfma_f32_16x16x32_bf16 v[108:111], v[152:155], v[184:187], v[108:111]
	v_mfma_f32_16x16x32_bf16 v[104:107], v[168:171], v[184:187], v[104:107]
	v_mfma_f32_16x16x32_bf16 v[92:95], v[152:155], v[196:199], v[92:95]
	v_mfma_f32_16x16x32_bf16 v[88:91], v[168:171], v[196:199], v[88:91]
	v_mfma_f32_16x16x32_bf16 v[76:79], v[152:155], v[204:207], v[76:79]
	v_mfma_f32_16x16x32_bf16 v[72:75], v[168:171], v[204:207], v[72:75]
	s_barrier
	s_add_i32 s54, 0, 0x1c000
	s_add_i32 s55, s93, s57
	v_add_u32_e32 v136, s54, v158
	v_lshl_add_u64 v[156:157], v[156:157], 0, s[0:1]
	s_mov_b32 m0, s55
	ds_read_b128 v[208:211], v136
	ds_read_b128 v[212:215], v136 offset:1024
	ds_read_b128 v[216:219], v136 offset:2048
	ds_read_b128 v[220:223], v136 offset:3072
	global_load_lds_dwordx4 v[156:157], off
	v_lshl_add_u64 v[156:157], v[224:225], 0, s[0:1]
	s_add_i32 m0, s55, 0x2000
	s_nop 0
	global_load_lds_dwordx4 v[156:157], off
	s_barrier
	s_waitcnt lgkmcnt(0)
	v_mfma_f32_16x16x32_bf16 v[116:119], v[208:211], v[172:175], v[116:119]
	v_mfma_f32_16x16x32_bf16 v[112:115], v[216:219], v[172:175], v[112:115]
	v_mfma_f32_16x16x32_bf16 v[100:103], v[208:211], v[180:183], v[100:103]
	v_mfma_f32_16x16x32_bf16 v[96:99], v[216:219], v[180:183], v[96:99]
	v_mfma_f32_16x16x32_bf16 v[84:87], v[208:211], v[188:191], v[84:87]
	v_mfma_f32_16x16x32_bf16 v[80:83], v[216:219], v[188:191], v[80:83]
	v_mfma_f32_16x16x32_bf16 v[68:71], v[208:211], v[200:203], v[68:71]
	v_mfma_f32_16x16x32_bf16 v[64:67], v[216:219], v[200:203], v[64:67]
	v_mfma_f32_16x16x32_bf16 v[116:119], v[212:215], v[176:179], v[116:119]
	v_mfma_f32_16x16x32_bf16 v[112:115], v[220:223], v[176:179], v[112:115]
	v_mfma_f32_16x16x32_bf16 v[100:103], v[212:215], v[184:187], v[100:103]
	v_mfma_f32_16x16x32_bf16 v[96:99], v[220:223], v[184:187], v[96:99]
	v_mfma_f32_16x16x32_bf16 v[84:87], v[212:215], v[196:199], v[84:87]
	v_mfma_f32_16x16x32_bf16 v[80:83], v[220:223], v[196:199], v[80:83]
	v_mfma_f32_16x16x32_bf16 v[68:71], v[212:215], v[204:207], v[68:71]
	v_mfma_f32_16x16x32_bf16 v[64:67], v[220:223], v[204:207], v[64:67]
	s_mov_b32 m0, s65
	v_lshl_add_u64 v[156:157], v[226:227], 0, s[0:1]
	s_barrier
	ds_read_b128 v[172:175], v160 offset:49152
	ds_read_b128 v[176:179], v160 offset:50176
	ds_read_b128 v[180:183], v160 offset:51200
	ds_read_b128 v[184:187], v160 offset:52224
	ds_read_b128 v[188:191], v160 offset:53248
	ds_read_b128 v[196:199], v160 offset:54272
	ds_read_b128 v[200:203], v160 offset:55296
	ds_read_b128 v[204:207], v160 offset:56320
	global_load_lds_dwordx4 v[156:157], off
	v_lshl_add_u64 v[156:157], v[228:229], 0, s[0:1]
	s_mov_b32 m0, s66
	s_nop 0
	global_load_lds_dwordx4 v[156:157], off
	s_barrier
	s_waitcnt lgkmcnt(0)
	v_mfma_f32_16x16x32_bf16 v[60:63], v[148:151], v[172:175], v[60:63]
	v_mfma_f32_16x16x32_bf16 v[56:59], v[164:167], v[172:175], v[56:59]
	v_mfma_f32_16x16x32_bf16 v[44:47], v[148:151], v[180:183], v[44:47]
	v_mfma_f32_16x16x32_bf16 v[40:43], v[164:167], v[180:183], v[40:43]
	v_mfma_f32_16x16x32_bf16 v[28:31], v[148:151], v[188:191], v[28:31]
	v_mfma_f32_16x16x32_bf16 v[24:27], v[164:167], v[188:191], v[24:27]
	v_mfma_f32_16x16x32_bf16 v[12:15], v[148:151], v[200:203], v[12:15]
	v_mfma_f32_16x16x32_bf16 v[8:11], v[164:167], v[200:203], v[8:11]
	v_mfma_f32_16x16x32_bf16 v[60:63], v[152:155], v[176:179], v[60:63]
	v_mfma_f32_16x16x32_bf16 v[56:59], v[168:171], v[176:179], v[56:59]
	v_mfma_f32_16x16x32_bf16 v[44:47], v[152:155], v[184:187], v[44:47]
	v_mfma_f32_16x16x32_bf16 v[40:43], v[168:171], v[184:187], v[40:43]
	v_mfma_f32_16x16x32_bf16 v[28:31], v[152:155], v[196:199], v[28:31]
	v_mfma_f32_16x16x32_bf16 v[24:27], v[168:171], v[196:199], v[24:27]
	v_mfma_f32_16x16x32_bf16 v[12:15], v[152:155], v[204:207], v[12:15]
	v_mfma_f32_16x16x32_bf16 v[8:11], v[168:171], v[204:207], v[8:11]
	s_barrier
	s_add_u32 s52, s52, 0x10080
	s_addc_u32 s53, s53, 0
	s_add_i32 s54, s54, s57
	v_lshl_add_u64 v[148:149], s[52:53], 0, v[130:131]
	s_mov_b32 m0, s54
	s_nop 0
	global_load_lds_dwordx4 v[148:149], off
	v_lshl_add_u64 v[148:149], s[52:53], 0, v[134:135]
	s_add_i32 m0, s54, 0x2000
	s_nop 0
	global_load_lds_dwordx4 v[148:149], off
	s_waitcnt vmcnt(6)
	s_barrier
	v_mfma_f32_16x16x32_bf16 v[52:55], v[208:211], v[172:175], v[52:55]
	v_mfma_f32_16x16x32_bf16 v[48:51], v[216:219], v[172:175], v[48:51]
	v_mfma_f32_16x16x32_bf16 v[36:39], v[208:211], v[180:183], v[36:39]
	v_mfma_f32_16x16x32_bf16 v[32:35], v[216:219], v[180:183], v[32:35]
	v_mfma_f32_16x16x32_bf16 v[20:23], v[208:211], v[188:191], v[20:23]
	v_mfma_f32_16x16x32_bf16 v[16:19], v[216:219], v[188:191], v[16:19]
	v_mfma_f32_16x16x32_bf16 v[4:7], v[208:211], v[200:203], v[4:7]
	v_mfma_f32_16x16x32_bf16 v[0:3], v[216:219], v[200:203], v[0:3]
	v_mfma_f32_16x16x32_bf16 v[52:55], v[212:215], v[176:179], v[52:55]
	v_mfma_f32_16x16x32_bf16 v[48:51], v[220:223], v[176:179], v[48:51]
	v_mfma_f32_16x16x32_bf16 v[36:39], v[212:215], v[184:187], v[36:39]
	v_mfma_f32_16x16x32_bf16 v[32:35], v[220:223], v[184:187], v[32:35]
	v_mfma_f32_16x16x32_bf16 v[20:23], v[212:215], v[196:199], v[20:23]
	v_mfma_f32_16x16x32_bf16 v[16:19], v[220:223], v[196:199], v[16:19]
	v_mfma_f32_16x16x32_bf16 v[4:7], v[212:215], v[204:207], v[4:7]
	v_mfma_f32_16x16x32_bf16 v[0:3], v[220:223], v[204:207], v[0:3]
	s_add_i32 s92, s92, 2
	s_add_u32 s50, s50, 0x100
	s_addc_u32 s51, s51, 0
	s_add_u32 s45, s45, 0x100
	s_addc_u32 s91, s91, 0
	s_cmp_gt_u32 s92, 13
	s_barrier
	s_cbranch_scc0 .LBB0_178
	v_lshl_add_u32 v148, s12, 8, v139
	v_and_b32_e32 v149, 24, v138
	s_lshl_b32 s11, s10, 8
	s_or_b32 s11, s11, s87
	s_cmp_gt_i32 s10, 11
	s_cbranch_scc1 .Le1_gates
	s_lshr_b32 s13, s10, 1
	s_lshl_b32 s50, s13, 25
	s_add_u32 s50, s20, s50
	s_addc_u32 s51, s21, 0
	s_bfe_u32 s17, s11, 0x30006
	v_ashrrev_i32_e32 v150, 8, v148
	v_and_or_b32 v150, v150, -8, s17
	v_mov_b32_e32 v151, 0
	v_lshlrev_b64 v[150:151], 18, v[150:151]
	v_lshlrev_b32_e32 v136, 7, v148
	v_and_b32_e32 v136, 0x3ff80, v136
	v_lshl_add_u32 v136, v149, 1, v136
	v_lshl_add_u64 v[150:151], v[150:151], 0, v[136:137]
	v_lshl_add_u64 v[150:151], v[150:151], 0, s[50:51]
	s_movk_i32 s11, 0x800
	s_movk_i32 s17, 0x2800
	s_branch .Le1_addr

.LBB0_342:
	ds_read_b128 v[146:149], v143
	ds_read_b128 v[150:153], v143 offset:1024
	ds_read_b128 v[154:157], v143 offset:2048
	ds_read_b128 v[158:161], v143 offset:3072
	ds_read_b128 v[162:165], v144
	ds_read_b128 v[166:169], v144 offset:1024
	ds_read_b128 v[170:173], v144 offset:2048
	ds_read_b128 v[174:177], v144 offset:3072
	ds_read_b128 v[178:181], v144 offset:4096
	ds_read_b128 v[182:185], v144 offset:5120
	ds_read_b128 v[186:189], v144 offset:6144
	ds_read_b128 v[196:199], v144 offset:7168
	s_add_u32 s46, s44, 0xfffc0080
	s_addc_u32 s47, s45, -1
	s_cmp_eq_u32 s67, 12
	s_cselect_b32 s49, s9, s47
	s_cselect_b32 s48, s63, s46
	s_cselect_b32 s47, s7, s66
	s_cselect_b32 s46, s64, s65
	v_lshl_add_u64 v[190:191], s[44:45], 0, v[136:137]
	s_add_i32 m0, s43, 0xc000
	global_load_lds_dwordx4 v[190:191], off
	v_lshl_add_u64 v[190:191], s[44:45], 0, v[138:139]
	s_add_i32 m0, s43, 0xe000
	s_nop 0
	global_load_lds_dwordx4 v[190:191], off
	s_waitcnt lgkmcnt(8)
	s_barrier
	s_waitcnt lgkmcnt(0)
	v_mfma_f32_16x16x32_bf16 v[124:127], v[146:149], v[162:165], v[124:127]
	v_mfma_f32_16x16x32_bf16 v[120:123], v[154:157], v[162:165], v[120:123]
	v_mfma_f32_16x16x32_bf16 v[108:111], v[146:149], v[170:173], v[108:111]
	v_mfma_f32_16x16x32_bf16 v[104:107], v[154:157], v[170:173], v[104:107]
	v_mfma_f32_16x16x32_bf16 v[92:95], v[146:149], v[178:181], v[92:95]
	v_mfma_f32_16x16x32_bf16 v[88:91], v[154:157], v[178:181], v[88:91]
	v_mfma_f32_16x16x32_bf16 v[76:79], v[146:149], v[186:189], v[76:79]
	v_mfma_f32_16x16x32_bf16 v[72:75], v[154:157], v[186:189], v[72:75]
	v_mfma_f32_16x16x32_bf16 v[124:127], v[150:153], v[166:169], v[124:127]
	v_mfma_f32_16x16x32_bf16 v[120:123], v[158:161], v[166:169], v[120:123]
	v_mfma_f32_16x16x32_bf16 v[108:111], v[150:153], v[174:177], v[108:111]
	v_mfma_f32_16x16x32_bf16 v[104:107], v[158:161], v[174:177], v[104:107]
	v_mfma_f32_16x16x32_bf16 v[92:95], v[150:153], v[182:185], v[92:95]
	v_mfma_f32_16x16x32_bf16 v[88:91], v[158:161], v[182:185], v[88:91]
	v_mfma_f32_16x16x32_bf16 v[76:79], v[150:153], v[196:199], v[76:79]
	v_mfma_f32_16x16x32_bf16 v[72:75], v[158:161], v[196:199], v[72:75]
	s_barrier
	s_add_i32 s84, s60, s50
	v_lshl_add_u64 v[190:191], s[46:47], 0, v[132:133]
	s_mov_b32 m0, s84
	ds_read_b128 v[200:203], v145
	ds_read_b128 v[204:207], v145 offset:1024
	ds_read_b128 v[208:211], v145 offset:2048
	ds_read_b128 v[212:215], v145 offset:3072
	global_load_lds_dwordx4 v[190:191], off
	v_lshl_add_u64 v[216:217], s[46:47], 0, v[128:129]
	s_add_i32 m0, s84, 0x2000
	s_nop 0
	global_load_lds_dwordx4 v[216:217], off
	s_barrier
	s_waitcnt lgkmcnt(0)
	v_mfma_f32_16x16x32_bf16 v[116:119], v[200:203], v[162:165], v[116:119]
	v_mfma_f32_16x16x32_bf16 v[112:115], v[208:211], v[162:165], v[112:115]
	v_mfma_f32_16x16x32_bf16 v[100:103], v[200:203], v[170:173], v[100:103]
	v_mfma_f32_16x16x32_bf16 v[96:99], v[208:211], v[170:173], v[96:99]
	v_mfma_f32_16x16x32_bf16 v[84:87], v[200:203], v[178:181], v[84:87]
	v_mfma_f32_16x16x32_bf16 v[80:83], v[208:211], v[178:181], v[80:83]
	v_mfma_f32_16x16x32_bf16 v[68:71], v[200:203], v[186:189], v[68:71]
	v_mfma_f32_16x16x32_bf16 v[64:67], v[208:211], v[186:189], v[64:67]
	v_mfma_f32_16x16x32_bf16 v[116:119], v[204:207], v[166:169], v[116:119]
	v_mfma_f32_16x16x32_bf16 v[112:115], v[212:215], v[166:169], v[112:115]
	v_mfma_f32_16x16x32_bf16 v[100:103], v[204:207], v[174:177], v[100:103]
	v_mfma_f32_16x16x32_bf16 v[96:99], v[212:215], v[174:177], v[96:99]
	v_mfma_f32_16x16x32_bf16 v[84:87], v[204:207], v[182:185], v[84:87]
	v_mfma_f32_16x16x32_bf16 v[80:83], v[212:215], v[182:185], v[80:83]
	v_mfma_f32_16x16x32_bf16 v[68:71], v[204:207], v[196:199], v[68:71]
	v_mfma_f32_16x16x32_bf16 v[64:67], v[212:215], v[196:199], v[64:67]
	s_mov_b32 m0, s43
	v_lshl_add_u64 v[218:219], s[48:49], 0, v[134:135]
	s_barrier
	ds_read_b128 v[162:165], v144 offset:16384
	ds_read_b128 v[166:169], v144 offset:17408
	ds_read_b128 v[170:173], v144 offset:18432
	ds_read_b128 v[174:177], v144 offset:19456
	ds_read_b128 v[178:181], v144 offset:20480
	ds_read_b128 v[182:185], v144 offset:21504
	ds_read_b128 v[186:189], v144 offset:22528
	ds_read_b128 v[196:199], v144 offset:23552
	global_load_lds_dwordx4 v[218:219], off
	v_lshl_add_u64 v[220:221], s[48:49], 0, v[130:131]
	s_mov_b32 m0, s52
	s_nop 0
	global_load_lds_dwordx4 v[220:221], off
	s_barrier
	s_waitcnt lgkmcnt(0)
	v_mfma_f32_16x16x32_bf16 v[60:63], v[146:149], v[162:165], v[60:63]
	v_mfma_f32_16x16x32_bf16 v[56:59], v[154:157], v[162:165], v[56:59]
	v_mfma_f32_16x16x32_bf16 v[44:47], v[146:149], v[170:173], v[44:47]
	v_mfma_f32_16x16x32_bf16 v[40:43], v[154:157], v[170:173], v[40:43]
	v_mfma_f32_16x16x32_bf16 v[28:31], v[146:149], v[178:181], v[28:31]
	v_mfma_f32_16x16x32_bf16 v[24:27], v[154:157], v[178:181], v[24:27]
	v_mfma_f32_16x16x32_bf16 v[12:15], v[146:149], v[186:189], v[12:15]
	v_mfma_f32_16x16x32_bf16 v[8:11], v[154:157], v[186:189], v[8:11]
	v_mfma_f32_16x16x32_bf16 v[60:63], v[150:153], v[166:169], v[60:63]
	v_mfma_f32_16x16x32_bf16 v[56:59], v[158:161], v[166:169], v[56:59]
	v_mfma_f32_16x16x32_bf16 v[44:47], v[150:153], v[174:177], v[44:47]
	v_mfma_f32_16x16x32_bf16 v[40:43], v[158:161], v[174:177], v[40:43]
	v_mfma_f32_16x16x32_bf16 v[28:31], v[150:153], v[182:185], v[28:31]
	v_mfma_f32_16x16x32_bf16 v[24:27], v[158:161], v[182:185], v[24:27]
	v_mfma_f32_16x16x32_bf16 v[12:15], v[150:153], v[196:199], v[12:15]
	v_mfma_f32_16x16x32_bf16 v[8:11], v[158:161], v[196:199], v[8:11]
	s_barrier
	s_add_u32 s84, s46, 0x10000
	s_addc_u32 s85, s47, 0
	s_add_i32 s89, s61, s50
	v_lshl_add_u64 v[146:147], s[84:85], 0, v[132:133]
	s_mov_b32 m0, s89
	s_nop 0
	global_load_lds_dwordx4 v[146:147], off
	v_lshl_add_u64 v[146:147], s[84:85], 0, v[128:129]
	s_add_i32 m0, s89, 0x2000
	s_nop 0
	global_load_lds_dwordx4 v[146:147], off
	s_waitcnt vmcnt(6)
	s_barrier
	v_mfma_f32_16x16x32_bf16 v[52:55], v[200:203], v[162:165], v[52:55]
	v_mfma_f32_16x16x32_bf16 v[48:51], v[208:211], v[162:165], v[48:51]
	v_mfma_f32_16x16x32_bf16 v[36:39], v[200:203], v[170:173], v[36:39]
	v_mfma_f32_16x16x32_bf16 v[32:35], v[208:211], v[170:173], v[32:35]
	v_mfma_f32_16x16x32_bf16 v[20:23], v[200:203], v[178:181], v[20:23]
	v_mfma_f32_16x16x32_bf16 v[16:19], v[208:211], v[178:181], v[16:19]
	v_mfma_f32_16x16x32_bf16 v[4:7], v[200:203], v[186:189], v[4:7]
	v_mfma_f32_16x16x32_bf16 v[0:3], v[208:211], v[186:189], v[0:3]
	v_mfma_f32_16x16x32_bf16 v[52:55], v[204:207], v[166:169], v[52:55]
	v_mfma_f32_16x16x32_bf16 v[48:51], v[212:215], v[166:169], v[48:51]
	v_mfma_f32_16x16x32_bf16 v[36:39], v[204:207], v[174:177], v[36:39]
	v_mfma_f32_16x16x32_bf16 v[32:35], v[212:215], v[174:177], v[32:35]
	v_mfma_f32_16x16x32_bf16 v[20:23], v[204:207], v[182:185], v[20:23]
	v_mfma_f32_16x16x32_bf16 v[16:19], v[212:215], v[182:185], v[16:19]
	v_mfma_f32_16x16x32_bf16 v[4:7], v[204:207], v[196:199], v[4:7]
	v_mfma_f32_16x16x32_bf16 v[0:3], v[212:215], v[196:199], v[0:3]
	s_add_i32 s84, 0, 0x18000
	v_add_u32_e32 v158, s84, v141
	s_barrier
	ds_read_b128 v[146:149], v158
	ds_read_b128 v[150:153], v158 offset:1024
	ds_read_b128 v[154:157], v158 offset:2048
	ds_read_b128 v[158:161], v158 offset:3072
	ds_read_b128 v[162:165], v144 offset:32768
	ds_read_b128 v[166:169], v144 offset:33792
	ds_read_b128 v[170:173], v144 offset:34816
	ds_read_b128 v[174:177], v144 offset:35840
	ds_read_b128 v[178:181], v144 offset:36864
	ds_read_b128 v[182:185], v144 offset:37888
	ds_read_b128 v[186:189], v144 offset:38912
	ds_read_b128 v[196:199], v144 offset:39936
	s_add_u32 s48, s48, 0x40000
	s_addc_u32 s49, s49, 0
	s_mov_b32 m0, s53
	v_lshl_add_u64 v[200:201], s[48:49], 0, v[134:135]
	global_load_lds_dwordx4 v[200:201], off
	v_lshl_add_u64 v[200:201], s[48:49], 0, v[130:131]
	s_mov_b32 m0, s54
	s_nop 0
	global_load_lds_dwordx4 v[200:201], off
	s_waitcnt lgkmcnt(8)
	s_barrier
	s_waitcnt lgkmcnt(0)
	v_mfma_f32_16x16x32_bf16 v[124:127], v[146:149], v[162:165], v[124:127]
	v_mfma_f32_16x16x32_bf16 v[120:123], v[154:157], v[162:165], v[120:123]
	v_mfma_f32_16x16x32_bf16 v[108:111], v[146:149], v[170:173], v[108:111]
	v_mfma_f32_16x16x32_bf16 v[104:107], v[154:157], v[170:173], v[104:107]
	v_mfma_f32_16x16x32_bf16 v[92:95], v[146:149], v[178:181], v[92:95]
	v_mfma_f32_16x16x32_bf16 v[88:91], v[154:157], v[178:181], v[88:91]
	v_mfma_f32_16x16x32_bf16 v[76:79], v[146:149], v[186:189], v[76:79]
	v_mfma_f32_16x16x32_bf16 v[72:75], v[154:157], v[186:189], v[72:75]
	v_mfma_f32_16x16x32_bf16 v[124:127], v[150:153], v[166:169], v[124:127]
	v_mfma_f32_16x16x32_bf16 v[120:123], v[158:161], v[166:169], v[120:123]
	v_mfma_f32_16x16x32_bf16 v[108:111], v[150:153], v[174:177], v[108:111]
	v_mfma_f32_16x16x32_bf16 v[104:107], v[158:161], v[174:177], v[104:107]
	v_mfma_f32_16x16x32_bf16 v[92:95], v[150:153], v[182:185], v[92:95]
	v_mfma_f32_16x16x32_bf16 v[88:91], v[158:161], v[182:185], v[88:91]
	v_mfma_f32_16x16x32_bf16 v[76:79], v[150:153], v[196:199], v[76:79]
	v_mfma_f32_16x16x32_bf16 v[72:75], v[158:161], v[196:199], v[72:75]
	s_barrier
	s_add_i32 s48, 0, 0x1c000
	s_add_i32 s49, s84, s50
	v_add_u32_e32 v195, s48, v141
	v_lshl_add_u64 v[190:191], v[190:191], 0, s[0:1]
	s_mov_b32 m0, s49
	ds_read_b128 v[200:203], v195
	ds_read_b128 v[204:207], v195 offset:1024
	ds_read_b128 v[208:211], v195 offset:2048
	ds_read_b128 v[212:215], v195 offset:3072
	global_load_lds_dwordx4 v[190:191], off
	v_lshl_add_u64 v[190:191], v[216:217], 0, s[0:1]
	s_add_i32 m0, s49, 0x2000
	s_nop 0
	global_load_lds_dwordx4 v[190:191], off
	s_barrier
	s_waitcnt lgkmcnt(0)
	v_mfma_f32_16x16x32_bf16 v[116:119], v[200:203], v[162:165], v[116:119]
	v_mfma_f32_16x16x32_bf16 v[112:115], v[208:211], v[162:165], v[112:115]
	v_mfma_f32_16x16x32_bf16 v[100:103], v[200:203], v[170:173], v[100:103]
	v_mfma_f32_16x16x32_bf16 v[96:99], v[208:211], v[170:173], v[96:99]
	v_mfma_f32_16x16x32_bf16 v[84:87], v[200:203], v[178:181], v[84:87]
	v_mfma_f32_16x16x32_bf16 v[80:83], v[208:211], v[178:181], v[80:83]
	v_mfma_f32_16x16x32_bf16 v[68:71], v[200:203], v[186:189], v[68:71]
	v_mfma_f32_16x16x32_bf16 v[64:67], v[208:211], v[186:189], v[64:67]
	v_mfma_f32_16x16x32_bf16 v[116:119], v[204:207], v[166:169], v[116:119]
	v_mfma_f32_16x16x32_bf16 v[112:115], v[212:215], v[166:169], v[112:115]
	v_mfma_f32_16x16x32_bf16 v[100:103], v[204:207], v[174:177], v[100:103]
	v_mfma_f32_16x16x32_bf16 v[96:99], v[212:215], v[174:177], v[96:99]
	v_mfma_f32_16x16x32_bf16 v[84:87], v[204:207], v[182:185], v[84:87]
	v_mfma_f32_16x16x32_bf16 v[80:83], v[212:215], v[182:185], v[80:83]
	v_mfma_f32_16x16x32_bf16 v[68:71], v[204:207], v[196:199], v[68:71]
	v_mfma_f32_16x16x32_bf16 v[64:67], v[212:215], v[196:199], v[64:67]
	s_mov_b32 m0, s57
	v_lshl_add_u64 v[190:191], v[218:219], 0, s[0:1]
	s_barrier
	ds_read_b128 v[162:165], v144 offset:49152
	ds_read_b128 v[166:169], v144 offset:50176
	ds_read_b128 v[170:173], v144 offset:51200
	ds_read_b128 v[174:177], v144 offset:52224
	ds_read_b128 v[178:181], v144 offset:53248
	ds_read_b128 v[182:185], v144 offset:54272
	ds_read_b128 v[186:189], v144 offset:55296
	ds_read_b128 v[196:199], v144 offset:56320
	global_load_lds_dwordx4 v[190:191], off
	v_lshl_add_u64 v[190:191], v[220:221], 0, s[0:1]
	s_mov_b32 m0, s58
	s_nop 0
	global_load_lds_dwordx4 v[190:191], off
	s_barrier
	s_waitcnt lgkmcnt(0)
	v_mfma_f32_16x16x32_bf16 v[60:63], v[146:149], v[162:165], v[60:63]
	v_mfma_f32_16x16x32_bf16 v[56:59], v[154:157], v[162:165], v[56:59]
	v_mfma_f32_16x16x32_bf16 v[44:47], v[146:149], v[170:173], v[44:47]
	v_mfma_f32_16x16x32_bf16 v[40:43], v[154:157], v[170:173], v[40:43]
	v_mfma_f32_16x16x32_bf16 v[28:31], v[146:149], v[178:181], v[28:31]
	v_mfma_f32_16x16x32_bf16 v[24:27], v[154:157], v[178:181], v[24:27]
	v_mfma_f32_16x16x32_bf16 v[12:15], v[146:149], v[186:189], v[12:15]
	v_mfma_f32_16x16x32_bf16 v[8:11], v[154:157], v[186:189], v[8:11]
	v_mfma_f32_16x16x32_bf16 v[60:63], v[150:153], v[166:169], v[60:63]
	v_mfma_f32_16x16x32_bf16 v[56:59], v[158:161], v[166:169], v[56:59]
	v_mfma_f32_16x16x32_bf16 v[44:47], v[150:153], v[174:177], v[44:47]
	v_mfma_f32_16x16x32_bf16 v[40:43], v[158:161], v[174:177], v[40:43]
	v_mfma_f32_16x16x32_bf16 v[28:31], v[150:153], v[182:185], v[28:31]
	v_mfma_f32_16x16x32_bf16 v[24:27], v[158:161], v[182:185], v[24:27]
	v_mfma_f32_16x16x32_bf16 v[12:15], v[150:153], v[196:199], v[12:15]
	v_mfma_f32_16x16x32_bf16 v[8:11], v[158:161], v[196:199], v[8:11]
	s_barrier
	s_add_u32 s46, s46, 0x10080
	s_addc_u32 s47, s47, 0
	s_add_i32 s48, s48, s50
	v_lshl_add_u64 v[146:147], s[46:47], 0, v[132:133]
	s_mov_b32 m0, s48
	s_nop 0
	global_load_lds_dwordx4 v[146:147], off
	v_lshl_add_u64 v[146:147], s[46:47], 0, v[128:129]
	s_add_i32 m0, s48, 0x2000
	s_nop 0
	global_load_lds_dwordx4 v[146:147], off
	s_waitcnt vmcnt(6)
	s_barrier
	v_mfma_f32_16x16x32_bf16 v[52:55], v[200:203], v[162:165], v[52:55]
	v_mfma_f32_16x16x32_bf16 v[48:51], v[208:211], v[162:165], v[48:51]
	v_mfma_f32_16x16x32_bf16 v[36:39], v[200:203], v[170:173], v[36:39]
	v_mfma_f32_16x16x32_bf16 v[32:35], v[208:211], v[170:173], v[32:35]
	v_mfma_f32_16x16x32_bf16 v[20:23], v[200:203], v[178:181], v[20:23]
	v_mfma_f32_16x16x32_bf16 v[16:19], v[208:211], v[178:181], v[16:19]
	v_mfma_f32_16x16x32_bf16 v[4:7], v[200:203], v[186:189], v[4:7]
	v_mfma_f32_16x16x32_bf16 v[0:3], v[208:211], v[186:189], v[0:3]
	v_mfma_f32_16x16x32_bf16 v[52:55], v[204:207], v[166:169], v[52:55]
	v_mfma_f32_16x16x32_bf16 v[48:51], v[212:215], v[166:169], v[48:51]
	v_mfma_f32_16x16x32_bf16 v[36:39], v[204:207], v[174:177], v[36:39]
	v_mfma_f32_16x16x32_bf16 v[32:35], v[212:215], v[174:177], v[32:35]
	v_mfma_f32_16x16x32_bf16 v[20:23], v[204:207], v[182:185], v[20:23]
	v_mfma_f32_16x16x32_bf16 v[16:19], v[212:215], v[182:185], v[16:19]
	v_mfma_f32_16x16x32_bf16 v[4:7], v[204:207], v[196:199], v[4:7]
	v_mfma_f32_16x16x32_bf16 v[0:3], v[212:215], v[196:199], v[0:3]
	s_add_i32 s67, s67, 2
	s_add_u32 s44, s44, 0x100
	s_addc_u32 s45, s45, 0
	s_add_u32 s65, s65, 0x100
	s_addc_u32 s66, s66, 0
	s_cmp_gt_u32 s67, 13
	s_barrier
	s_cbranch_scc0 .LBB0_342
	v_cvt_pk_bf16_f32 v124, v124, v125
	v_cvt_pk_bf16_f32 v120, v120, v121
	v_cvt_pk_bf16_f32 v121, v122, v123
	v_cvt_pk_bf16_f32 v122, v116, v117
	v_cvt_pk_bf16_f32 v112, v112, v113
	v_cvt_pk_bf16_f32 v125, v126, v127
	v_cvt_pk_bf16_f32 v118, v118, v119
	v_cvt_pk_bf16_f32 v113, v114, v115
	v_cndmask_b32_e64 v114, v124, v122, s[2:3]
	v_mov_b32_e32 v123, 0
	v_cndmask_b32_e64 v115, v120, v112, s[2:3]
	v_mov_b32_e32 v126, 0
	v_lshl_add_u32 v148, s42, 8, v140
	v_mov_b32_dpp v123, v114 row_ror:8 row_mask:0xf bank_mask:0xf
	v_cndmask_b32_e64 v114, v125, v118, s[2:3]
	v_mov_b32_e32 v119, 0
	v_mov_b32_dpp v126, v115 row_ror:8 row_mask:0xf bank_mask:0xf
	v_mov_b32_e32 v127, 0
	v_mov_b32_dpp v119, v114 row_ror:8 row_mask:0xf bank_mask:0xf
	v_cndmask_b32_e64 v114, v121, v113, s[2:3]
	v_cndmask_b32_e64 v116, v126, v120, s[2:3]
	v_cndmask_b32_e64 v120, v112, v126, s[2:3]
	v_add_u32_e32 v112, -8, v148
	v_mov_b32_dpp v127, v114 row_ror:8 row_mask:0xf bank_mask:0xf
	v_cndmask_b32_e64 v112, v112, v148, s[2:3]
	v_lshl_or_b32 v146, s62, 8, v142
	v_cndmask_b32_e64 v117, v127, v121, s[2:3]
	v_cndmask_b32_e64 v121, v113, v127, s[2:3]
	v_ashrrev_i32_e32 v113, 31, v112
	v_ashrrev_i32_e32 v147, 31, v146
	v_lshlrev_b64 v[112:113], 11, v[112:113]
	v_cndmask_b32_e64 v115, v119, v125, s[2:3]
	v_cndmask_b32_e64 v114, v123, v124, s[2:3]
	v_cndmask_b32_e64 v119, v118, v119, s[2:3]
	v_cndmask_b32_e64 v118, v122, v123, s[2:3]
	v_lshl_add_u64 v[122:123], s[40:41], 0, v[112:113]
	v_lshlrev_b64 v[112:113], 1, v[146:147]
	v_lshl_add_u64 v[122:123], v[122:123], 0, v[112:113]
	global_store_dwordx4 v[122:123], v[114:117], off
	v_cvt_pk_bf16_f32 v108, v108, v109
	v_cvt_pk_bf16_f32 v100, v100, v101
	v_add_u32_e32 v116, 8, v148
	v_cndmask_b32_e64 v114, v148, v116, s[2:3]
	v_ashrrev_i32_e32 v115, 31, v114
	v_lshlrev_b64 v[114:115], 11, v[114:115]
	v_lshl_add_u64 v[114:115], s[40:41], 0, v[114:115]
	v_cvt_pk_bf16_f32 v109, v110, v111
	v_cvt_pk_bf16_f32 v104, v104, v105
	v_cvt_pk_bf16_f32 v105, v106, v107
	v_cvt_pk_bf16_f32 v101, v102, v103
	v_cvt_pk_bf16_f32 v102, v96, v97
	v_cndmask_b32_e64 v96, v108, v100, s[2:3]
	v_mov_b32_e32 v106, 0
	v_lshl_add_u64 v[114:115], v[114:115], 0, v[112:113]
	v_cvt_pk_bf16_f32 v103, v98, v99
	v_mov_b32_dpp v106, v96 row_ror:8 row_mask:0xf bank_mask:0xf
	v_cndmask_b32_e64 v96, v109, v101, s[2:3]
	v_mov_b32_e32 v107, 0
	v_cndmask_b32_e64 v97, v104, v102, s[2:3]
	v_mov_b32_e32 v110, 0
	global_store_dwordx4 v[114:115], v[118:121], off
	v_or_b32_e32 v114, 16, v148
	v_mov_b32_dpp v107, v96 row_ror:8 row_mask:0xf bank_mask:0xf
	v_cndmask_b32_e64 v96, v105, v103, s[2:3]
	v_mov_b32_dpp v110, v97 row_ror:8 row_mask:0xf bank_mask:0xf
	v_mov_b32_e32 v111, 0
	v_cndmask_b32_e64 v98, v110, v104, s[2:3]
	v_cndmask_b32_e64 v104, v116, v114, s[2:3]
	v_mov_b32_dpp v111, v96 row_ror:8 row_mask:0xf bank_mask:0xf
	v_cndmask_b32_e64 v99, v111, v105, s[2:3]
	v_ashrrev_i32_e32 v105, 31, v104
	v_lshlrev_b64 v[104:105], 11, v[104:105]
	v_lshl_add_u64 v[104:105], s[40:41], 0, v[104:105]
	v_cndmask_b32_e64 v97, v107, v109, s[2:3]
	v_cndmask_b32_e64 v96, v106, v108, s[2:3]
	v_lshl_add_u64 v[104:105], v[104:105], 0, v[112:113]
	global_store_dwordx4 v[104:105], v[96:99], off
	v_cvt_pk_bf16_f32 v92, v92, v93
	v_cvt_pk_bf16_f32 v84, v84, v85
	v_add_u32_e32 v98, 24, v148
	v_cndmask_b32_e64 v96, v114, v98, s[2:3]
	v_ashrrev_i32_e32 v97, 31, v96
	v_lshlrev_b64 v[96:97], 11, v[96:97]
	v_lshl_add_u64 v[96:97], s[40:41], 0, v[96:97]
	v_cvt_pk_bf16_f32 v93, v94, v95
	v_cvt_pk_bf16_f32 v88, v88, v89
	v_cvt_pk_bf16_f32 v89, v90, v91
	v_cvt_pk_bf16_f32 v85, v86, v87
	v_cvt_pk_bf16_f32 v86, v80, v81
	v_cndmask_b32_e64 v80, v92, v84, s[2:3]
	v_mov_b32_e32 v90, 0
	v_cndmask_b32_e64 v103, v103, v111, s[2:3]
	v_cndmask_b32_e64 v102, v102, v110, s[2:3]
	v_cndmask_b32_e64 v101, v101, v107, s[2:3]
	v_cndmask_b32_e64 v100, v100, v106, s[2:3]
	v_lshl_add_u64 v[96:97], v[96:97], 0, v[112:113]
	v_cvt_pk_bf16_f32 v87, v82, v83
	v_mov_b32_dpp v90, v80 row_ror:8 row_mask:0xf bank_mask:0xf
	v_cndmask_b32_e64 v80, v93, v85, s[2:3]
	v_mov_b32_e32 v91, 0
	v_cndmask_b32_e64 v81, v88, v86, s[2:3]
	v_mov_b32_e32 v94, 0
	global_store_dwordx4 v[96:97], v[100:103], off
	v_or_b32_e32 v96, 32, v148
	v_mov_b32_dpp v91, v80 row_ror:8 row_mask:0xf bank_mask:0xf
	v_cndmask_b32_e64 v80, v89, v87, s[2:3]
	v_mov_b32_dpp v94, v81 row_ror:8 row_mask:0xf bank_mask:0xf
	v_mov_b32_e32 v95, 0
	v_cndmask_b32_e64 v82, v94, v88, s[2:3]
	v_cndmask_b32_e64 v88, v98, v96, s[2:3]
	v_mov_b32_dpp v95, v80 row_ror:8 row_mask:0xf bank_mask:0xf
	v_cndmask_b32_e64 v83, v95, v89, s[2:3]
	v_ashrrev_i32_e32 v89, 31, v88
	v_lshlrev_b64 v[88:89], 11, v[88:89]
	v_lshl_add_u64 v[88:89], s[40:41], 0, v[88:89]
	v_cndmask_b32_e64 v81, v91, v93, s[2:3]
	v_cndmask_b32_e64 v80, v90, v92, s[2:3]
	v_lshl_add_u64 v[88:89], v[88:89], 0, v[112:113]
	global_store_dwordx4 v[88:89], v[80:83], off
	v_cvt_pk_bf16_f32 v76, v76, v77
	v_cvt_pk_bf16_f32 v68, v68, v69
	v_add_u32_e32 v82, 40, v148
	v_cndmask_b32_e64 v80, v96, v82, s[2:3]
	v_ashrrev_i32_e32 v81, 31, v80
	v_lshlrev_b64 v[80:81], 11, v[80:81]
	v_lshl_add_u64 v[80:81], s[40:41], 0, v[80:81]
	v_cvt_pk_bf16_f32 v77, v78, v79
	v_cvt_pk_bf16_f32 v72, v72, v73
	v_cvt_pk_bf16_f32 v73, v74, v75
	v_cvt_pk_bf16_f32 v69, v70, v71
	v_cvt_pk_bf16_f32 v70, v64, v65
	v_cndmask_b32_e64 v64, v76, v68, s[2:3]
	v_mov_b32_e32 v74, 0
	v_cndmask_b32_e64 v87, v87, v95, s[2:3]
	v_cndmask_b32_e64 v86, v86, v94, s[2:3]
	v_cndmask_b32_e64 v85, v85, v91, s[2:3]
	v_cndmask_b32_e64 v84, v84, v90, s[2:3]
	v_lshl_add_u64 v[80:81], v[80:81], 0, v[112:113]
	v_cvt_pk_bf16_f32 v71, v66, v67
	v_mov_b32_dpp v74, v64 row_ror:8 row_mask:0xf bank_mask:0xf
	v_cndmask_b32_e64 v64, v77, v69, s[2:3]
	v_mov_b32_e32 v75, 0
	v_cndmask_b32_e64 v65, v72, v70, s[2:3]
	v_mov_b32_e32 v78, 0
	global_store_dwordx4 v[80:81], v[84:87], off
	v_or_b32_e32 v80, 48, v148
	v_mov_b32_dpp v75, v64 row_ror:8 row_mask:0xf bank_mask:0xf
	v_cndmask_b32_e64 v64, v73, v71, s[2:3]
	v_mov_b32_dpp v78, v65 row_ror:8 row_mask:0xf bank_mask:0xf
	v_mov_b32_e32 v79, 0
	v_cndmask_b32_e64 v66, v78, v72, s[2:3]
	v_cndmask_b32_e64 v72, v82, v80, s[2:3]
	v_mov_b32_dpp v79, v64 row_ror:8 row_mask:0xf bank_mask:0xf
	v_cndmask_b32_e64 v67, v79, v73, s[2:3]
	v_ashrrev_i32_e32 v73, 31, v72
	v_lshlrev_b64 v[72:73], 11, v[72:73]
	v_lshl_add_u64 v[72:73], s[40:41], 0, v[72:73]
	v_cndmask_b32_e64 v65, v75, v77, s[2:3]
	v_cndmask_b32_e64 v64, v74, v76, s[2:3]
	v_lshl_add_u64 v[72:73], v[72:73], 0, v[112:113]
	global_store_dwordx4 v[72:73], v[64:67], off
	v_cvt_pk_bf16_f32 v60, v60, v61
	v_cvt_pk_bf16_f32 v56, v56, v57
	v_add_u32_e32 v64, 56, v148
	v_cndmask_b32_e64 v64, v80, v64, s[2:3]
	v_ashrrev_i32_e32 v65, 31, v64
	v_lshlrev_b64 v[64:65], 11, v[64:65]
	v_cvt_pk_bf16_f32 v52, v52, v53
	v_cvt_pk_bf16_f32 v53, v54, v55
	v_cvt_pk_bf16_f32 v54, v48, v49
	v_lshl_add_u64 v[64:65], s[40:41], 0, v[64:65]
	v_cvt_pk_bf16_f32 v61, v62, v63
	v_cvt_pk_bf16_f32 v57, v58, v59
	v_cndmask_b32_e64 v48, v60, v52, s[2:3]
	v_mov_b32_e32 v58, 0
	v_cndmask_b32_e64 v49, v56, v54, s[2:3]
	v_mov_b32_e32 v62, 0
	v_cndmask_b32_e64 v71, v71, v79, s[2:3]
	v_cndmask_b32_e64 v70, v70, v78, s[2:3]
	v_cndmask_b32_e64 v69, v69, v75, s[2:3]
	v_cndmask_b32_e64 v68, v68, v74, s[2:3]
	v_lshl_add_u64 v[64:65], v[64:65], 0, v[112:113]
	v_cvt_pk_bf16_f32 v55, v50, v51
	v_mov_b32_dpp v58, v48 row_ror:8 row_mask:0xf bank_mask:0xf
	v_cndmask_b32_e64 v48, v61, v53, s[2:3]
	v_mov_b32_e32 v59, 0
	v_mov_b32_dpp v62, v49 row_ror:8 row_mask:0xf bank_mask:0xf
	global_store_dwordx4 v[64:65], v[68:71], off
	v_add_u32_e32 v64, 0x80, v148
	v_mov_b32_dpp v59, v48 row_ror:8 row_mask:0xf bank_mask:0xf
	v_cndmask_b32_e64 v48, v57, v55, s[2:3]
	v_mov_b32_e32 v63, 0
	v_cndmask_b32_e64 v50, v62, v56, s[2:3]
	v_add_u32_e32 v56, 0x78, v148
	v_mov_b32_dpp v63, v48 row_ror:8 row_mask:0xf bank_mask:0xf
	v_cndmask_b32_e64 v56, v56, v64, s[2:3]
	v_cndmask_b32_e64 v51, v63, v57, s[2:3]
	v_ashrrev_i32_e32 v57, 31, v56
	v_lshlrev_b64 v[56:57], 11, v[56:57]
	v_lshl_add_u64 v[56:57], s[40:41], 0, v[56:57]
	v_cndmask_b32_e64 v49, v59, v61, s[2:3]
	v_cndmask_b32_e64 v48, v58, v60, s[2:3]
	v_lshl_add_u64 v[56:57], v[56:57], 0, v[112:113]
	global_store_dwordx4 v[56:57], v[48:51], off
	v_cvt_pk_bf16_f32 v44, v44, v45
	v_cvt_pk_bf16_f32 v36, v36, v37
	v_add_u32_e32 v50, 0x88, v148
	v_cndmask_b32_e64 v48, v64, v50, s[2:3]
	v_ashrrev_i32_e32 v49, 31, v48
	v_lshlrev_b64 v[48:49], 11, v[48:49]
	v_lshl_add_u64 v[48:49], s[40:41], 0, v[48:49]
	v_cvt_pk_bf16_f32 v45, v46, v47
	v_cvt_pk_bf16_f32 v40, v40, v41
	v_cvt_pk_bf16_f32 v41, v42, v43
	v_cvt_pk_bf16_f32 v37, v38, v39
	v_cvt_pk_bf16_f32 v38, v32, v33
	v_cndmask_b32_e64 v32, v44, v36, s[2:3]
	v_mov_b32_e32 v42, 0
	v_cndmask_b32_e64 v55, v55, v63, s[2:3]
	v_cndmask_b32_e64 v54, v54, v62, s[2:3]
	v_cndmask_b32_e64 v53, v53, v59, s[2:3]
	v_cndmask_b32_e64 v52, v52, v58, s[2:3]
	v_lshl_add_u64 v[48:49], v[48:49], 0, v[112:113]
	v_cvt_pk_bf16_f32 v39, v34, v35
	v_mov_b32_dpp v42, v32 row_ror:8 row_mask:0xf bank_mask:0xf
	v_cndmask_b32_e64 v32, v45, v37, s[2:3]
	v_mov_b32_e32 v43, 0
	v_cndmask_b32_e64 v33, v40, v38, s[2:3]
	v_mov_b32_e32 v46, 0
	global_store_dwordx4 v[48:49], v[52:55], off
	v_add_u32_e32 v48, 0x90, v148
	v_mov_b32_dpp v43, v32 row_ror:8 row_mask:0xf bank_mask:0xf
	v_cndmask_b32_e64 v32, v41, v39, s[2:3]
	v_mov_b32_dpp v46, v33 row_ror:8 row_mask:0xf bank_mask:0xf
	v_mov_b32_e32 v47, 0
	v_cndmask_b32_e64 v34, v46, v40, s[2:3]
	v_cndmask_b32_e64 v40, v50, v48, s[2:3]
	v_mov_b32_dpp v47, v32 row_ror:8 row_mask:0xf bank_mask:0xf
	v_cndmask_b32_e64 v35, v47, v41, s[2:3]
	v_ashrrev_i32_e32 v41, 31, v40
	v_lshlrev_b64 v[40:41], 11, v[40:41]
	v_lshl_add_u64 v[40:41], s[40:41], 0, v[40:41]
	v_cndmask_b32_e64 v33, v43, v45, s[2:3]
	v_cndmask_b32_e64 v32, v42, v44, s[2:3]
	v_lshl_add_u64 v[40:41], v[40:41], 0, v[112:113]
	global_store_dwordx4 v[40:41], v[32:35], off
	v_cvt_pk_bf16_f32 v28, v28, v29
	v_cvt_pk_bf16_f32 v20, v20, v21
	v_add_u32_e32 v34, 0x98, v148
	v_cndmask_b32_e64 v32, v48, v34, s[2:3]
	v_ashrrev_i32_e32 v33, 31, v32
	v_lshlrev_b64 v[32:33], 11, v[32:33]
	v_lshl_add_u64 v[32:33], s[40:41], 0, v[32:33]
	v_cvt_pk_bf16_f32 v29, v30, v31
	v_cvt_pk_bf16_f32 v24, v24, v25
	v_cvt_pk_bf16_f32 v25, v26, v27
	v_cvt_pk_bf16_f32 v21, v22, v23
	v_cvt_pk_bf16_f32 v22, v16, v17
	v_cndmask_b32_e64 v16, v28, v20, s[2:3]
	v_mov_b32_e32 v26, 0
	v_cndmask_b32_e64 v39, v39, v47, s[2:3]
	v_cndmask_b32_e64 v38, v38, v46, s[2:3]
	v_cndmask_b32_e64 v37, v37, v43, s[2:3]
	v_cndmask_b32_e64 v36, v36, v42, s[2:3]
	v_lshl_add_u64 v[32:33], v[32:33], 0, v[112:113]
	v_cvt_pk_bf16_f32 v23, v18, v19
	v_mov_b32_dpp v26, v16 row_ror:8 row_mask:0xf bank_mask:0xf
	v_cndmask_b32_e64 v16, v29, v21, s[2:3]
	v_mov_b32_e32 v27, 0
	v_cndmask_b32_e64 v17, v24, v22, s[2:3]
	v_mov_b32_e32 v30, 0
	global_store_dwordx4 v[32:33], v[36:39], off
	v_add_u32_e32 v32, 0xa0, v148
	v_mov_b32_dpp v27, v16 row_ror:8 row_mask:0xf bank_mask:0xf
	v_cndmask_b32_e64 v16, v25, v23, s[2:3]
	v_mov_b32_dpp v30, v17 row_ror:8 row_mask:0xf bank_mask:0xf
	v_mov_b32_e32 v31, 0
	v_cndmask_b32_e64 v18, v30, v24, s[2:3]
	v_cndmask_b32_e64 v24, v34, v32, s[2:3]
	v_mov_b32_dpp v31, v16 row_ror:8 row_mask:0xf bank_mask:0xf
	v_cndmask_b32_e64 v19, v31, v25, s[2:3]
	v_ashrrev_i32_e32 v25, 31, v24
	v_lshlrev_b64 v[24:25], 11, v[24:25]
	v_lshl_add_u64 v[24:25], s[40:41], 0, v[24:25]
	v_cndmask_b32_e64 v17, v27, v29, s[2:3]
	v_cndmask_b32_e64 v16, v26, v28, s[2:3]
	v_lshl_add_u64 v[24:25], v[24:25], 0, v[112:113]
	global_store_dwordx4 v[24:25], v[16:19], off
	v_cndmask_b32_e64 v23, v23, v31, s[2:3]
	v_cndmask_b32_e64 v22, v22, v30, s[2:3]
	v_add_u32_e32 v18, 0xa8, v148
	v_cndmask_b32_e64 v16, v32, v18, s[2:3]
	v_ashrrev_i32_e32 v17, 31, v16
	v_lshlrev_b64 v[16:17], 11, v[16:17]
	v_lshl_add_u64 v[16:17], s[40:41], 0, v[16:17]
	v_cndmask_b32_e64 v21, v21, v27, s[2:3]
	v_cndmask_b32_e64 v20, v20, v26, s[2:3]
	v_lshl_add_u64 v[16:17], v[16:17], 0, v[112:113]
	global_store_dwordx4 v[16:17], v[20:23], off
	v_add_u32_e32 v16, 0xb0, v148
	v_cvt_pk_bf16_f32 v12, v12, v13
	v_cvt_pk_bf16_f32 v8, v8, v9
	v_cvt_pk_bf16_f32 v9, v10, v11
	v_cvt_pk_bf16_f32 v10, v4, v5
	v_cvt_pk_bf16_f32 v13, v14, v15
	v_cvt_pk_bf16_f32 v6, v6, v7
	v_cvt_pk_bf16_f32 v7, v0, v1
	v_cndmask_b32_e64 v0, v12, v10, s[2:3]
	v_mov_b32_e32 v14, 0
	v_cndmask_b32_e64 v4, v18, v16, s[2:3]
	v_cvt_pk_bf16_f32 v11, v2, v3
	v_mov_b32_dpp v14, v0 row_ror:8 row_mask:0xf bank_mask:0xf
	v_cndmask_b32_e64 v0, v13, v6, s[2:3]
	v_mov_b32_e32 v15, 0
	v_ashrrev_i32_e32 v5, 31, v4
	v_cndmask_b32_e64 v1, v8, v7, s[2:3]
	v_mov_b32_dpp v15, v0 row_ror:8 row_mask:0xf bank_mask:0xf
	v_cndmask_b32_e64 v0, v9, v11, s[2:3]
	v_mov_b32_e32 v17, 0
	v_mov_b32_e32 v19, 0
	v_lshlrev_b64 v[4:5], 11, v[4:5]
	v_mov_b32_dpp v17, v1 row_ror:8 row_mask:0xf bank_mask:0xf
	v_mov_b32_dpp v19, v0 row_ror:8 row_mask:0xf bank_mask:0xf
	v_lshl_add_u64 v[4:5], s[40:41], 0, v[4:5]
	v_cndmask_b32_e64 v3, v19, v9, s[2:3]
	v_cndmask_b32_e64 v2, v17, v8, s[2:3]
	v_cndmask_b32_e64 v1, v15, v13, s[2:3]
	v_cndmask_b32_e64 v0, v14, v12, s[2:3]
	v_lshl_add_u64 v[4:5], v[4:5], 0, v[112:113]
	global_store_dwordx4 v[4:5], v[0:3], off
	s_and_b64 vcc, exec, s[4:5]
	s_mov_b32 s62, s6
	v_add_u32_e32 v0, 0xb8, v148
	v_cndmask_b32_e64 v0, v16, v0, s[2:3]
	v_ashrrev_i32_e32 v1, 31, v0
	v_lshlrev_b64 v[0:1], 11, v[0:1]
	v_lshl_add_u64 v[0:1], s[40:41], 0, v[0:1]
	v_lshl_add_u64 v[4:5], v[0:1], 0, v[112:113]
	v_cndmask_b32_e64 v3, v11, v19, s[2:3]
	v_cndmask_b32_e64 v2, v7, v17, s[2:3]
	v_cndmask_b32_e64 v1, v6, v15, s[2:3]
	v_cndmask_b32_e64 v0, v10, v14, s[2:3]
	s_mov_b32 s42, s8
	s_mov_b64 s[46:47], s[12:13]
	s_mov_b64 s[44:45], s[10:11]
	global_store_dwordx4 v[4:5], v[0:3], off
	s_cbranch_vccz .LBB0_335
	s_waitcnt vmcnt(0)
	s_cmpk_gt_u32 s17, 0xff
	s_cbranch_scc1 .LBB0_346
	s_barrier

.LBB0_667:
	s_add_u32 s56, s52, s54
	s_addc_u32 s57, s53, s55
	s_add_u32 s56, s56, 0x100
	s_addc_u32 s57, s57, 0
	s_add_u32 vcc_lo, s96, s54
	s_addc_u32 vcc_hi, s97, s55
	s_cmpk_eq_i32 s54, 0x700
	s_cselect_b32 s59, s47, s57
	s_cselect_b32 s58, s94, s56
	s_cselect_b32 s57, s45, vcc_hi
	s_cselect_b32 s56, s95, vcc_lo
	s_add_i32 vcc_lo, 0, 0x10000
	v_add_u32_e32 v1, vcc_lo, v196
	ds_read_b128 v[132:135], v1
	ds_read_b128 v[136:139], v1 offset:1024
	ds_read_b128 v[140:143], v1 offset:2048
	ds_read_b128 v[144:147], v1 offset:3072
	ds_read_b128 v[148:151], v199
	ds_read_b128 v[152:155], v199 offset:1024
	ds_read_b128 v[156:159], v199 offset:2048
	ds_read_b128 v[160:163], v199 offset:3072
	ds_read_b128 v[164:167], v199 offset:4096
	ds_read_b128 v[200:203], v199 offset:5120
	ds_read_b128 v[204:207], v199 offset:6144
	ds_read_b128 v[208:211], v199 offset:7168
	v_lshl_add_u64 v[2:3], v[188:189], 0, s[54:55]
	s_add_i32 m0, s63, 0xc000
	global_load_lds_dwordx4 v[2:3], off
	v_lshl_add_u64 v[2:3], v[190:191], 0, s[54:55]
	s_add_i32 m0, s63, 0xe000
	s_nop 0
	global_load_lds_dwordx4 v[2:3], off
	s_waitcnt lgkmcnt(8)
	s_barrier
	s_waitcnt lgkmcnt(0)
	v_mfma_f32_16x16x32_bf16 v[128:131], v[132:135], v[148:151], v[128:131]
	v_mfma_f32_16x16x32_bf16 v[124:127], v[140:143], v[148:151], v[124:127]
	v_mfma_f32_16x16x32_bf16 v[112:115], v[132:135], v[156:159], v[112:115]
	v_mfma_f32_16x16x32_bf16 v[108:111], v[140:143], v[156:159], v[108:111]
	v_mfma_f32_16x16x32_bf16 v[96:99], v[132:135], v[164:167], v[96:99]
	v_mfma_f32_16x16x32_bf16 v[92:95], v[140:143], v[164:167], v[92:95]
	v_mfma_f32_16x16x32_bf16 v[80:83], v[132:135], v[204:207], v[80:83]
	v_mfma_f32_16x16x32_bf16 v[76:79], v[140:143], v[204:207], v[76:79]
	v_mfma_f32_16x16x32_bf16 v[128:131], v[136:139], v[152:155], v[128:131]
	v_mfma_f32_16x16x32_bf16 v[124:127], v[144:147], v[152:155], v[124:127]
	v_mfma_f32_16x16x32_bf16 v[112:115], v[136:139], v[160:163], v[112:115]
	v_mfma_f32_16x16x32_bf16 v[108:111], v[144:147], v[160:163], v[108:111]
	v_mfma_f32_16x16x32_bf16 v[96:99], v[136:139], v[200:203], v[96:99]
	v_mfma_f32_16x16x32_bf16 v[92:95], v[144:147], v[200:203], v[92:95]
	v_mfma_f32_16x16x32_bf16 v[80:83], v[136:139], v[208:211], v[80:83]
	v_mfma_f32_16x16x32_bf16 v[76:79], v[144:147], v[208:211], v[76:79]
	s_barrier
	s_add_i32 vcc_lo, vcc_lo, s61
	v_add_u32_e32 v1, s93, v196
	v_lshl_add_u64 v[228:229], s[56:57], 0, v[172:173]
	s_mov_b32 m0, vcc_lo
	ds_read_b128 v[212:215], v1
	ds_read_b128 v[216:219], v1 offset:1024
	ds_read_b128 v[220:223], v1 offset:2048
	ds_read_b128 v[224:227], v1 offset:3072
	global_load_lds_dwordx4 v[228:229], off
	v_lshl_add_u64 v[230:231], s[56:57], 0, v[168:169]
	s_add_i32 m0, vcc_lo, 0x2000
	s_nop 0
	global_load_lds_dwordx4 v[230:231], off
	s_barrier
	s_waitcnt lgkmcnt(0)
	v_mfma_f32_16x16x32_bf16 v[120:123], v[212:215], v[148:151], v[120:123]
	v_mfma_f32_16x16x32_bf16 v[116:119], v[220:223], v[148:151], v[116:119]
	v_mfma_f32_16x16x32_bf16 v[104:107], v[212:215], v[156:159], v[104:107]
	v_mfma_f32_16x16x32_bf16 v[100:103], v[220:223], v[156:159], v[100:103]
	v_mfma_f32_16x16x32_bf16 v[88:91], v[212:215], v[164:167], v[88:91]
	v_mfma_f32_16x16x32_bf16 v[84:87], v[220:223], v[164:167], v[84:87]
	v_mfma_f32_16x16x32_bf16 v[72:75], v[212:215], v[204:207], v[72:75]
	v_mfma_f32_16x16x32_bf16 v[68:71], v[220:223], v[204:207], v[68:71]
	v_mfma_f32_16x16x32_bf16 v[120:123], v[216:219], v[152:155], v[120:123]
	v_mfma_f32_16x16x32_bf16 v[116:119], v[224:227], v[152:155], v[116:119]
	v_mfma_f32_16x16x32_bf16 v[104:107], v[216:219], v[160:163], v[104:107]
	v_mfma_f32_16x16x32_bf16 v[100:103], v[224:227], v[160:163], v[100:103]
	v_mfma_f32_16x16x32_bf16 v[88:91], v[216:219], v[200:203], v[88:91]
	v_mfma_f32_16x16x32_bf16 v[84:87], v[224:227], v[200:203], v[84:87]
	v_mfma_f32_16x16x32_bf16 v[72:75], v[216:219], v[208:211], v[72:75]
	v_mfma_f32_16x16x32_bf16 v[68:71], v[224:227], v[208:211], v[68:71]
	s_mov_b32 m0, s63
	v_lshl_add_u64 v[232:233], s[58:59], 0, v[174:175]
	s_barrier
	ds_read_b128 v[148:151], v199 offset:16384
	ds_read_b128 v[152:155], v199 offset:17408
	ds_read_b128 v[156:159], v199 offset:18432
	ds_read_b128 v[160:163], v199 offset:19456
	ds_read_b128 v[164:167], v199 offset:20480
	ds_read_b128 v[200:203], v199 offset:21504
	ds_read_b128 v[204:207], v199 offset:22528
	ds_read_b128 v[208:211], v199 offset:23552
	global_load_lds_dwordx4 v[232:233], off
	v_lshl_add_u64 v[234:235], s[58:59], 0, v[170:171]
	s_mov_b32 m0, s64
	s_nop 0
	global_load_lds_dwordx4 v[234:235], off
	s_barrier
	s_waitcnt lgkmcnt(0)
	v_mfma_f32_16x16x32_bf16 v[64:67], v[132:135], v[148:151], v[64:67]
	v_mfma_f32_16x16x32_bf16 v[60:63], v[140:143], v[148:151], v[60:63]
	v_mfma_f32_16x16x32_bf16 v[48:51], v[132:135], v[156:159], v[48:51]
	v_mfma_f32_16x16x32_bf16 v[44:47], v[140:143], v[156:159], v[44:47]
	v_mfma_f32_16x16x32_bf16 v[32:35], v[132:135], v[164:167], v[32:35]
	v_mfma_f32_16x16x32_bf16 v[28:31], v[140:143], v[164:167], v[28:31]
	v_mfma_f32_16x16x32_bf16 v[16:19], v[132:135], v[204:207], v[16:19]
	v_mfma_f32_16x16x32_bf16 v[12:15], v[140:143], v[204:207], v[12:15]
	v_mfma_f32_16x16x32_bf16 v[64:67], v[136:139], v[152:155], v[64:67]
	v_mfma_f32_16x16x32_bf16 v[60:63], v[144:147], v[152:155], v[60:63]
	v_mfma_f32_16x16x32_bf16 v[48:51], v[136:139], v[160:163], v[48:51]
	v_mfma_f32_16x16x32_bf16 v[44:47], v[144:147], v[160:163], v[44:47]
	v_mfma_f32_16x16x32_bf16 v[32:35], v[136:139], v[200:203], v[32:35]
	v_mfma_f32_16x16x32_bf16 v[28:31], v[144:147], v[200:203], v[28:31]
	v_mfma_f32_16x16x32_bf16 v[16:19], v[136:139], v[208:211], v[16:19]
	v_mfma_f32_16x16x32_bf16 v[12:15], v[144:147], v[208:211], v[12:15]
	s_barrier
	s_add_u32 vcc_lo, s56, 0x10000
	s_addc_u32 vcc_hi, s57, 0
	s_add_i32 s28, s93, s61
	v_lshl_add_u64 v[2:3], vcc, 0, v[172:173]
	s_mov_b32 m0, s28
	s_nop 0
	global_load_lds_dwordx4 v[2:3], off
	v_lshl_add_u64 v[2:3], vcc, 0, v[168:169]
	s_add_i32 m0, s28, 0x2000
	s_nop 0
	global_load_lds_dwordx4 v[2:3], off
	s_waitcnt vmcnt(6)
	s_barrier
	v_mfma_f32_16x16x32_bf16 v[56:59], v[212:215], v[148:151], v[56:59]
	v_mfma_f32_16x16x32_bf16 v[52:55], v[220:223], v[148:151], v[52:55]
	v_mfma_f32_16x16x32_bf16 v[40:43], v[212:215], v[156:159], v[40:43]
	v_mfma_f32_16x16x32_bf16 v[36:39], v[220:223], v[156:159], v[36:39]
	v_mfma_f32_16x16x32_bf16 v[24:27], v[212:215], v[164:167], v[24:27]
	v_mfma_f32_16x16x32_bf16 v[20:23], v[220:223], v[164:167], v[20:23]
	v_mfma_f32_16x16x32_bf16 v[8:11], v[212:215], v[204:207], v[8:11]
	v_mfma_f32_16x16x32_bf16 v[2:5], v[220:223], v[204:207], v[4:7]
	v_mfma_f32_16x16x32_bf16 v[56:59], v[216:219], v[152:155], v[56:59]
	v_mfma_f32_16x16x32_bf16 v[52:55], v[224:227], v[152:155], v[52:55]
	v_mfma_f32_16x16x32_bf16 v[40:43], v[216:219], v[160:163], v[40:43]
	v_mfma_f32_16x16x32_bf16 v[36:39], v[224:227], v[160:163], v[36:39]
	v_mfma_f32_16x16x32_bf16 v[24:27], v[216:219], v[200:203], v[24:27]
	v_mfma_f32_16x16x32_bf16 v[20:23], v[224:227], v[200:203], v[20:23]
	v_mfma_f32_16x16x32_bf16 v[8:11], v[216:219], v[208:211], v[8:11]
	v_mfma_f32_16x16x32_bf16 v[2:5], v[224:227], v[208:211], v[2:5]
	s_add_i32 s28, 0, 0x18000
	v_add_u32_e32 v1, s28, v196
	s_barrier
	ds_read_b128 v[132:135], v1
	ds_read_b128 v[136:139], v1 offset:1024
	ds_read_b128 v[140:143], v1 offset:2048
	ds_read_b128 v[144:147], v1 offset:3072
	ds_read_b128 v[148:151], v199 offset:32768
	ds_read_b128 v[152:155], v199 offset:33792
	ds_read_b128 v[156:159], v199 offset:34816
	ds_read_b128 v[160:163], v199 offset:35840
	ds_read_b128 v[164:167], v199 offset:36864
	ds_read_b128 v[200:203], v199 offset:37888
	ds_read_b128 v[204:207], v199 offset:38912
	ds_read_b128 v[208:211], v199 offset:39936
	s_add_u32 s58, s58, 0x40000
	s_addc_u32 s59, s59, 0
	s_mov_b32 m0, s65
	v_lshl_add_u64 v[6:7], s[58:59], 0, v[174:175]
	global_load_lds_dwordx4 v[6:7], off
	v_lshl_add_u64 v[6:7], s[58:59], 0, v[170:171]
	s_mov_b32 m0, s66
	s_nop 0
	global_load_lds_dwordx4 v[6:7], off
	s_waitcnt lgkmcnt(8)
	s_barrier
	s_waitcnt lgkmcnt(0)
	v_mfma_f32_16x16x32_bf16 v[128:131], v[132:135], v[148:151], v[128:131]
	v_mfma_f32_16x16x32_bf16 v[124:127], v[140:143], v[148:151], v[124:127]
	v_mfma_f32_16x16x32_bf16 v[112:115], v[132:135], v[156:159], v[112:115]
	v_mfma_f32_16x16x32_bf16 v[108:111], v[140:143], v[156:159], v[108:111]
	v_mfma_f32_16x16x32_bf16 v[96:99], v[132:135], v[164:167], v[96:99]
	v_mfma_f32_16x16x32_bf16 v[92:95], v[140:143], v[164:167], v[92:95]
	v_mfma_f32_16x16x32_bf16 v[80:83], v[132:135], v[204:207], v[80:83]
	v_mfma_f32_16x16x32_bf16 v[76:79], v[140:143], v[204:207], v[76:79]
	v_mfma_f32_16x16x32_bf16 v[128:131], v[136:139], v[152:155], v[128:131]
	v_mfma_f32_16x16x32_bf16 v[124:127], v[144:147], v[152:155], v[124:127]
	v_mfma_f32_16x16x32_bf16 v[112:115], v[136:139], v[160:163], v[112:115]
	v_mfma_f32_16x16x32_bf16 v[108:111], v[144:147], v[160:163], v[108:111]
	v_mfma_f32_16x16x32_bf16 v[96:99], v[136:139], v[200:203], v[96:99]
	v_mfma_f32_16x16x32_bf16 v[92:95], v[144:147], v[200:203], v[92:95]
	v_mfma_f32_16x16x32_bf16 v[80:83], v[136:139], v[208:211], v[80:83]
	v_mfma_f32_16x16x32_bf16 v[76:79], v[144:147], v[208:211], v[76:79]
	s_barrier
	s_add_i32 s29, 0, 0x1c000
	s_add_i32 s28, s28, s61
	v_add_u32_e32 v1, s29, v196
	v_lshl_add_u64 v[6:7], v[228:229], 0, s[0:1]
	s_mov_b32 m0, s28
	ds_read_b128 v[212:215], v1
	ds_read_b128 v[216:219], v1 offset:1024
	ds_read_b128 v[220:223], v1 offset:2048
	ds_read_b128 v[224:227], v1 offset:3072
	global_load_lds_dwordx4 v[6:7], off
	v_lshl_add_u64 v[6:7], v[230:231], 0, s[0:1]
	s_add_i32 m0, s28, 0x2000
	s_nop 0
	global_load_lds_dwordx4 v[6:7], off
	s_barrier
	s_waitcnt lgkmcnt(0)
	v_mfma_f32_16x16x32_bf16 v[120:123], v[212:215], v[148:151], v[120:123]
	v_mfma_f32_16x16x32_bf16 v[116:119], v[220:223], v[148:151], v[116:119]
	v_mfma_f32_16x16x32_bf16 v[104:107], v[212:215], v[156:159], v[104:107]
	v_mfma_f32_16x16x32_bf16 v[100:103], v[220:223], v[156:159], v[100:103]
	v_mfma_f32_16x16x32_bf16 v[88:91], v[212:215], v[164:167], v[88:91]
	v_mfma_f32_16x16x32_bf16 v[84:87], v[220:223], v[164:167], v[84:87]
	v_mfma_f32_16x16x32_bf16 v[72:75], v[212:215], v[204:207], v[72:75]
	v_mfma_f32_16x16x32_bf16 v[68:71], v[220:223], v[204:207], v[68:71]
	v_mfma_f32_16x16x32_bf16 v[120:123], v[216:219], v[152:155], v[120:123]
	v_mfma_f32_16x16x32_bf16 v[116:119], v[224:227], v[152:155], v[116:119]
	v_mfma_f32_16x16x32_bf16 v[104:107], v[216:219], v[160:163], v[104:107]
	v_mfma_f32_16x16x32_bf16 v[100:103], v[224:227], v[160:163], v[100:103]
	v_mfma_f32_16x16x32_bf16 v[88:91], v[216:219], v[200:203], v[88:91]
	v_mfma_f32_16x16x32_bf16 v[84:87], v[224:227], v[200:203], v[84:87]
	v_mfma_f32_16x16x32_bf16 v[72:75], v[216:219], v[208:211], v[72:75]
	v_mfma_f32_16x16x32_bf16 v[68:71], v[224:227], v[208:211], v[68:71]
	s_mov_b32 m0, s81
	v_lshl_add_u64 v[6:7], v[232:233], 0, s[0:1]
	s_barrier
	ds_read_b128 v[148:151], v199 offset:49152
	ds_read_b128 v[152:155], v199 offset:50176
	ds_read_b128 v[156:159], v199 offset:51200
	ds_read_b128 v[160:163], v199 offset:52224
	ds_read_b128 v[164:167], v199 offset:53248
	ds_read_b128 v[200:203], v199 offset:54272
	ds_read_b128 v[204:207], v199 offset:55296
	ds_read_b128 v[208:211], v199 offset:56320
	global_load_lds_dwordx4 v[6:7], off
	v_lshl_add_u64 v[6:7], v[234:235], 0, s[0:1]
	s_mov_b32 m0, s82
	s_nop 0
	global_load_lds_dwordx4 v[6:7], off
	s_barrier
	s_waitcnt lgkmcnt(0)
	v_mfma_f32_16x16x32_bf16 v[64:67], v[132:135], v[148:151], v[64:67]
	v_mfma_f32_16x16x32_bf16 v[60:63], v[140:143], v[148:151], v[60:63]
	v_mfma_f32_16x16x32_bf16 v[48:51], v[132:135], v[156:159], v[48:51]
	v_mfma_f32_16x16x32_bf16 v[44:47], v[140:143], v[156:159], v[44:47]
	v_mfma_f32_16x16x32_bf16 v[32:35], v[132:135], v[164:167], v[32:35]
	v_mfma_f32_16x16x32_bf16 v[28:31], v[140:143], v[164:167], v[28:31]
	v_mfma_f32_16x16x32_bf16 v[16:19], v[132:135], v[204:207], v[16:19]
	v_mfma_f32_16x16x32_bf16 v[12:15], v[140:143], v[204:207], v[12:15]
	v_mfma_f32_16x16x32_bf16 v[64:67], v[136:139], v[152:155], v[64:67]
	v_mfma_f32_16x16x32_bf16 v[60:63], v[144:147], v[152:155], v[60:63]
	v_mfma_f32_16x16x32_bf16 v[48:51], v[136:139], v[160:163], v[48:51]
	v_mfma_f32_16x16x32_bf16 v[44:47], v[144:147], v[160:163], v[44:47]
	v_mfma_f32_16x16x32_bf16 v[32:35], v[136:139], v[200:203], v[32:35]
	v_mfma_f32_16x16x32_bf16 v[28:31], v[144:147], v[200:203], v[28:31]
	v_mfma_f32_16x16x32_bf16 v[16:19], v[136:139], v[208:211], v[16:19]
	v_mfma_f32_16x16x32_bf16 v[12:15], v[144:147], v[208:211], v[12:15]
	s_barrier
	s_add_u32 s56, s56, 0x10080
	s_addc_u32 s57, s57, 0
	s_add_i32 s28, s29, s61
	v_lshl_add_u64 v[6:7], s[56:57], 0, v[172:173]
	s_mov_b32 m0, s28
	s_nop 0
	global_load_lds_dwordx4 v[6:7], off
	v_lshl_add_u64 v[6:7], s[56:57], 0, v[168:169]
	s_add_i32 m0, s28, 0x2000
	s_nop 0
	global_load_lds_dwordx4 v[6:7], off
	s_waitcnt vmcnt(6)
	s_barrier
	v_mfma_f32_16x16x32_bf16 v[56:59], v[212:215], v[148:151], v[56:59]
	v_mfma_f32_16x16x32_bf16 v[52:55], v[220:223], v[148:151], v[52:55]
	v_mfma_f32_16x16x32_bf16 v[40:43], v[212:215], v[156:159], v[40:43]
	v_mfma_f32_16x16x32_bf16 v[36:39], v[220:223], v[156:159], v[36:39]
	v_mfma_f32_16x16x32_bf16 v[24:27], v[212:215], v[164:167], v[24:27]
	v_mfma_f32_16x16x32_bf16 v[20:23], v[220:223], v[164:167], v[20:23]
	v_mfma_f32_16x16x32_bf16 v[6:9], v[212:215], v[204:207], v[8:11]
	v_mfma_f32_16x16x32_bf16 v[2:5], v[220:223], v[204:207], v[2:5]
	v_mfma_f32_16x16x32_bf16 v[56:59], v[216:219], v[152:155], v[56:59]
	v_mfma_f32_16x16x32_bf16 v[52:55], v[224:227], v[152:155], v[52:55]
	v_mfma_f32_16x16x32_bf16 v[40:43], v[216:219], v[160:163], v[40:43]
	v_mfma_f32_16x16x32_bf16 v[36:39], v[224:227], v[160:163], v[36:39]
	v_mfma_f32_16x16x32_bf16 v[24:27], v[216:219], v[200:203], v[24:27]
	v_mfma_f32_16x16x32_bf16 v[20:23], v[224:227], v[200:203], v[20:23]
	v_mfma_f32_16x16x32_bf16 v[8:11], v[216:219], v[208:211], v[6:9]
	v_mfma_f32_16x16x32_bf16 v[4:7], v[224:227], v[208:211], v[2:5]
	s_add_i32 s17, s17, 2
	s_add_u32 s54, s54, 0x100
	s_addc_u32 s55, s55, 0
	s_cmp_gt_u32 s17, 13
	s_barrier
	s_cbranch_scc1 .LBB0_659

.LBB0_740:
	ds_read_b128 v[64:67], v221
	ds_read_b128 v[68:71], v221 offset:1024
	ds_read_b128 v[84:87], v221 offset:2048
	ds_read_b128 v[92:95], v221 offset:3072
	ds_read_b128 v[144:147], v222
	ds_read_b128 v[148:151], v222 offset:1024
	ds_read_b128 v[152:155], v222 offset:2048
	ds_read_b128 v[156:159], v222 offset:3072
	ds_read_b128 v[160:163], v222 offset:4096
	ds_read_b128 v[164:167], v222 offset:5120
	ds_read_b128 v[168:171], v222 offset:6144
	ds_read_b128 v[172:175], v222 offset:7168
	s_add_u32 s28, s10, 0xfffc0080
	s_addc_u32 s29, s11, -1
	s_cmp_eq_u32 s92, 12
	s_cselect_b32 s65, s9, s29
	s_cselect_b32 s64, s13, s28
	s_cselect_b32 s63, s17, s57
	s_cselect_b32 s62, s44, s55
	v_lshl_add_u64 v[176:177], s[10:11], 0, v[204:205]
	s_add_i32 m0, s78, 0xc000
	global_load_lds_dwordx4 v[176:177], off
	v_lshl_add_u64 v[176:177], s[10:11], 0, v[206:207]
	s_add_i32 m0, s78, 0xe000
	s_nop 0
	global_load_lds_dwordx4 v[176:177], off
	s_waitcnt lgkmcnt(8)
	s_barrier
	s_waitcnt lgkmcnt(0)
	v_mfma_f32_16x16x32_bf16 v[140:143], v[64:67], v[144:147], v[140:143]
	v_mfma_f32_16x16x32_bf16 v[136:139], v[84:87], v[144:147], v[136:139]
	v_mfma_f32_16x16x32_bf16 v[124:127], v[64:67], v[152:155], v[124:127]
	v_mfma_f32_16x16x32_bf16 v[120:123], v[84:87], v[152:155], v[120:123]
	v_mfma_f32_16x16x32_bf16 v[108:111], v[64:67], v[160:163], v[108:111]
	v_mfma_f32_16x16x32_bf16 v[104:107], v[84:87], v[160:163], v[104:107]
	v_mfma_f32_16x16x32_bf16 v[88:91], v[64:67], v[168:171], v[88:91]
	v_mfma_f32_16x16x32_bf16 v[80:83], v[84:87], v[168:171], v[80:83]
	v_mfma_f32_16x16x32_bf16 v[140:143], v[68:71], v[148:151], v[140:143]
	v_mfma_f32_16x16x32_bf16 v[136:139], v[92:95], v[148:151], v[136:139]
	v_mfma_f32_16x16x32_bf16 v[124:127], v[68:71], v[156:159], v[124:127]
	v_mfma_f32_16x16x32_bf16 v[120:123], v[92:95], v[156:159], v[120:123]
	v_mfma_f32_16x16x32_bf16 v[108:111], v[68:71], v[164:167], v[108:111]
	v_mfma_f32_16x16x32_bf16 v[104:107], v[92:95], v[164:167], v[104:107]
	v_mfma_f32_16x16x32_bf16 v[88:91], v[68:71], v[172:175], v[88:91]
	v_mfma_f32_16x16x32_bf16 v[80:83], v[92:95], v[172:175], v[80:83]
	s_barrier
	s_add_i32 s28, s89, s67
	v_lshl_add_u64 v[212:213], s[62:63], 0, v[198:199]
	s_mov_b32 m0, s28
	ds_read_b128 v[176:179], v223
	ds_read_b128 v[180:183], v223 offset:1024
	ds_read_b128 v[184:187], v223 offset:2048
	ds_read_b128 v[188:191], v223 offset:3072
	global_load_lds_dwordx4 v[212:213], off
	v_lshl_add_u64 v[214:215], s[62:63], 0, v[202:203]
	s_add_i32 m0, s28, 0x2000
	s_nop 0
	global_load_lds_dwordx4 v[214:215], off
	s_barrier
	s_waitcnt lgkmcnt(0)
	v_mfma_f32_16x16x32_bf16 v[132:135], v[176:179], v[144:147], v[132:135]
	v_mfma_f32_16x16x32_bf16 v[128:131], v[184:187], v[144:147], v[128:131]
	v_mfma_f32_16x16x32_bf16 v[116:119], v[176:179], v[152:155], v[116:119]
	v_mfma_f32_16x16x32_bf16 v[112:115], v[184:187], v[152:155], v[112:115]
	v_mfma_f32_16x16x32_bf16 v[100:103], v[176:179], v[160:163], v[100:103]
	v_mfma_f32_16x16x32_bf16 v[96:99], v[184:187], v[160:163], v[96:99]
	v_mfma_f32_16x16x32_bf16 v[76:79], v[176:179], v[168:171], v[76:79]
	v_mfma_f32_16x16x32_bf16 v[72:75], v[184:187], v[168:171], v[72:75]
	v_mfma_f32_16x16x32_bf16 v[132:135], v[180:183], v[148:151], v[132:135]
	v_mfma_f32_16x16x32_bf16 v[128:131], v[188:191], v[148:151], v[128:131]
	v_mfma_f32_16x16x32_bf16 v[116:119], v[180:183], v[156:159], v[116:119]
	v_mfma_f32_16x16x32_bf16 v[112:115], v[188:191], v[156:159], v[112:115]
	v_mfma_f32_16x16x32_bf16 v[100:103], v[180:183], v[164:167], v[100:103]
	v_mfma_f32_16x16x32_bf16 v[96:99], v[188:191], v[164:167], v[96:99]
	v_mfma_f32_16x16x32_bf16 v[76:79], v[180:183], v[172:175], v[76:79]
	v_mfma_f32_16x16x32_bf16 v[72:75], v[188:191], v[172:175], v[72:75]
	s_mov_b32 m0, s78
	v_lshl_add_u64 v[216:217], s[64:65], 0, v[196:197]
	s_barrier
	ds_read_b128 v[144:147], v222 offset:16384
	ds_read_b128 v[148:151], v222 offset:17408
	ds_read_b128 v[152:155], v222 offset:18432
	ds_read_b128 v[156:159], v222 offset:19456
	ds_read_b128 v[160:163], v222 offset:20480
	ds_read_b128 v[164:167], v222 offset:21504
	ds_read_b128 v[168:171], v222 offset:22528
	ds_read_b128 v[172:175], v222 offset:23552
	global_load_lds_dwordx4 v[216:217], off
	v_lshl_add_u64 v[226:227], s[64:65], 0, v[200:201]
	s_mov_b32 m0, s79
	s_nop 0
	global_load_lds_dwordx4 v[226:227], off
	s_barrier
	s_waitcnt lgkmcnt(0)
	v_mfma_f32_16x16x32_bf16 v[60:63], v[64:67], v[144:147], v[60:63]
	v_mfma_f32_16x16x32_bf16 v[56:59], v[84:87], v[144:147], v[56:59]
	v_mfma_f32_16x16x32_bf16 v[44:47], v[64:67], v[152:155], v[44:47]
	v_mfma_f32_16x16x32_bf16 v[40:43], v[84:87], v[152:155], v[40:43]
	v_mfma_f32_16x16x32_bf16 v[28:31], v[64:67], v[160:163], v[28:31]
	v_mfma_f32_16x16x32_bf16 v[24:27], v[84:87], v[160:163], v[24:27]
	v_mfma_f32_16x16x32_bf16 v[12:15], v[64:67], v[168:171], v[12:15]
	v_mfma_f32_16x16x32_bf16 v[8:11], v[84:87], v[168:171], v[8:11]
	v_mfma_f32_16x16x32_bf16 v[60:63], v[68:71], v[148:151], v[60:63]
	v_mfma_f32_16x16x32_bf16 v[56:59], v[92:95], v[148:151], v[56:59]
	v_mfma_f32_16x16x32_bf16 v[44:47], v[68:71], v[156:159], v[44:47]
	v_mfma_f32_16x16x32_bf16 v[40:43], v[92:95], v[156:159], v[40:43]
	v_mfma_f32_16x16x32_bf16 v[28:31], v[68:71], v[164:167], v[28:31]
	v_mfma_f32_16x16x32_bf16 v[24:27], v[92:95], v[164:167], v[24:27]
	v_mfma_f32_16x16x32_bf16 v[12:15], v[68:71], v[172:175], v[12:15]
	v_mfma_f32_16x16x32_bf16 v[8:11], v[92:95], v[172:175], v[8:11]
	s_barrier
	s_add_u32 s94, s62, 0x10000
	s_addc_u32 s95, s63, 0
	s_add_i32 s28, s90, s67
	v_lshl_add_u64 v[64:65], s[94:95], 0, v[198:199]
	s_mov_b32 m0, s28
	s_nop 0
	global_load_lds_dwordx4 v[64:65], off
	v_lshl_add_u64 v[64:65], s[94:95], 0, v[202:203]
	s_add_i32 m0, s28, 0x2000
	s_nop 0
	global_load_lds_dwordx4 v[64:65], off
	s_waitcnt vmcnt(6)
	s_barrier
	v_mfma_f32_16x16x32_bf16 v[52:55], v[176:179], v[144:147], v[52:55]
	v_mfma_f32_16x16x32_bf16 v[48:51], v[184:187], v[144:147], v[48:51]
	v_mfma_f32_16x16x32_bf16 v[36:39], v[176:179], v[152:155], v[36:39]
	v_mfma_f32_16x16x32_bf16 v[32:35], v[184:187], v[152:155], v[32:35]
	v_mfma_f32_16x16x32_bf16 v[20:23], v[176:179], v[160:163], v[20:23]
	v_mfma_f32_16x16x32_bf16 v[16:19], v[184:187], v[160:163], v[16:19]
	v_mfma_f32_16x16x32_bf16 v[4:7], v[176:179], v[168:171], v[4:7]
	v_mfma_f32_16x16x32_bf16 v[0:3], v[184:187], v[168:171], v[0:3]
	v_mfma_f32_16x16x32_bf16 v[52:55], v[180:183], v[148:151], v[52:55]
	v_mfma_f32_16x16x32_bf16 v[48:51], v[188:191], v[148:151], v[48:51]
	v_mfma_f32_16x16x32_bf16 v[36:39], v[180:183], v[156:159], v[36:39]
	v_mfma_f32_16x16x32_bf16 v[32:35], v[188:191], v[156:159], v[32:35]
	v_mfma_f32_16x16x32_bf16 v[20:23], v[180:183], v[164:167], v[20:23]
	v_mfma_f32_16x16x32_bf16 v[16:19], v[188:191], v[164:167], v[16:19]
	v_mfma_f32_16x16x32_bf16 v[4:7], v[180:183], v[172:175], v[4:7]
	v_mfma_f32_16x16x32_bf16 v[0:3], v[188:191], v[172:175], v[0:3]
	s_add_i32 s28, 0, 0x18000
	v_add_u32_e32 v92, s28, v218
	s_barrier
	ds_read_b128 v[64:67], v92
	ds_read_b128 v[68:71], v92 offset:1024
	ds_read_b128 v[84:87], v92 offset:2048
	ds_read_b128 v[92:95], v92 offset:3072
	ds_read_b128 v[144:147], v222 offset:32768
	ds_read_b128 v[148:151], v222 offset:33792
	ds_read_b128 v[152:155], v222 offset:34816
	ds_read_b128 v[156:159], v222 offset:35840
	ds_read_b128 v[160:163], v222 offset:36864
	ds_read_b128 v[164:167], v222 offset:37888
	ds_read_b128 v[168:171], v222 offset:38912
	ds_read_b128 v[172:175], v222 offset:39936
	s_add_u32 s64, s64, 0x40000
	s_addc_u32 s65, s65, 0
	s_mov_b32 m0, s80
	v_lshl_add_u64 v[176:177], s[64:65], 0, v[196:197]
	global_load_lds_dwordx4 v[176:177], off
	v_lshl_add_u64 v[176:177], s[64:65], 0, v[200:201]
	s_mov_b32 m0, s81
	s_nop 0
	global_load_lds_dwordx4 v[176:177], off
	s_waitcnt lgkmcnt(8)
	s_barrier
	s_waitcnt lgkmcnt(0)
	v_mfma_f32_16x16x32_bf16 v[140:143], v[64:67], v[144:147], v[140:143]
	v_mfma_f32_16x16x32_bf16 v[136:139], v[84:87], v[144:147], v[136:139]
	v_mfma_f32_16x16x32_bf16 v[124:127], v[64:67], v[152:155], v[124:127]
	v_mfma_f32_16x16x32_bf16 v[120:123], v[84:87], v[152:155], v[120:123]
	v_mfma_f32_16x16x32_bf16 v[108:111], v[64:67], v[160:163], v[108:111]
	v_mfma_f32_16x16x32_bf16 v[104:107], v[84:87], v[160:163], v[104:107]
	v_mfma_f32_16x16x32_bf16 v[88:91], v[64:67], v[168:171], v[88:91]
	v_mfma_f32_16x16x32_bf16 v[80:83], v[84:87], v[168:171], v[80:83]
	v_mfma_f32_16x16x32_bf16 v[140:143], v[68:71], v[148:151], v[140:143]
	v_mfma_f32_16x16x32_bf16 v[136:139], v[92:95], v[148:151], v[136:139]
	v_mfma_f32_16x16x32_bf16 v[124:127], v[68:71], v[156:159], v[124:127]
	v_mfma_f32_16x16x32_bf16 v[120:123], v[92:95], v[156:159], v[120:123]
	v_mfma_f32_16x16x32_bf16 v[108:111], v[68:71], v[164:167], v[108:111]
	v_mfma_f32_16x16x32_bf16 v[104:107], v[92:95], v[164:167], v[104:107]
	v_mfma_f32_16x16x32_bf16 v[88:91], v[68:71], v[172:175], v[88:91]
	v_mfma_f32_16x16x32_bf16 v[80:83], v[92:95], v[172:175], v[80:83]
	s_barrier
	s_add_i32 s29, 0, 0x1c000
	s_add_i32 s28, s28, s67
	v_add_u32_e32 v188, s29, v218
	v_lshl_add_u64 v[212:213], v[212:213], 0, s[52:53]
	s_mov_b32 m0, s28
	ds_read_b128 v[176:179], v188
	ds_read_b128 v[180:183], v188 offset:1024
	ds_read_b128 v[184:187], v188 offset:2048
	ds_read_b128 v[188:191], v188 offset:3072
	global_load_lds_dwordx4 v[212:213], off
	v_lshl_add_u64 v[212:213], v[214:215], 0, s[52:53]
	s_add_i32 m0, s28, 0x2000
	s_nop 0
	global_load_lds_dwordx4 v[212:213], off
	s_barrier
	s_waitcnt lgkmcnt(0)
	v_mfma_f32_16x16x32_bf16 v[132:135], v[176:179], v[144:147], v[132:135]
	v_mfma_f32_16x16x32_bf16 v[128:131], v[184:187], v[144:147], v[128:131]
	v_mfma_f32_16x16x32_bf16 v[116:119], v[176:179], v[152:155], v[116:119]
	v_mfma_f32_16x16x32_bf16 v[112:115], v[184:187], v[152:155], v[112:115]
	v_mfma_f32_16x16x32_bf16 v[100:103], v[176:179], v[160:163], v[100:103]
	v_mfma_f32_16x16x32_bf16 v[96:99], v[184:187], v[160:163], v[96:99]
	v_mfma_f32_16x16x32_bf16 v[76:79], v[176:179], v[168:171], v[76:79]
	v_mfma_f32_16x16x32_bf16 v[72:75], v[184:187], v[168:171], v[72:75]
	v_mfma_f32_16x16x32_bf16 v[132:135], v[180:183], v[148:151], v[132:135]
	v_mfma_f32_16x16x32_bf16 v[128:131], v[188:191], v[148:151], v[128:131]
	v_mfma_f32_16x16x32_bf16 v[116:119], v[180:183], v[156:159], v[116:119]
	v_mfma_f32_16x16x32_bf16 v[112:115], v[188:191], v[156:159], v[112:115]
	v_mfma_f32_16x16x32_bf16 v[100:103], v[180:183], v[164:167], v[100:103]
	v_mfma_f32_16x16x32_bf16 v[96:99], v[188:191], v[164:167], v[96:99]
	v_mfma_f32_16x16x32_bf16 v[76:79], v[180:183], v[172:175], v[76:79]
	v_mfma_f32_16x16x32_bf16 v[72:75], v[188:191], v[172:175], v[72:75]
	s_mov_b32 m0, s85
	v_lshl_add_u64 v[212:213], v[216:217], 0, s[52:53]
	s_barrier
	ds_read_b128 v[144:147], v222 offset:49152
	ds_read_b128 v[148:151], v222 offset:50176
	ds_read_b128 v[152:155], v222 offset:51200
	ds_read_b128 v[156:159], v222 offset:52224
	ds_read_b128 v[160:163], v222 offset:53248
	ds_read_b128 v[164:167], v222 offset:54272
	ds_read_b128 v[168:171], v222 offset:55296
	ds_read_b128 v[172:175], v222 offset:56320
	global_load_lds_dwordx4 v[212:213], off
	v_lshl_add_u64 v[212:213], v[226:227], 0, s[52:53]
	s_mov_b32 m0, s87
	s_nop 0
	global_load_lds_dwordx4 v[212:213], off
	s_barrier
	s_waitcnt lgkmcnt(0)
	v_mfma_f32_16x16x32_bf16 v[60:63], v[64:67], v[144:147], v[60:63]
	v_mfma_f32_16x16x32_bf16 v[56:59], v[84:87], v[144:147], v[56:59]
	v_mfma_f32_16x16x32_bf16 v[44:47], v[64:67], v[152:155], v[44:47]
	v_mfma_f32_16x16x32_bf16 v[40:43], v[84:87], v[152:155], v[40:43]
	v_mfma_f32_16x16x32_bf16 v[28:31], v[64:67], v[160:163], v[28:31]
	v_mfma_f32_16x16x32_bf16 v[24:27], v[84:87], v[160:163], v[24:27]
	v_mfma_f32_16x16x32_bf16 v[12:15], v[64:67], v[168:171], v[12:15]
	v_mfma_f32_16x16x32_bf16 v[8:11], v[84:87], v[168:171], v[8:11]
	v_mfma_f32_16x16x32_bf16 v[60:63], v[68:71], v[148:151], v[60:63]
	v_mfma_f32_16x16x32_bf16 v[56:59], v[92:95], v[148:151], v[56:59]
	v_mfma_f32_16x16x32_bf16 v[44:47], v[68:71], v[156:159], v[44:47]
	v_mfma_f32_16x16x32_bf16 v[40:43], v[92:95], v[156:159], v[40:43]
	v_mfma_f32_16x16x32_bf16 v[28:31], v[68:71], v[164:167], v[28:31]
	v_mfma_f32_16x16x32_bf16 v[24:27], v[92:95], v[164:167], v[24:27]
	v_mfma_f32_16x16x32_bf16 v[12:15], v[68:71], v[172:175], v[12:15]
	v_mfma_f32_16x16x32_bf16 v[8:11], v[92:95], v[172:175], v[8:11]
	s_barrier
	s_add_u32 s62, s62, 0x10080
	s_addc_u32 s63, s63, 0
	s_add_i32 s28, s29, s67
	v_lshl_add_u64 v[64:65], s[62:63], 0, v[198:199]
	s_mov_b32 m0, s28
	s_nop 0
	global_load_lds_dwordx4 v[64:65], off
	v_lshl_add_u64 v[64:65], s[62:63], 0, v[202:203]
	s_add_i32 m0, s28, 0x2000
	s_nop 0
	global_load_lds_dwordx4 v[64:65], off
	s_waitcnt vmcnt(6)
	s_barrier
	v_mfma_f32_16x16x32_bf16 v[52:55], v[176:179], v[144:147], v[52:55]
	v_mfma_f32_16x16x32_bf16 v[48:51], v[184:187], v[144:147], v[48:51]
	v_mfma_f32_16x16x32_bf16 v[36:39], v[176:179], v[152:155], v[36:39]
	v_mfma_f32_16x16x32_bf16 v[32:35], v[184:187], v[152:155], v[32:35]
	v_mfma_f32_16x16x32_bf16 v[20:23], v[176:179], v[160:163], v[20:23]
	v_mfma_f32_16x16x32_bf16 v[16:19], v[184:187], v[160:163], v[16:19]
	v_mfma_f32_16x16x32_bf16 v[4:7], v[176:179], v[168:171], v[4:7]
	v_mfma_f32_16x16x32_bf16 v[0:3], v[184:187], v[168:171], v[0:3]
	v_mfma_f32_16x16x32_bf16 v[52:55], v[180:183], v[148:151], v[52:55]
	v_mfma_f32_16x16x32_bf16 v[48:51], v[188:191], v[148:151], v[48:51]
	v_mfma_f32_16x16x32_bf16 v[36:39], v[180:183], v[156:159], v[36:39]
	v_mfma_f32_16x16x32_bf16 v[32:35], v[188:191], v[156:159], v[32:35]
	v_mfma_f32_16x16x32_bf16 v[20:23], v[180:183], v[164:167], v[20:23]
	v_mfma_f32_16x16x32_bf16 v[16:19], v[188:191], v[164:167], v[16:19]
	v_mfma_f32_16x16x32_bf16 v[4:7], v[180:183], v[172:175], v[4:7]
	v_mfma_f32_16x16x32_bf16 v[0:3], v[188:191], v[172:175], v[0:3]
	s_add_i32 s92, s92, 2
	s_add_u32 s10, s10, 0x100
	s_addc_u32 s11, s11, 0
	s_add_u32 s55, s55, 0x100
	s_addc_u32 s57, s57, 0
	s_cmp_gt_u32 s92, 13
	s_barrier
	s_cbranch_scc0 .LBB0_740
	v_lshl_add_u32 v212, s8, 8, v195
	v_lshl_or_b32 v214, s12, 8, v219
	v_ashrrev_i32_e32 v213, 31, v212
	v_ashrrev_i32_e32 v215, 31, v214
	s_mov_b64 s[8:9], -1
	s_and_b64 vcc, exec, s[48:49]
	s_cbranch_vccz .LBB0_743
	v_lshlrev_b64 v[64:65], 12, v[212:213]
	v_lshl_add_u64 v[64:65], s[36:37], 0, v[64:65]
	v_lshl_add_u64 v[64:65], v[214:215], 2, v[64:65]
	global_load_dwordx4 v[160:163], v[64:65], off offset:16
	global_load_dwordx4 v[164:167], v[64:65], off
	global_load_dwordx4 v[168:171], v[64:65], off offset:144
	global_load_dwordx4 v[172:175], v[64:65], off offset:128
	s_mov_b64 s[8:9], 0

.LBB0_904:
	ds_read_b128 v[146:149], v169
	ds_read_b128 v[150:153], v169 offset:1024
	ds_read_b128 v[154:157], v169 offset:2048
	ds_read_b128 v[174:177], v169 offset:3072
	ds_read_b128 v[178:181], v171
	ds_read_b128 v[182:185], v171 offset:1024
	ds_read_b128 v[186:189], v171 offset:2048
	ds_read_b128 v[196:199], v171 offset:3072
	ds_read_b128 v[200:203], v171 offset:4096
	ds_read_b128 v[204:207], v171 offset:5120
	ds_read_b128 v[208:211], v171 offset:6144
	ds_read_b128 v[212:215], v171 offset:7168
	s_add_u32 s28, s0, 0xfffc0080
	s_addc_u32 s29, s1, -1
	s_cmp_eq_u32 s78, 12
	s_cselect_b32 s53, s7, s29
	s_cselect_b32 s52, s45, s28
	s_cselect_b32 s51, s37, s77
	s_cselect_b32 s50, s67, s76
	v_lshl_add_u64 v[158:159], s[0:1], 0, v[138:139]
	s_add_i32 m0, s54, 0xc000
	global_load_lds_dwordx4 v[158:159], off
	v_lshl_add_u64 v[158:159], s[0:1], 0, v[140:141]
	s_add_i32 m0, s54, 0xe000
	s_nop 0
	global_load_lds_dwordx4 v[158:159], off
	s_waitcnt lgkmcnt(8)
	s_barrier
	s_waitcnt lgkmcnt(0)
	v_mfma_f32_16x16x32_bf16 v[124:127], v[146:149], v[178:181], v[124:127]
	v_mfma_f32_16x16x32_bf16 v[120:123], v[154:157], v[178:181], v[120:123]
	v_mfma_f32_16x16x32_bf16 v[108:111], v[146:149], v[186:189], v[108:111]
	v_mfma_f32_16x16x32_bf16 v[104:107], v[154:157], v[186:189], v[104:107]
	v_mfma_f32_16x16x32_bf16 v[92:95], v[146:149], v[200:203], v[92:95]
	v_mfma_f32_16x16x32_bf16 v[88:91], v[154:157], v[200:203], v[88:91]
	v_mfma_f32_16x16x32_bf16 v[76:79], v[146:149], v[208:211], v[76:79]
	v_mfma_f32_16x16x32_bf16 v[72:75], v[154:157], v[208:211], v[72:75]
	v_mfma_f32_16x16x32_bf16 v[124:127], v[150:153], v[182:185], v[124:127]
	v_mfma_f32_16x16x32_bf16 v[120:123], v[174:177], v[182:185], v[120:123]
	v_mfma_f32_16x16x32_bf16 v[108:111], v[150:153], v[196:199], v[108:111]
	v_mfma_f32_16x16x32_bf16 v[104:107], v[174:177], v[196:199], v[104:107]
	v_mfma_f32_16x16x32_bf16 v[92:95], v[150:153], v[204:207], v[92:95]
	v_mfma_f32_16x16x32_bf16 v[88:91], v[174:177], v[204:207], v[88:91]
	v_mfma_f32_16x16x32_bf16 v[76:79], v[150:153], v[212:215], v[76:79]
	v_mfma_f32_16x16x32_bf16 v[72:75], v[174:177], v[212:215], v[72:75]
	s_barrier
	s_add_i32 s28, s63, s13
	v_lshl_add_u64 v[158:159], s[50:51], 0, v[132:133]
	s_mov_b32 m0, s28
	ds_read_b128 v[216:219], v172
	ds_read_b128 v[220:223], v172 offset:1024
	ds_read_b128 v[224:227], v172 offset:2048
	ds_read_b128 v[228:231], v172 offset:3072
	global_load_lds_dwordx4 v[158:159], off
	v_lshl_add_u64 v[164:165], s[50:51], 0, v[128:129]
	s_add_i32 m0, s28, 0x2000
	s_nop 0
	global_load_lds_dwordx4 v[164:165], off
	s_barrier
	s_waitcnt lgkmcnt(0)
	v_mfma_f32_16x16x32_bf16 v[116:119], v[216:219], v[178:181], v[116:119]
	v_mfma_f32_16x16x32_bf16 v[112:115], v[224:227], v[178:181], v[112:115]
	v_mfma_f32_16x16x32_bf16 v[100:103], v[216:219], v[186:189], v[100:103]
	v_mfma_f32_16x16x32_bf16 v[96:99], v[224:227], v[186:189], v[96:99]
	v_mfma_f32_16x16x32_bf16 v[84:87], v[216:219], v[200:203], v[84:87]
	v_mfma_f32_16x16x32_bf16 v[80:83], v[224:227], v[200:203], v[80:83]
	v_mfma_f32_16x16x32_bf16 v[68:71], v[216:219], v[208:211], v[68:71]
	v_mfma_f32_16x16x32_bf16 v[64:67], v[224:227], v[208:211], v[64:67]
	v_mfma_f32_16x16x32_bf16 v[116:119], v[220:223], v[182:185], v[116:119]
	v_mfma_f32_16x16x32_bf16 v[112:115], v[228:231], v[182:185], v[112:115]
	v_mfma_f32_16x16x32_bf16 v[100:103], v[220:223], v[196:199], v[100:103]
	v_mfma_f32_16x16x32_bf16 v[96:99], v[228:231], v[196:199], v[96:99]
	v_mfma_f32_16x16x32_bf16 v[84:87], v[220:223], v[204:207], v[84:87]
	v_mfma_f32_16x16x32_bf16 v[80:83], v[228:231], v[204:207], v[80:83]
	v_mfma_f32_16x16x32_bf16 v[68:71], v[220:223], v[212:215], v[68:71]
	v_mfma_f32_16x16x32_bf16 v[64:67], v[228:231], v[212:215], v[64:67]
	s_mov_b32 m0, s54
	v_lshl_add_u64 v[190:191], s[52:53], 0, v[134:135]
	s_barrier
	ds_read_b128 v[178:181], v171 offset:16384
	ds_read_b128 v[182:185], v171 offset:17408
	ds_read_b128 v[186:189], v171 offset:18432
	ds_read_b128 v[196:199], v171 offset:19456
	ds_read_b128 v[200:203], v171 offset:20480
	ds_read_b128 v[204:207], v171 offset:21504
	ds_read_b128 v[208:211], v171 offset:22528
	ds_read_b128 v[212:215], v171 offset:23552
	global_load_lds_dwordx4 v[190:191], off
	v_lshl_add_u64 v[232:233], s[52:53], 0, v[130:131]
	s_mov_b32 m0, s55
	s_nop 0
	global_load_lds_dwordx4 v[232:233], off
	s_barrier
	s_waitcnt lgkmcnt(0)
	v_mfma_f32_16x16x32_bf16 v[60:63], v[146:149], v[178:181], v[60:63]
	v_mfma_f32_16x16x32_bf16 v[56:59], v[154:157], v[178:181], v[56:59]
	v_mfma_f32_16x16x32_bf16 v[44:47], v[146:149], v[186:189], v[44:47]
	v_mfma_f32_16x16x32_bf16 v[40:43], v[154:157], v[186:189], v[40:43]
	v_mfma_f32_16x16x32_bf16 v[28:31], v[146:149], v[200:203], v[28:31]
	v_mfma_f32_16x16x32_bf16 v[24:27], v[154:157], v[200:203], v[24:27]
	v_mfma_f32_16x16x32_bf16 v[12:15], v[146:149], v[208:211], v[12:15]
	v_mfma_f32_16x16x32_bf16 v[8:11], v[154:157], v[208:211], v[8:11]
	v_mfma_f32_16x16x32_bf16 v[60:63], v[150:153], v[182:185], v[60:63]
	v_mfma_f32_16x16x32_bf16 v[56:59], v[174:177], v[182:185], v[56:59]
	v_mfma_f32_16x16x32_bf16 v[44:47], v[150:153], v[196:199], v[44:47]
	v_mfma_f32_16x16x32_bf16 v[40:43], v[174:177], v[196:199], v[40:43]
	v_mfma_f32_16x16x32_bf16 v[28:31], v[150:153], v[204:207], v[28:31]
	v_mfma_f32_16x16x32_bf16 v[24:27], v[174:177], v[204:207], v[24:27]
	v_mfma_f32_16x16x32_bf16 v[12:15], v[150:153], v[212:215], v[12:15]
	v_mfma_f32_16x16x32_bf16 v[8:11], v[174:177], v[212:215], v[8:11]
	s_barrier
	s_add_u32 s80, s50, 0x10000
	s_addc_u32 s81, s51, 0
	s_add_i32 s28, s64, s13
	v_lshl_add_u64 v[146:147], s[80:81], 0, v[132:133]
	s_mov_b32 m0, s28
	s_nop 0
	global_load_lds_dwordx4 v[146:147], off
	v_lshl_add_u64 v[146:147], s[80:81], 0, v[128:129]
	s_add_i32 m0, s28, 0x2000
	s_nop 0
	global_load_lds_dwordx4 v[146:147], off
	s_waitcnt vmcnt(6)
	s_barrier
	v_mfma_f32_16x16x32_bf16 v[52:55], v[216:219], v[178:181], v[52:55]
	v_mfma_f32_16x16x32_bf16 v[48:51], v[224:227], v[178:181], v[48:51]
	v_mfma_f32_16x16x32_bf16 v[36:39], v[216:219], v[186:189], v[36:39]
	v_mfma_f32_16x16x32_bf16 v[32:35], v[224:227], v[186:189], v[32:35]
	v_mfma_f32_16x16x32_bf16 v[20:23], v[216:219], v[200:203], v[20:23]
	v_mfma_f32_16x16x32_bf16 v[16:19], v[224:227], v[200:203], v[16:19]
	v_mfma_f32_16x16x32_bf16 v[4:7], v[216:219], v[208:211], v[4:7]
	v_mfma_f32_16x16x32_bf16 v[0:3], v[224:227], v[208:211], v[0:3]
	v_mfma_f32_16x16x32_bf16 v[52:55], v[220:223], v[182:185], v[52:55]
	v_mfma_f32_16x16x32_bf16 v[48:51], v[228:231], v[182:185], v[48:51]
	v_mfma_f32_16x16x32_bf16 v[36:39], v[220:223], v[196:199], v[36:39]
	v_mfma_f32_16x16x32_bf16 v[32:35], v[228:231], v[196:199], v[32:35]
	v_mfma_f32_16x16x32_bf16 v[20:23], v[220:223], v[204:207], v[20:23]
	v_mfma_f32_16x16x32_bf16 v[16:19], v[228:231], v[204:207], v[16:19]
	v_mfma_f32_16x16x32_bf16 v[4:7], v[220:223], v[212:215], v[4:7]
	v_mfma_f32_16x16x32_bf16 v[0:3], v[228:231], v[212:215], v[0:3]
	s_add_i32 s28, 0, 0x18000
	v_add_u32_e32 v160, s28, v163
	s_barrier
	ds_read_b128 v[146:149], v160
	ds_read_b128 v[150:153], v160 offset:1024
	ds_read_b128 v[154:157], v160 offset:2048
	ds_read_b128 v[174:177], v160 offset:3072
	ds_read_b128 v[178:181], v171 offset:32768
	ds_read_b128 v[182:185], v171 offset:33792
	ds_read_b128 v[186:189], v171 offset:34816
	ds_read_b128 v[196:199], v171 offset:35840
	ds_read_b128 v[200:203], v171 offset:36864
	ds_read_b128 v[204:207], v171 offset:37888
	ds_read_b128 v[208:211], v171 offset:38912
	ds_read_b128 v[212:215], v171 offset:39936
	s_add_u32 s52, s52, 0x40000
	s_addc_u32 s53, s53, 0
	s_mov_b32 m0, s56
	v_lshl_add_u64 v[216:217], s[52:53], 0, v[134:135]
	global_load_lds_dwordx4 v[216:217], off
	v_lshl_add_u64 v[216:217], s[52:53], 0, v[130:131]
	s_mov_b32 m0, s57
	s_nop 0
	global_load_lds_dwordx4 v[216:217], off
	s_waitcnt lgkmcnt(8)
	s_barrier
	s_waitcnt lgkmcnt(0)
	v_mfma_f32_16x16x32_bf16 v[124:127], v[146:149], v[178:181], v[124:127]
	v_mfma_f32_16x16x32_bf16 v[120:123], v[154:157], v[178:181], v[120:123]
	v_mfma_f32_16x16x32_bf16 v[108:111], v[146:149], v[186:189], v[108:111]
	v_mfma_f32_16x16x32_bf16 v[104:107], v[154:157], v[186:189], v[104:107]
	v_mfma_f32_16x16x32_bf16 v[92:95], v[146:149], v[200:203], v[92:95]
	v_mfma_f32_16x16x32_bf16 v[88:91], v[154:157], v[200:203], v[88:91]
	v_mfma_f32_16x16x32_bf16 v[76:79], v[146:149], v[208:211], v[76:79]
	v_mfma_f32_16x16x32_bf16 v[72:75], v[154:157], v[208:211], v[72:75]
	v_mfma_f32_16x16x32_bf16 v[124:127], v[150:153], v[182:185], v[124:127]
	v_mfma_f32_16x16x32_bf16 v[120:123], v[174:177], v[182:185], v[120:123]
	v_mfma_f32_16x16x32_bf16 v[108:111], v[150:153], v[196:199], v[108:111]
	v_mfma_f32_16x16x32_bf16 v[104:107], v[174:177], v[196:199], v[104:107]
	v_mfma_f32_16x16x32_bf16 v[92:95], v[150:153], v[204:207], v[92:95]
	v_mfma_f32_16x16x32_bf16 v[88:91], v[174:177], v[204:207], v[88:91]
	v_mfma_f32_16x16x32_bf16 v[76:79], v[150:153], v[212:215], v[76:79]
	v_mfma_f32_16x16x32_bf16 v[72:75], v[174:177], v[212:215], v[72:75]
	s_barrier
	s_add_i32 s29, 0, 0x1c000
	s_add_i32 s28, s28, s13
	v_add_u32_e32 v160, s29, v163
	v_lshl_add_u64 v[158:159], v[158:159], 0, s[8:9]
	s_mov_b32 m0, s28
	ds_read_b128 v[216:219], v160
	ds_read_b128 v[220:223], v160 offset:1024
	ds_read_b128 v[224:227], v160 offset:2048
	ds_read_b128 v[228:231], v160 offset:3072
	global_load_lds_dwordx4 v[158:159], off
	v_lshl_add_u64 v[158:159], v[164:165], 0, s[8:9]
	s_add_i32 m0, s28, 0x2000
	s_nop 0
	global_load_lds_dwordx4 v[158:159], off
	s_barrier
	s_waitcnt lgkmcnt(0)
	v_mfma_f32_16x16x32_bf16 v[116:119], v[216:219], v[178:181], v[116:119]
	v_mfma_f32_16x16x32_bf16 v[112:115], v[224:227], v[178:181], v[112:115]
	v_mfma_f32_16x16x32_bf16 v[100:103], v[216:219], v[186:189], v[100:103]
	v_mfma_f32_16x16x32_bf16 v[96:99], v[224:227], v[186:189], v[96:99]
	v_mfma_f32_16x16x32_bf16 v[84:87], v[216:219], v[200:203], v[84:87]
	v_mfma_f32_16x16x32_bf16 v[80:83], v[224:227], v[200:203], v[80:83]
	v_mfma_f32_16x16x32_bf16 v[68:71], v[216:219], v[208:211], v[68:71]
	v_mfma_f32_16x16x32_bf16 v[64:67], v[224:227], v[208:211], v[64:67]
	v_mfma_f32_16x16x32_bf16 v[116:119], v[220:223], v[182:185], v[116:119]
	v_mfma_f32_16x16x32_bf16 v[112:115], v[228:231], v[182:185], v[112:115]
	v_mfma_f32_16x16x32_bf16 v[100:103], v[220:223], v[196:199], v[100:103]
	v_mfma_f32_16x16x32_bf16 v[96:99], v[228:231], v[196:199], v[96:99]
	v_mfma_f32_16x16x32_bf16 v[84:87], v[220:223], v[204:207], v[84:87]
	v_mfma_f32_16x16x32_bf16 v[80:83], v[228:231], v[204:207], v[80:83]
	v_mfma_f32_16x16x32_bf16 v[68:71], v[220:223], v[212:215], v[68:71]
	v_mfma_f32_16x16x32_bf16 v[64:67], v[228:231], v[212:215], v[64:67]
	s_mov_b32 m0, s60
	v_lshl_add_u64 v[158:159], v[190:191], 0, s[8:9]
	s_barrier
	ds_read_b128 v[178:181], v171 offset:49152
	ds_read_b128 v[182:185], v171 offset:50176
	ds_read_b128 v[186:189], v171 offset:51200
	ds_read_b128 v[196:199], v171 offset:52224
	ds_read_b128 v[200:203], v171 offset:53248
	ds_read_b128 v[204:207], v171 offset:54272
	ds_read_b128 v[208:211], v171 offset:55296
	ds_read_b128 v[212:215], v171 offset:56320
	global_load_lds_dwordx4 v[158:159], off
	v_lshl_add_u64 v[158:159], v[232:233], 0, s[8:9]
	s_mov_b32 m0, s61
	s_nop 0
	global_load_lds_dwordx4 v[158:159], off
	s_barrier
	s_waitcnt lgkmcnt(0)
	v_mfma_f32_16x16x32_bf16 v[60:63], v[146:149], v[178:181], v[60:63]
	v_mfma_f32_16x16x32_bf16 v[56:59], v[154:157], v[178:181], v[56:59]
	v_mfma_f32_16x16x32_bf16 v[44:47], v[146:149], v[186:189], v[44:47]
	v_mfma_f32_16x16x32_bf16 v[40:43], v[154:157], v[186:189], v[40:43]
	v_mfma_f32_16x16x32_bf16 v[28:31], v[146:149], v[200:203], v[28:31]
	v_mfma_f32_16x16x32_bf16 v[24:27], v[154:157], v[200:203], v[24:27]
	v_mfma_f32_16x16x32_bf16 v[12:15], v[146:149], v[208:211], v[12:15]
	v_mfma_f32_16x16x32_bf16 v[8:11], v[154:157], v[208:211], v[8:11]
	v_mfma_f32_16x16x32_bf16 v[60:63], v[150:153], v[182:185], v[60:63]
	v_mfma_f32_16x16x32_bf16 v[56:59], v[174:177], v[182:185], v[56:59]
	v_mfma_f32_16x16x32_bf16 v[44:47], v[150:153], v[196:199], v[44:47]
	v_mfma_f32_16x16x32_bf16 v[40:43], v[174:177], v[196:199], v[40:43]
	v_mfma_f32_16x16x32_bf16 v[28:31], v[150:153], v[204:207], v[28:31]
	v_mfma_f32_16x16x32_bf16 v[24:27], v[174:177], v[204:207], v[24:27]
	v_mfma_f32_16x16x32_bf16 v[12:15], v[150:153], v[212:215], v[12:15]
	v_mfma_f32_16x16x32_bf16 v[8:11], v[174:177], v[212:215], v[8:11]
	s_barrier
	s_add_u32 s50, s50, 0x10080
	s_addc_u32 s51, s51, 0
	s_add_i32 s28, s29, s13
	v_lshl_add_u64 v[146:147], s[50:51], 0, v[132:133]
	s_mov_b32 m0, s28
	s_nop 0
	global_load_lds_dwordx4 v[146:147], off
	v_lshl_add_u64 v[146:147], s[50:51], 0, v[128:129]
	s_add_i32 m0, s28, 0x2000
	s_nop 0
	global_load_lds_dwordx4 v[146:147], off
	s_waitcnt vmcnt(6)
	s_barrier
	v_mfma_f32_16x16x32_bf16 v[52:55], v[216:219], v[178:181], v[52:55]
	v_mfma_f32_16x16x32_bf16 v[48:51], v[224:227], v[178:181], v[48:51]
	v_mfma_f32_16x16x32_bf16 v[36:39], v[216:219], v[186:189], v[36:39]
	v_mfma_f32_16x16x32_bf16 v[32:35], v[224:227], v[186:189], v[32:35]
	v_mfma_f32_16x16x32_bf16 v[20:23], v[216:219], v[200:203], v[20:23]
	v_mfma_f32_16x16x32_bf16 v[16:19], v[224:227], v[200:203], v[16:19]
	v_mfma_f32_16x16x32_bf16 v[4:7], v[216:219], v[208:211], v[4:7]
	v_mfma_f32_16x16x32_bf16 v[0:3], v[224:227], v[208:211], v[0:3]
	v_mfma_f32_16x16x32_bf16 v[52:55], v[220:223], v[182:185], v[52:55]
	v_mfma_f32_16x16x32_bf16 v[48:51], v[228:231], v[182:185], v[48:51]
	v_mfma_f32_16x16x32_bf16 v[36:39], v[220:223], v[196:199], v[36:39]
	v_mfma_f32_16x16x32_bf16 v[32:35], v[228:231], v[196:199], v[32:35]
	v_mfma_f32_16x16x32_bf16 v[20:23], v[220:223], v[204:207], v[20:23]
	v_mfma_f32_16x16x32_bf16 v[16:19], v[228:231], v[204:207], v[16:19]
	v_mfma_f32_16x16x32_bf16 v[4:7], v[220:223], v[212:215], v[4:7]
	v_mfma_f32_16x16x32_bf16 v[0:3], v[228:231], v[212:215], v[0:3]
	s_add_i32 s78, s78, 2
	s_add_u32 s0, s0, 0x100
	s_addc_u32 s1, s1, 0
	s_add_u32 s76, s76, 0x100
	s_addc_u32 s77, s77, 0
	s_cmp_gt_u32 s78, 13
	s_barrier
	s_cbranch_scc0 .LBB0_904
	v_lshl_add_u32 v146, s6, 8, v161
	v_or_b32_e32 v164, 16, v146
	v_ashrrev_i32_e32 v165, 31, v164
	v_lshlrev_b64 v[148:149], 6, v[164:165]
	v_or_b32_e32 v158, 32, v146
	v_lshl_add_u64 v[148:149], v[136:137], 0, v[148:149]
	v_ashrrev_i32_e32 v159, 31, v158
	v_or_b32_e32 v156, 48, v146
	global_load_dwordx4 v[174:177], v[148:149], off
	v_lshlrev_b64 v[148:149], 6, v[158:159]
	v_ashrrev_i32_e32 v157, 31, v156
	v_add_u32_e32 v154, 0x80, v146
	v_lshl_add_u64 v[148:149], v[136:137], 0, v[148:149]
	v_lshlrev_b64 v[150:151], 6, v[156:157]
	v_ashrrev_i32_e32 v155, 31, v154
	v_lshl_add_u64 v[150:151], v[136:137], 0, v[150:151]
	global_load_dwordx4 v[178:181], v[148:149], off
	global_load_dwordx4 v[182:185], v[150:151], off
	v_lshlrev_b64 v[148:149], 6, v[154:155]
	v_lshl_add_u64 v[148:149], v[136:137], 0, v[148:149]
	global_load_dwordx4 v[186:189], v[148:149], off
	v_ashrrev_i32_e32 v147, 31, v146
	v_lshlrev_b64 v[148:149], 6, v[146:147]
	v_add_u32_e32 v152, 0x90, v146
	v_lshl_add_u64 v[148:149], v[136:137], 0, v[148:149]
	v_ashrrev_i32_e32 v153, 31, v152
	global_load_dwordx4 v[196:199], v[148:149], off
	v_lshlrev_b64 v[148:149], 6, v[152:153]
	v_lshl_add_u64 v[148:149], v[136:137], 0, v[148:149]
	global_load_dwordx4 v[200:203], v[148:149], off
	v_add_u32_e32 v148, 0xa0, v146
	v_ashrrev_i32_e32 v149, 31, v148
	v_lshlrev_b64 v[150:151], 6, v[148:149]
	v_lshl_add_u64 v[150:151], v[136:137], 0, v[150:151]
	global_load_dwordx4 v[204:207], v[150:151], off
	v_add_u32_e32 v150, 0xb0, v146
	v_ashrrev_i32_e32 v151, 31, v150
	v_lshlrev_b64 v[208:209], 6, v[150:151]
	v_lshl_add_u64 v[208:209], v[136:137], 0, v[208:209]
	global_load_dwordx4 v[208:211], v[208:209], off
	v_and_b32_e32 v149, 64, v173
	v_xor_b32_e32 v147, 16, v173
	v_add_u32_e32 v149, 64, v149
	v_cmp_lt_i32_e32 vcc, v147, v149
	v_xor_b32_e32 v153, 32, v173
	v_mov_b64_e32 v[190:191], s[12:13]
	v_cndmask_b32_e32 v147, v173, v147, vcc
	v_lshlrev_b32_e32 v147, 2, v147
	v_cmp_lt_i32_e32 vcc, v153, v149
	s_waitcnt vmcnt(0)
	v_mov_b32_e32 v212, v175
	v_mov_b32_e32 v213, v176
	v_mov_b32_e32 v175, v177
	v_pk_add_f32 v[174:175], v[212:213], v[174:175]
	v_cndmask_b32_e32 v149, v173, v153, vcc
	v_lshlrev_b32_e32 v149, 2, v149
	v_mov_b32_e32 v176, v179
	v_mov_b32_e32 v177, v180
	v_mov_b32_e32 v179, v181
	v_mov_b32_e32 v180, v183
	v_mov_b32_e32 v181, v184
	v_mov_b32_e32 v183, v185
	v_mov_b32_e32 v184, v187
	v_mov_b32_e32 v185, v188
	v_mov_b32_e32 v187, v189
	v_pk_add_f32 v[176:177], v[176:177], v[178:179]
	v_pk_add_f32 v[178:179], v[180:181], v[182:183]
	v_pk_add_f32 v[180:181], v[184:185], v[186:187]
	v_mov_b32_e32 v182, v176
	v_mov_b32_e32 v183, v174
	v_mov_b32_e32 v174, v177
	v_mov_b32_e32 v176, v180
	v_mov_b32_e32 v177, v178
	v_mov_b32_e32 v178, v181
	v_pk_add_f32 v[174:175], v[182:183], v[174:175]
	v_pk_add_f32 v[176:177], v[176:177], v[178:179]
	ds_bpermute_b32 v179, v147, v175
	ds_bpermute_b32 v178, v147, v174
	ds_bpermute_b32 v181, v147, v177
	ds_bpermute_b32 v180, v147, v176
	v_mov_b32_e32 v184, v201
	v_mov_b32_e32 v185, v202
	s_waitcnt lgkmcnt(0)
	v_pk_add_f32 v[174:175], v[174:175], v[178:179]
	ds_bpermute_b32 v179, v149, v175
	v_pk_add_f32 v[176:177], v[176:177], v[180:181]
	ds_bpermute_b32 v178, v149, v174
	ds_bpermute_b32 v181, v149, v177
	ds_bpermute_b32 v180, v149, v176
	v_mov_b32_e32 v201, v203
	v_mov_b32_e32 v182, v197
	s_waitcnt lgkmcnt(2)
	v_pk_add_f32 v[174:175], v[174:175], v[178:179]
	v_pk_add_f32 v[178:179], v[184:185], v[200:201]
	s_waitcnt lgkmcnt(0)
	v_pk_add_f32 v[176:177], v[176:177], v[180:181]
	v_pk_fma_f32 v[174:175], v[174:175], s[10:11], v[190:191] op_sel_hi:[1,0,0]
	v_mov_b32_e32 v180, v205
	v_mov_b32_e32 v181, v206
	v_mov_b32_e32 v205, v207
	v_mul_f32_e32 v151, 0x4b800000, v175
	v_cmp_gt_f32_e32 vcc, s65, v175
	v_pk_add_f32 v[180:181], v[180:181], v[204:205]
	v_mov_b32_e32 v185, v178
	v_cndmask_b32_e32 v151, v175, v151, vcc
	v_mov_b32_e32 v184, v180
	v_mov_b32_e32 v178, v181
	v_rsq_f32_e32 v151, v151
	v_pk_add_f32 v[178:179], v[184:185], v[178:179]
	ds_bpermute_b32 v181, v147, v179
	ds_bpermute_b32 v180, v147, v178
	v_pk_fma_f32 v[176:177], v[176:177], s[10:11], v[190:191] op_sel_hi:[1,0,0]
	v_mul_f32_e32 v153, 0x4b800000, v174
	v_cmp_gt_f32_e64 s[0:1], s65, v174
	v_mul_f32_e32 v157, 0x45800000, v151
	v_mul_f32_e32 v155, 0x4b800000, v177
	v_cndmask_b32_e64 v153, v174, v153, s[0:1]
	v_cmp_gt_f32_e64 s[6:7], s65, v177
	v_cndmask_b32_e32 v174, v151, v157, vcc
	v_mul_f32_e32 v151, 0x4b800000, v176
	v_cmp_gt_f32_e32 vcc, s65, v176
	v_cndmask_b32_e64 v155, v177, v155, s[6:7]
	v_rsq_f32_e32 v153, v153
	v_cndmask_b32_e32 v151, v176, v151, vcc
	s_waitcnt lgkmcnt(0)
	v_pk_add_f32 v[176:177], v[178:179], v[180:181]
	ds_bpermute_b32 v179, v149, v177
	ds_bpermute_b32 v178, v149, v176
	v_rsq_f32_e32 v155, v155
	v_mul_f32_e32 v159, 0x45800000, v153
	v_cndmask_b32_e64 v180, v153, v159, s[0:1]
	v_rsq_f32_e32 v151, v151
	s_waitcnt lgkmcnt(0)
	v_pk_add_f32 v[176:177], v[176:177], v[178:179]
	v_mul_f32_e32 v153, 0x45800000, v155
	v_pk_fma_f32 v[176:177], v[176:177], s[10:11], v[190:191] op_sel_hi:[1,0,0]
	v_cndmask_b32_e64 v170, v155, v153, s[6:7]
	v_mul_f32_e32 v155, 0x4b800000, v177
	v_cmp_gt_f32_e64 s[0:1], s65, v177
	v_mul_f32_e32 v157, 0x4b800000, v176
	v_cmp_gt_f32_e64 s[6:7], s65, v176
	v_cndmask_b32_e64 v155, v177, v155, s[0:1]
	v_rsq_f32_e32 v155, v155
	v_cndmask_b32_e64 v157, v176, v157, s[6:7]
	v_rsq_f32_e32 v157, v157
	v_mul_f32_e32 v153, 0x45800000, v151
	v_cndmask_b32_e32 v168, v151, v153, vcc
	v_mul_f32_e32 v151, 0x45800000, v155
	v_mov_b32_e32 v183, v198
	v_mov_b32_e32 v197, v199
	v_cndmask_b32_e64 v166, v155, v151, s[0:1]
	v_mul_f32_e32 v151, 0x45800000, v157
	v_mov_b32_e32 v176, v209
	v_mov_b32_e32 v177, v210
	v_mov_b32_e32 v209, v211
	v_pk_add_f32 v[182:183], v[182:183], v[196:197]
	v_cndmask_b32_e64 v162, v157, v151, s[6:7]
	v_pk_add_f32 v[176:177], v[176:177], v[208:209]
	v_mov_b32_e32 v178, v182
	v_mov_b32_e32 v179, v176
	v_mov_b32_e32 v176, v183
	v_pk_add_f32 v[176:177], v[178:179], v[176:177]
	ds_bpermute_b32 v178, v147, v176
	ds_bpermute_b32 v179, v147, v177
	v_lshl_or_b32 v182, s66, 8, v167
	v_pk_mul_f32 v[100:101], v[100:101], v[174:175] op_sel_hi:[1,0]
	v_pk_mul_f32 v[108:109], v[108:109], v[174:175] op_sel_hi:[1,0]
	v_ashrrev_i32_e32 v183, 31, v182
	s_waitcnt lgkmcnt(0)
	v_pk_add_f32 v[176:177], v[176:177], v[178:179]
	ds_bpermute_b32 v178, v149, v176
	ds_bpermute_b32 v179, v149, v177
	v_pk_mul_f32 v[96:97], v[96:97], v[174:175] op_sel_hi:[1,0]
	v_pk_mul_f32 v[102:103], v[102:103], v[174:175] op_sel_hi:[1,0]
	v_pk_mul_f32 v[110:111], v[110:111], v[174:175] op_sel_hi:[1,0]
	v_cvt_pk_bf16_f32 v108, v108, v109
	s_waitcnt lgkmcnt(0)
	v_pk_add_f32 v[176:177], v[176:177], v[178:179]
	v_pk_mul_f32 v[106:107], v[106:107], v[174:175] op_sel_hi:[1,0]
	v_pk_fma_f32 v[176:177], v[176:177], s[10:11], v[190:191] op_sel_hi:[1,0,0]
	v_pk_mul_f32 v[104:105], v[104:105], v[174:175] op_sel_hi:[1,0]
	v_mul_f32_e32 v147, 0x4b800000, v177
	v_cmp_gt_f32_e32 vcc, s65, v177
	v_mul_f32_e32 v149, 0x4b800000, v176
	v_cmp_gt_f32_e64 s[0:1], s65, v176
	v_cndmask_b32_e32 v147, v177, v147, vcc
	v_rsq_f32_e32 v147, v147
	v_cndmask_b32_e64 v149, v176, v149, s[0:1]
	v_rsq_f32_e32 v149, v149
	v_cvt_pk_bf16_f32 v100, v100, v101
	v_mul_f32_e32 v151, 0x45800000, v147
	v_cndmask_b32_e32 v160, v147, v151, vcc
	v_mul_f32_e32 v147, 0x45800000, v149
	v_cndmask_b32_e64 v176, v149, v147, s[0:1]
	v_pk_mul_f32 v[112:113], v[112:113], v[176:177] op_sel_hi:[1,0]
	v_pk_mul_f32 v[116:117], v[116:117], v[176:177] op_sel_hi:[1,0]
	v_pk_mul_f32 v[124:125], v[124:125], v[176:177] op_sel_hi:[1,0]
	v_pk_mul_f32 v[122:123], v[122:123], v[176:177] op_sel_hi:[1,0]
	v_pk_mul_f32 v[120:121], v[120:121], v[176:177] op_sel_hi:[1,0]
	v_pk_mul_f32 v[114:115], v[114:115], v[176:177] op_sel_hi:[1,0]
	v_pk_mul_f32 v[118:119], v[118:119], v[176:177] op_sel_hi:[1,0]
	v_pk_mul_f32 v[126:127], v[126:127], v[176:177] op_sel_hi:[1,0]
	v_cvt_pk_bf16_f32 v124, v124, v125
	v_cvt_pk_bf16_f32 v120, v120, v121
	v_cvt_pk_bf16_f32 v121, v122, v123
	v_cvt_pk_bf16_f32 v122, v116, v117
	v_cvt_pk_bf16_f32 v112, v112, v113
	v_cvt_pk_bf16_f32 v125, v126, v127
	v_cvt_pk_bf16_f32 v118, v118, v119
	v_cvt_pk_bf16_f32 v113, v114, v115
	v_cndmask_b32_e64 v114, v124, v122, s[2:3]
	v_mov_b32_e32 v123, 0
	v_cndmask_b32_e64 v115, v120, v112, s[2:3]
	v_mov_b32_e32 v126, 0
	v_mov_b32_dpp v123, v114 row_ror:8 row_mask:0xf bank_mask:0xf
	v_cndmask_b32_e64 v114, v125, v118, s[2:3]
	v_mov_b32_e32 v119, 0
	v_mov_b32_dpp v126, v115 row_ror:8 row_mask:0xf bank_mask:0xf
	v_mov_b32_e32 v127, 0
	v_mov_b32_dpp v119, v114 row_ror:8 row_mask:0xf bank_mask:0xf
	v_cndmask_b32_e64 v114, v121, v113, s[2:3]
	v_cndmask_b32_e64 v116, v126, v120, s[2:3]
	v_cndmask_b32_e64 v120, v112, v126, s[2:3]
	v_add_u32_e32 v112, -8, v146
	v_mov_b32_dpp v127, v114 row_ror:8 row_mask:0xf bank_mask:0xf
	v_cndmask_b32_e64 v112, v112, v146, s[2:3]
	v_cndmask_b32_e64 v117, v127, v121, s[2:3]
	v_cndmask_b32_e64 v121, v113, v127, s[2:3]
	v_ashrrev_i32_e32 v113, 31, v112
	v_lshlrev_b64 v[112:113], 10, v[112:113]
	v_cndmask_b32_e64 v115, v119, v125, s[2:3]
	v_cndmask_b32_e64 v114, v123, v124, s[2:3]
	v_cndmask_b32_e64 v119, v118, v119, s[2:3]
	v_cndmask_b32_e64 v118, v122, v123, s[2:3]
	v_lshl_add_u64 v[122:123], s[38:39], 0, v[112:113]
	v_lshlrev_b64 v[112:113], 1, v[182:183]
	v_pk_mul_f32 v[98:99], v[98:99], v[174:175] op_sel_hi:[1,0]
	v_cvt_pk_bf16_f32 v109, v110, v111
	v_cvt_pk_bf16_f32 v104, v104, v105
	v_cvt_pk_bf16_f32 v105, v106, v107
	v_cvt_pk_bf16_f32 v101, v102, v103
	v_cvt_pk_bf16_f32 v102, v96, v97
	v_cndmask_b32_e64 v96, v108, v100, s[2:3]
	v_mov_b32_e32 v106, 0
	v_lshl_add_u64 v[122:123], v[122:123], 0, v[112:113]
	v_cvt_pk_bf16_f32 v103, v98, v99
	v_mov_b32_dpp v106, v96 row_ror:8 row_mask:0xf bank_mask:0xf
	v_cndmask_b32_e64 v96, v109, v101, s[2:3]
	v_mov_b32_e32 v107, 0
	v_cndmask_b32_e64 v97, v104, v102, s[2:3]
	v_mov_b32_e32 v110, 0
	global_store_dwordx4 v[122:123], v[114:117], off
	v_mov_b32_dpp v107, v96 row_ror:8 row_mask:0xf bank_mask:0xf
	v_cndmask_b32_e64 v96, v105, v103, s[2:3]
	v_add_u32_e32 v116, 8, v146
	v_mov_b32_dpp v110, v97 row_ror:8 row_mask:0xf bank_mask:0xf
	v_mov_b32_e32 v111, 0
	v_cndmask_b32_e64 v114, v146, v116, s[2:3]
	v_cndmask_b32_e64 v98, v110, v104, s[2:3]
	v_mov_b32_dpp v111, v96 row_ror:8 row_mask:0xf bank_mask:0xf
	v_cndmask_b32_e64 v104, v116, v164, s[2:3]
	v_ashrrev_i32_e32 v115, 31, v114
	v_cndmask_b32_e64 v99, v111, v105, s[2:3]
	v_ashrrev_i32_e32 v105, 31, v104
	v_pk_mul_f32 v[84:85], v[84:85], v[180:181] op_sel_hi:[1,0]
	v_pk_mul_f32 v[92:93], v[92:93], v[180:181] op_sel_hi:[1,0]
	v_lshlrev_b64 v[114:115], 10, v[114:115]
	v_lshlrev_b64 v[104:105], 10, v[104:105]
	v_pk_mul_f32 v[80:81], v[80:81], v[180:181] op_sel_hi:[1,0]
	v_pk_mul_f32 v[86:87], v[86:87], v[180:181] op_sel_hi:[1,0]
	v_pk_mul_f32 v[94:95], v[94:95], v[180:181] op_sel_hi:[1,0]
	v_cvt_pk_bf16_f32 v92, v92, v93
	v_pk_mul_f32 v[90:91], v[90:91], v[180:181] op_sel_hi:[1,0]
	v_pk_mul_f32 v[88:89], v[88:89], v[180:181] op_sel_hi:[1,0]
	v_cvt_pk_bf16_f32 v84, v84, v85
	v_lshl_add_u64 v[114:115], s[38:39], 0, v[114:115]
	v_lshl_add_u64 v[104:105], s[38:39], 0, v[104:105]
	v_pk_mul_f32 v[82:83], v[82:83], v[180:181] op_sel_hi:[1,0]
	v_cvt_pk_bf16_f32 v93, v94, v95
	v_cvt_pk_bf16_f32 v88, v88, v89
	v_cvt_pk_bf16_f32 v89, v90, v91
	v_cvt_pk_bf16_f32 v85, v86, v87
	v_cvt_pk_bf16_f32 v86, v80, v81
	v_cndmask_b32_e64 v80, v92, v84, s[2:3]
	v_mov_b32_e32 v90, 0
	v_lshl_add_u64 v[114:115], v[114:115], 0, v[112:113]
	v_cndmask_b32_e64 v97, v107, v109, s[2:3]
	v_cndmask_b32_e64 v96, v106, v108, s[2:3]
	v_lshl_add_u64 v[104:105], v[104:105], 0, v[112:113]
	v_cvt_pk_bf16_f32 v87, v82, v83
	v_mov_b32_dpp v90, v80 row_ror:8 row_mask:0xf bank_mask:0xf
	v_cndmask_b32_e64 v80, v93, v85, s[2:3]
	v_mov_b32_e32 v91, 0
	v_cndmask_b32_e64 v81, v88, v86, s[2:3]
	v_mov_b32_e32 v94, 0
	global_store_dwordx4 v[114:115], v[118:121], off
	global_store_dwordx4 v[104:105], v[96:99], off
	v_mov_b32_dpp v91, v80 row_ror:8 row_mask:0xf bank_mask:0xf
	v_cndmask_b32_e64 v80, v89, v87, s[2:3]
	v_add_u32_e32 v98, 24, v146
	v_mov_b32_dpp v94, v81 row_ror:8 row_mask:0xf bank_mask:0xf
	v_mov_b32_e32 v95, 0
	v_cndmask_b32_e64 v96, v164, v98, s[2:3]
	v_cndmask_b32_e64 v82, v94, v88, s[2:3]
	v_mov_b32_dpp v95, v80 row_ror:8 row_mask:0xf bank_mask:0xf
	v_cndmask_b32_e64 v88, v98, v158, s[2:3]
	v_ashrrev_i32_e32 v97, 31, v96
	v_cndmask_b32_e64 v83, v95, v89, s[2:3]
	v_ashrrev_i32_e32 v89, 31, v88
	v_pk_mul_f32 v[68:69], v[68:69], v[170:171] op_sel_hi:[1,0]
	v_pk_mul_f32 v[76:77], v[76:77], v[170:171] op_sel_hi:[1,0]
	v_lshlrev_b64 v[96:97], 10, v[96:97]
	v_lshlrev_b64 v[88:89], 10, v[88:89]
	v_pk_mul_f32 v[64:65], v[64:65], v[170:171] op_sel_hi:[1,0]
	v_pk_mul_f32 v[70:71], v[70:71], v[170:171] op_sel_hi:[1,0]
	v_pk_mul_f32 v[78:79], v[78:79], v[170:171] op_sel_hi:[1,0]
	v_cvt_pk_bf16_f32 v76, v76, v77
	v_pk_mul_f32 v[74:75], v[74:75], v[170:171] op_sel_hi:[1,0]
	v_pk_mul_f32 v[72:73], v[72:73], v[170:171] op_sel_hi:[1,0]
	v_cvt_pk_bf16_f32 v68, v68, v69
	v_lshl_add_u64 v[96:97], s[38:39], 0, v[96:97]
	v_lshl_add_u64 v[88:89], s[38:39], 0, v[88:89]
	v_pk_mul_f32 v[66:67], v[66:67], v[170:171] op_sel_hi:[1,0]
	v_cvt_pk_bf16_f32 v77, v78, v79
	v_cvt_pk_bf16_f32 v72, v72, v73
	v_cvt_pk_bf16_f32 v73, v74, v75
	v_cvt_pk_bf16_f32 v69, v70, v71
	v_cvt_pk_bf16_f32 v70, v64, v65
	v_cndmask_b32_e64 v64, v76, v68, s[2:3]
	v_mov_b32_e32 v74, 0
	v_cndmask_b32_e64 v103, v103, v111, s[2:3]
	v_cndmask_b32_e64 v102, v102, v110, s[2:3]
	v_cndmask_b32_e64 v101, v101, v107, s[2:3]
	v_cndmask_b32_e64 v100, v100, v106, s[2:3]
	v_lshl_add_u64 v[96:97], v[96:97], 0, v[112:113]
	v_cndmask_b32_e64 v81, v91, v93, s[2:3]
	v_cndmask_b32_e64 v80, v90, v92, s[2:3]
	v_lshl_add_u64 v[88:89], v[88:89], 0, v[112:113]
	v_cvt_pk_bf16_f32 v71, v66, v67
	v_mov_b32_dpp v74, v64 row_ror:8 row_mask:0xf bank_mask:0xf
	v_cndmask_b32_e64 v64, v77, v69, s[2:3]
	v_mov_b32_e32 v75, 0
	v_cndmask_b32_e64 v65, v72, v70, s[2:3]
	v_mov_b32_e32 v78, 0
	global_store_dwordx4 v[96:97], v[100:103], off
	global_store_dwordx4 v[88:89], v[80:83], off
	v_mov_b32_dpp v75, v64 row_ror:8 row_mask:0xf bank_mask:0xf
	v_cndmask_b32_e64 v64, v73, v71, s[2:3]
	v_add_u32_e32 v82, 40, v146
	v_mov_b32_dpp v78, v65 row_ror:8 row_mask:0xf bank_mask:0xf
	v_mov_b32_e32 v79, 0
	v_cndmask_b32_e64 v80, v158, v82, s[2:3]
	v_cndmask_b32_e64 v66, v78, v72, s[2:3]
	v_mov_b32_dpp v79, v64 row_ror:8 row_mask:0xf bank_mask:0xf
	v_cndmask_b32_e64 v72, v82, v156, s[2:3]
	v_ashrrev_i32_e32 v81, 31, v80
	v_cndmask_b32_e64 v67, v79, v73, s[2:3]
	v_ashrrev_i32_e32 v73, 31, v72
	v_pk_mul_f32 v[48:49], v[48:49], v[168:169] op_sel_hi:[1,0]
	v_pk_mul_f32 v[54:55], v[54:55], v[168:169] op_sel_hi:[1,0]
	v_pk_mul_f32 v[52:53], v[52:53], v[168:169] op_sel_hi:[1,0]
	v_pk_mul_f32 v[60:61], v[60:61], v[168:169] op_sel_hi:[1,0]
	v_pk_mul_f32 v[56:57], v[56:57], v[168:169] op_sel_hi:[1,0]
	v_lshlrev_b64 v[80:81], 10, v[80:81]
	v_lshlrev_b64 v[72:73], 10, v[72:73]
	v_pk_mul_f32 v[62:63], v[62:63], v[168:169] op_sel_hi:[1,0]
	v_cvt_pk_bf16_f32 v60, v60, v61
	v_pk_mul_f32 v[58:59], v[58:59], v[168:169] op_sel_hi:[1,0]
	v_cvt_pk_bf16_f32 v56, v56, v57
	v_cvt_pk_bf16_f32 v52, v52, v53
	v_cvt_pk_bf16_f32 v53, v54, v55
	v_cvt_pk_bf16_f32 v54, v48, v49
	v_lshl_add_u64 v[80:81], s[38:39], 0, v[80:81]
	v_lshl_add_u64 v[72:73], s[38:39], 0, v[72:73]
	v_pk_mul_f32 v[50:51], v[50:51], v[168:169] op_sel_hi:[1,0]
	v_cvt_pk_bf16_f32 v61, v62, v63
	v_cvt_pk_bf16_f32 v57, v58, v59
	v_cndmask_b32_e64 v48, v60, v52, s[2:3]
	v_mov_b32_e32 v58, 0
	v_cndmask_b32_e64 v49, v56, v54, s[2:3]
	v_mov_b32_e32 v62, 0
	v_cndmask_b32_e64 v87, v87, v95, s[2:3]
	v_cndmask_b32_e64 v86, v86, v94, s[2:3]
	v_cndmask_b32_e64 v85, v85, v91, s[2:3]
	v_cndmask_b32_e64 v84, v84, v90, s[2:3]
	v_lshl_add_u64 v[80:81], v[80:81], 0, v[112:113]
	v_cndmask_b32_e64 v65, v75, v77, s[2:3]
	v_cndmask_b32_e64 v64, v74, v76, s[2:3]
	v_lshl_add_u64 v[72:73], v[72:73], 0, v[112:113]
	v_cvt_pk_bf16_f32 v55, v50, v51
	v_mov_b32_dpp v58, v48 row_ror:8 row_mask:0xf bank_mask:0xf
	v_cndmask_b32_e64 v48, v61, v53, s[2:3]
	v_mov_b32_e32 v59, 0
	v_mov_b32_dpp v62, v49 row_ror:8 row_mask:0xf bank_mask:0xf
	global_store_dwordx4 v[80:81], v[84:87], off
	global_store_dwordx4 v[72:73], v[64:67], off
	v_mov_b32_dpp v59, v48 row_ror:8 row_mask:0xf bank_mask:0xf
	v_cndmask_b32_e64 v48, v57, v55, s[2:3]
	v_add_u32_e32 v64, 56, v146
	v_mov_b32_e32 v63, 0
	v_cndmask_b32_e64 v50, v62, v56, s[2:3]
	v_add_u32_e32 v56, 0x78, v146
	v_cndmask_b32_e64 v64, v156, v64, s[2:3]
	v_mov_b32_dpp v63, v48 row_ror:8 row_mask:0xf bank_mask:0xf
	v_cndmask_b32_e64 v56, v56, v154, s[2:3]
	v_ashrrev_i32_e32 v65, 31, v64
	v_cndmask_b32_e64 v51, v63, v57, s[2:3]
	v_ashrrev_i32_e32 v57, 31, v56
	v_pk_mul_f32 v[36:37], v[36:37], v[166:167] op_sel_hi:[1,0]
	v_pk_mul_f32 v[44:45], v[44:45], v[166:167] op_sel_hi:[1,0]
	v_lshlrev_b64 v[64:65], 10, v[64:65]
	v_lshlrev_b64 v[56:57], 10, v[56:57]
	v_pk_mul_f32 v[32:33], v[32:33], v[166:167] op_sel_hi:[1,0]
	v_pk_mul_f32 v[38:39], v[38:39], v[166:167] op_sel_hi:[1,0]
	v_pk_mul_f32 v[46:47], v[46:47], v[166:167] op_sel_hi:[1,0]
	v_cvt_pk_bf16_f32 v44, v44, v45
	v_pk_mul_f32 v[42:43], v[42:43], v[166:167] op_sel_hi:[1,0]
	v_pk_mul_f32 v[40:41], v[40:41], v[166:167] op_sel_hi:[1,0]
	v_cvt_pk_bf16_f32 v36, v36, v37
	v_lshl_add_u64 v[64:65], s[38:39], 0, v[64:65]
	v_lshl_add_u64 v[56:57], s[38:39], 0, v[56:57]
	v_pk_mul_f32 v[34:35], v[34:35], v[166:167] op_sel_hi:[1,0]
	v_cvt_pk_bf16_f32 v45, v46, v47
	v_cvt_pk_bf16_f32 v40, v40, v41
	v_cvt_pk_bf16_f32 v41, v42, v43
	v_cvt_pk_bf16_f32 v37, v38, v39
	v_cvt_pk_bf16_f32 v38, v32, v33
	v_cndmask_b32_e64 v32, v44, v36, s[2:3]
	v_mov_b32_e32 v42, 0
	v_cndmask_b32_e64 v71, v71, v79, s[2:3]
	v_cndmask_b32_e64 v70, v70, v78, s[2:3]
	v_cndmask_b32_e64 v69, v69, v75, s[2:3]
	v_cndmask_b32_e64 v68, v68, v74, s[2:3]
	v_lshl_add_u64 v[64:65], v[64:65], 0, v[112:113]
	v_cndmask_b32_e64 v49, v59, v61, s[2:3]
	v_cndmask_b32_e64 v48, v58, v60, s[2:3]
	v_lshl_add_u64 v[56:57], v[56:57], 0, v[112:113]
	v_cvt_pk_bf16_f32 v39, v34, v35
	v_mov_b32_dpp v42, v32 row_ror:8 row_mask:0xf bank_mask:0xf
	v_cndmask_b32_e64 v32, v45, v37, s[2:3]
	v_mov_b32_e32 v43, 0
	v_cndmask_b32_e64 v33, v40, v38, s[2:3]
	v_mov_b32_e32 v46, 0
	global_store_dwordx4 v[64:65], v[68:71], off
	global_store_dwordx4 v[56:57], v[48:51], off
	v_mov_b32_dpp v43, v32 row_ror:8 row_mask:0xf bank_mask:0xf
	v_cndmask_b32_e64 v32, v41, v39, s[2:3]
	v_add_u32_e32 v50, 0x88, v146
	v_mov_b32_dpp v46, v33 row_ror:8 row_mask:0xf bank_mask:0xf
	v_mov_b32_e32 v47, 0
	v_cndmask_b32_e64 v34, v46, v40, s[2:3]
	v_cndmask_b32_e64 v40, v50, v152, s[2:3]
	v_mov_b32_dpp v47, v32 row_ror:8 row_mask:0xf bank_mask:0xf
	v_cndmask_b32_e64 v35, v47, v41, s[2:3]
	v_ashrrev_i32_e32 v41, 31, v40
	v_pk_mul_f32 v[20:21], v[20:21], v[162:163] op_sel_hi:[1,0]
	v_pk_mul_f32 v[28:29], v[28:29], v[162:163] op_sel_hi:[1,0]
	v_lshlrev_b64 v[40:41], 10, v[40:41]
	v_pk_mul_f32 v[16:17], v[16:17], v[162:163] op_sel_hi:[1,0]
	v_pk_mul_f32 v[22:23], v[22:23], v[162:163] op_sel_hi:[1,0]
	v_pk_mul_f32 v[30:31], v[30:31], v[162:163] op_sel_hi:[1,0]
	v_cvt_pk_bf16_f32 v28, v28, v29
	v_pk_mul_f32 v[26:27], v[26:27], v[162:163] op_sel_hi:[1,0]
	v_pk_mul_f32 v[24:25], v[24:25], v[162:163] op_sel_hi:[1,0]
	v_cvt_pk_bf16_f32 v20, v20, v21
	v_lshl_add_u64 v[40:41], s[38:39], 0, v[40:41]
	v_pk_mul_f32 v[18:19], v[18:19], v[162:163] op_sel_hi:[1,0]
	v_cvt_pk_bf16_f32 v29, v30, v31
	v_cvt_pk_bf16_f32 v24, v24, v25
	v_cvt_pk_bf16_f32 v25, v26, v27
	v_cvt_pk_bf16_f32 v21, v22, v23
	v_cvt_pk_bf16_f32 v22, v16, v17
	v_cndmask_b32_e64 v16, v28, v20, s[2:3]
	v_mov_b32_e32 v26, 0
	v_cndmask_b32_e64 v33, v43, v45, s[2:3]
	v_cndmask_b32_e64 v32, v42, v44, s[2:3]
	v_lshl_add_u64 v[40:41], v[40:41], 0, v[112:113]
	v_cvt_pk_bf16_f32 v23, v18, v19
	v_mov_b32_dpp v26, v16 row_ror:8 row_mask:0xf bank_mask:0xf
	v_cndmask_b32_e64 v16, v29, v21, s[2:3]
	v_mov_b32_e32 v27, 0
	v_cndmask_b32_e64 v17, v24, v22, s[2:3]
	v_mov_b32_e32 v30, 0
	global_store_dwordx4 v[40:41], v[32:35], off
	v_mov_b32_dpp v27, v16 row_ror:8 row_mask:0xf bank_mask:0xf
	v_cndmask_b32_e64 v16, v25, v23, s[2:3]
	v_add_u32_e32 v34, 0x98, v146
	v_mov_b32_dpp v30, v17 row_ror:8 row_mask:0xf bank_mask:0xf
	v_mov_b32_e32 v31, 0
	v_cndmask_b32_e64 v18, v30, v24, s[2:3]
	v_cndmask_b32_e64 v24, v34, v148, s[2:3]
	v_mov_b32_dpp v31, v16 row_ror:8 row_mask:0xf bank_mask:0xf
	v_cndmask_b32_e64 v19, v31, v25, s[2:3]
	v_ashrrev_i32_e32 v25, 31, v24
	v_lshlrev_b64 v[24:25], 10, v[24:25]
	v_lshl_add_u64 v[24:25], s[38:39], 0, v[24:25]
	v_cndmask_b32_e64 v17, v27, v29, s[2:3]
	v_cndmask_b32_e64 v16, v26, v28, s[2:3]
	v_lshl_add_u64 v[24:25], v[24:25], 0, v[112:113]
	global_store_dwordx4 v[24:25], v[16:19], off
	v_pk_mul_f32 v[4:5], v[4:5], v[160:161] op_sel_hi:[1,0]
	v_pk_mul_f32 v[12:13], v[12:13], v[160:161] op_sel_hi:[1,0]
	v_add_u32_e32 v18, 0xa8, v146
	v_cndmask_b32_e64 v16, v148, v18, s[2:3]
	v_ashrrev_i32_e32 v17, 31, v16
	v_pk_mul_f32 v[10:11], v[10:11], v[160:161] op_sel_hi:[1,0]
	v_pk_mul_f32 v[8:9], v[8:9], v[160:161] op_sel_hi:[1,0]
	v_lshlrev_b64 v[16:17], 10, v[16:17]
	v_pk_mul_f32 v[0:1], v[0:1], v[160:161] op_sel_hi:[1,0]
	v_pk_mul_f32 v[6:7], v[6:7], v[160:161] op_sel_hi:[1,0]
	v_pk_mul_f32 v[14:15], v[14:15], v[160:161] op_sel_hi:[1,0]
	v_cvt_pk_bf16_f32 v12, v12, v13
	v_cvt_pk_bf16_f32 v8, v8, v9
	v_cvt_pk_bf16_f32 v9, v10, v11
	v_cvt_pk_bf16_f32 v10, v4, v5
	v_lshl_add_u64 v[16:17], s[38:39], 0, v[16:17]
	v_pk_mul_f32 v[2:3], v[2:3], v[160:161] op_sel_hi:[1,0]
	v_cvt_pk_bf16_f32 v13, v14, v15
	v_cvt_pk_bf16_f32 v6, v6, v7
	v_cvt_pk_bf16_f32 v7, v0, v1
	v_cndmask_b32_e64 v0, v12, v10, s[2:3]
	v_mov_b32_e32 v14, 0
	v_cndmask_b32_e64 v4, v18, v150, s[2:3]
	v_cndmask_b32_e64 v23, v23, v31, s[2:3]
	v_cndmask_b32_e64 v22, v22, v30, s[2:3]
	v_cndmask_b32_e64 v21, v21, v27, s[2:3]
	v_cndmask_b32_e64 v20, v20, v26, s[2:3]
	v_lshl_add_u64 v[16:17], v[16:17], 0, v[112:113]
	v_cvt_pk_bf16_f32 v11, v2, v3
	v_mov_b32_dpp v14, v0 row_ror:8 row_mask:0xf bank_mask:0xf
	v_cndmask_b32_e64 v0, v13, v6, s[2:3]
	v_mov_b32_e32 v15, 0
	v_ashrrev_i32_e32 v5, 31, v4
	global_store_dwordx4 v[16:17], v[20:23], off
	v_mov_b32_dpp v15, v0 row_ror:8 row_mask:0xf bank_mask:0xf
	v_cndmask_b32_e64 v0, v9, v11, s[2:3]
	v_cndmask_b32_e64 v1, v8, v7, s[2:3]
	v_mov_b32_e32 v16, 0
	v_mov_b32_e32 v17, 0
	v_lshlrev_b64 v[4:5], 10, v[4:5]
	v_mov_b32_dpp v16, v1 row_ror:8 row_mask:0xf bank_mask:0xf
	v_mov_b32_dpp v17, v0 row_ror:8 row_mask:0xf bank_mask:0xf
	v_lshl_add_u64 v[4:5], s[38:39], 0, v[4:5]
	v_cndmask_b32_e64 v3, v17, v9, s[2:3]
	v_cndmask_b32_e64 v2, v16, v8, s[2:3]
	v_cndmask_b32_e64 v1, v15, v13, s[2:3]
	v_cndmask_b32_e64 v0, v14, v12, s[2:3]
	v_lshl_add_u64 v[4:5], v[4:5], 0, v[112:113]
	global_store_dwordx4 v[4:5], v[0:3], off
	v_cndmask_b32_e64 v48, v154, v50, s[2:3]
	v_cndmask_b32_e64 v32, v152, v34, s[2:3]
	v_add_u32_e32 v0, 0xb8, v146
	v_cndmask_b32_e64 v0, v150, v0, s[2:3]
	v_ashrrev_i32_e32 v49, 31, v48
	v_ashrrev_i32_e32 v33, 31, v32
	v_ashrrev_i32_e32 v1, 31, v0
	v_lshlrev_b64 v[48:49], 10, v[48:49]
	v_lshlrev_b64 v[32:33], 10, v[32:33]
	v_lshlrev_b64 v[0:1], 10, v[0:1]
	v_lshl_add_u64 v[48:49], s[38:39], 0, v[48:49]
	v_lshl_add_u64 v[32:33], s[38:39], 0, v[32:33]
	v_lshl_add_u64 v[0:1], s[38:39], 0, v[0:1]
	v_cndmask_b32_e64 v55, v55, v63, s[2:3]
	v_cndmask_b32_e64 v54, v54, v62, s[2:3]
	v_cndmask_b32_e64 v53, v53, v59, s[2:3]
	v_cndmask_b32_e64 v52, v52, v58, s[2:3]
	v_lshl_add_u64 v[48:49], v[48:49], 0, v[112:113]
	v_cndmask_b32_e64 v39, v39, v47, s[2:3]
	v_cndmask_b32_e64 v38, v38, v46, s[2:3]
	v_cndmask_b32_e64 v37, v37, v43, s[2:3]
	v_cndmask_b32_e64 v36, v36, v42, s[2:3]
	v_lshl_add_u64 v[32:33], v[32:33], 0, v[112:113]
	v_lshl_add_u64 v[4:5], v[0:1], 0, v[112:113]
	v_cndmask_b32_e64 v3, v11, v17, s[2:3]
	v_cndmask_b32_e64 v2, v7, v16, s[2:3]
	v_cndmask_b32_e64 v1, v6, v15, s[2:3]
	v_cndmask_b32_e64 v0, v10, v14, s[2:3]
	s_and_b64 vcc, exec, s[4:5]
	s_mov_b32 s66, s36
	s_mov_b32 s6, s44
	s_mov_b64 s[50:51], s[48:49]
	s_mov_b64 s[52:53], s[46:47]
	global_store_dwordx4 v[48:49], v[52:55], off
	global_store_dwordx4 v[32:33], v[36:39], off
	global_store_dwordx4 v[4:5], v[0:3], off
	s_cbranch_vccz .LBB0_897
	s_waitcnt vmcnt(0)
	s_cmpk_gt_u32 s11, 0xff
	s_cbranch_scc1 .LBB0_908
	s_barrier

.LBB0_997:
	ds_read_b128 v[128:131], v164
	ds_read_b128 v[132:135], v164 offset:1024
	ds_read_b128 v[152:155], v164 offset:2048
	ds_read_b128 v[156:159], v164 offset:3072
	ds_read_b128 v[168:171], v165
	ds_read_b128 v[172:175], v165 offset:1024
	ds_read_b128 v[176:179], v165 offset:2048
	ds_read_b128 v[180:183], v165 offset:3072
	ds_read_b128 v[184:187], v165 offset:4096
	ds_read_b128 v[188:191], v165 offset:5120
	ds_read_b128 v[196:199], v165 offset:6144
	ds_read_b128 v[200:203], v165 offset:7168
	s_add_u32 s28, s48, 0xfffe0080
	s_addc_u32 s29, s49, -1
	s_cmp_eq_u32 s79, 4
	s_cselect_b32 s53, s9, s29
	s_cselect_b32 s52, s41, s28
	s_cselect_b32 s51, s39, s78
	s_cselect_b32 s50, s76, s77
	v_lshl_add_u64 v[204:205], s[48:49], 0, v[144:145]
	s_add_i32 m0, s55, 0xc000
	global_load_lds_dwordx4 v[204:205], off
	v_lshl_add_u64 v[204:205], s[48:49], 0, v[146:147]
	s_add_i32 m0, s55, 0xe000
	s_nop 0
	global_load_lds_dwordx4 v[204:205], off
	s_waitcnt lgkmcnt(8)
	s_barrier
	s_waitcnt lgkmcnt(0)
	v_mfma_f32_16x16x32_bf16 v[124:127], v[128:131], v[168:171], v[124:127]
	v_mfma_f32_16x16x32_bf16 v[120:123], v[152:155], v[168:171], v[120:123]
	v_mfma_f32_16x16x32_bf16 v[108:111], v[128:131], v[176:179], v[108:111]
	v_mfma_f32_16x16x32_bf16 v[104:107], v[152:155], v[176:179], v[104:107]
	v_mfma_f32_16x16x32_bf16 v[92:95], v[128:131], v[184:187], v[92:95]
	v_mfma_f32_16x16x32_bf16 v[88:91], v[152:155], v[184:187], v[88:91]
	v_mfma_f32_16x16x32_bf16 v[76:79], v[128:131], v[196:199], v[76:79]
	v_mfma_f32_16x16x32_bf16 v[72:75], v[152:155], v[196:199], v[72:75]
	v_mfma_f32_16x16x32_bf16 v[124:127], v[132:135], v[172:175], v[124:127]
	v_mfma_f32_16x16x32_bf16 v[120:123], v[156:159], v[172:175], v[120:123]
	v_mfma_f32_16x16x32_bf16 v[108:111], v[132:135], v[180:183], v[108:111]
	v_mfma_f32_16x16x32_bf16 v[104:107], v[156:159], v[180:183], v[104:107]
	v_mfma_f32_16x16x32_bf16 v[92:95], v[132:135], v[188:191], v[92:95]
	v_mfma_f32_16x16x32_bf16 v[88:91], v[156:159], v[188:191], v[88:91]
	v_mfma_f32_16x16x32_bf16 v[76:79], v[132:135], v[200:203], v[76:79]
	v_mfma_f32_16x16x32_bf16 v[72:75], v[156:159], v[200:203], v[72:75]
	s_barrier
	s_add_i32 s28, s65, s54
	v_lshl_add_u64 v[220:221], s[50:51], 0, v[138:139]
	s_mov_b32 m0, s28
	ds_read_b128 v[204:207], v166
	ds_read_b128 v[208:211], v166 offset:1024
	ds_read_b128 v[212:215], v166 offset:2048
	ds_read_b128 v[216:219], v166 offset:3072
	global_load_lds_dwordx4 v[220:221], off
	v_lshl_add_u64 v[222:223], s[50:51], 0, v[142:143]
	s_add_i32 m0, s28, 0x2000
	s_nop 0
	global_load_lds_dwordx4 v[222:223], off
	s_barrier
	s_waitcnt lgkmcnt(0)
	v_mfma_f32_16x16x32_bf16 v[116:119], v[204:207], v[168:171], v[116:119]
	v_mfma_f32_16x16x32_bf16 v[112:115], v[212:215], v[168:171], v[112:115]
	v_mfma_f32_16x16x32_bf16 v[100:103], v[204:207], v[176:179], v[100:103]
	v_mfma_f32_16x16x32_bf16 v[96:99], v[212:215], v[176:179], v[96:99]
	v_mfma_f32_16x16x32_bf16 v[84:87], v[204:207], v[184:187], v[84:87]
	v_mfma_f32_16x16x32_bf16 v[80:83], v[212:215], v[184:187], v[80:83]
	v_mfma_f32_16x16x32_bf16 v[68:71], v[204:207], v[196:199], v[68:71]
	v_mfma_f32_16x16x32_bf16 v[64:67], v[212:215], v[196:199], v[64:67]
	v_mfma_f32_16x16x32_bf16 v[116:119], v[208:211], v[172:175], v[116:119]
	v_mfma_f32_16x16x32_bf16 v[112:115], v[216:219], v[172:175], v[112:115]
	v_mfma_f32_16x16x32_bf16 v[100:103], v[208:211], v[180:183], v[100:103]
	v_mfma_f32_16x16x32_bf16 v[96:99], v[216:219], v[180:183], v[96:99]
	v_mfma_f32_16x16x32_bf16 v[84:87], v[208:211], v[188:191], v[84:87]
	v_mfma_f32_16x16x32_bf16 v[80:83], v[216:219], v[188:191], v[80:83]
	v_mfma_f32_16x16x32_bf16 v[68:71], v[208:211], v[200:203], v[68:71]
	v_mfma_f32_16x16x32_bf16 v[64:67], v[216:219], v[200:203], v[64:67]
	s_mov_b32 m0, s55
	v_lshl_add_u64 v[224:225], s[52:53], 0, v[136:137]
	s_barrier
	ds_read_b128 v[168:171], v165 offset:16384
	ds_read_b128 v[172:175], v165 offset:17408
	ds_read_b128 v[176:179], v165 offset:18432
	ds_read_b128 v[180:183], v165 offset:19456
	ds_read_b128 v[184:187], v165 offset:20480
	ds_read_b128 v[188:191], v165 offset:21504
	ds_read_b128 v[196:199], v165 offset:22528
	ds_read_b128 v[200:203], v165 offset:23552
	global_load_lds_dwordx4 v[224:225], off
	v_lshl_add_u64 v[226:227], s[52:53], 0, v[140:141]
	s_mov_b32 m0, s56
	s_nop 0
	global_load_lds_dwordx4 v[226:227], off
	s_barrier
	s_waitcnt lgkmcnt(0)
	v_mfma_f32_16x16x32_bf16 v[60:63], v[128:131], v[168:171], v[60:63]
	v_mfma_f32_16x16x32_bf16 v[56:59], v[152:155], v[168:171], v[56:59]
	v_mfma_f32_16x16x32_bf16 v[44:47], v[128:131], v[176:179], v[44:47]
	v_mfma_f32_16x16x32_bf16 v[40:43], v[152:155], v[176:179], v[40:43]
	v_mfma_f32_16x16x32_bf16 v[28:31], v[128:131], v[184:187], v[28:31]
	v_mfma_f32_16x16x32_bf16 v[24:27], v[152:155], v[184:187], v[24:27]
	v_mfma_f32_16x16x32_bf16 v[12:15], v[128:131], v[196:199], v[12:15]
	v_mfma_f32_16x16x32_bf16 v[8:11], v[152:155], v[196:199], v[8:11]
	v_mfma_f32_16x16x32_bf16 v[60:63], v[132:135], v[172:175], v[60:63]
	v_mfma_f32_16x16x32_bf16 v[56:59], v[156:159], v[172:175], v[56:59]
	v_mfma_f32_16x16x32_bf16 v[44:47], v[132:135], v[180:183], v[44:47]
	v_mfma_f32_16x16x32_bf16 v[40:43], v[156:159], v[180:183], v[40:43]
	v_mfma_f32_16x16x32_bf16 v[28:31], v[132:135], v[188:191], v[28:31]
	v_mfma_f32_16x16x32_bf16 v[24:27], v[156:159], v[188:191], v[24:27]
	v_mfma_f32_16x16x32_bf16 v[12:15], v[132:135], v[200:203], v[12:15]
	v_mfma_f32_16x16x32_bf16 v[8:11], v[156:159], v[200:203], v[8:11]
	s_barrier
	s_add_u32 s80, s50, 0x8000
	s_addc_u32 s81, s51, 0
	s_add_i32 s28, s66, s54
	v_lshl_add_u64 v[128:129], s[80:81], 0, v[138:139]
	s_mov_b32 m0, s28
	s_nop 0
	global_load_lds_dwordx4 v[128:129], off
	v_lshl_add_u64 v[128:129], s[80:81], 0, v[142:143]
	s_add_i32 m0, s28, 0x2000
	s_nop 0
	global_load_lds_dwordx4 v[128:129], off
	s_waitcnt vmcnt(6)
	s_barrier
	v_mfma_f32_16x16x32_bf16 v[52:55], v[204:207], v[168:171], v[52:55]
	v_mfma_f32_16x16x32_bf16 v[48:51], v[212:215], v[168:171], v[48:51]
	v_mfma_f32_16x16x32_bf16 v[36:39], v[204:207], v[176:179], v[36:39]
	v_mfma_f32_16x16x32_bf16 v[32:35], v[212:215], v[176:179], v[32:35]
	v_mfma_f32_16x16x32_bf16 v[20:23], v[204:207], v[184:187], v[20:23]
	v_mfma_f32_16x16x32_bf16 v[16:19], v[212:215], v[184:187], v[16:19]
	v_mfma_f32_16x16x32_bf16 v[4:7], v[204:207], v[196:199], v[4:7]
	v_mfma_f32_16x16x32_bf16 v[0:3], v[212:215], v[196:199], v[0:3]
	v_mfma_f32_16x16x32_bf16 v[52:55], v[208:211], v[172:175], v[52:55]
	v_mfma_f32_16x16x32_bf16 v[48:51], v[216:219], v[172:175], v[48:51]
	v_mfma_f32_16x16x32_bf16 v[36:39], v[208:211], v[180:183], v[36:39]
	v_mfma_f32_16x16x32_bf16 v[32:35], v[216:219], v[180:183], v[32:35]
	v_mfma_f32_16x16x32_bf16 v[20:23], v[208:211], v[188:191], v[20:23]
	v_mfma_f32_16x16x32_bf16 v[16:19], v[216:219], v[188:191], v[16:19]
	v_mfma_f32_16x16x32_bf16 v[4:7], v[208:211], v[200:203], v[4:7]
	v_mfma_f32_16x16x32_bf16 v[0:3], v[216:219], v[200:203], v[0:3]
	s_add_i32 s28, 0, 0x18000
	v_add_u32_e32 v156, s28, v161
	s_barrier
	ds_read_b128 v[128:131], v156
	ds_read_b128 v[132:135], v156 offset:1024
	ds_read_b128 v[152:155], v156 offset:2048
	ds_read_b128 v[156:159], v156 offset:3072
	ds_read_b128 v[168:171], v165 offset:32768
	ds_read_b128 v[172:175], v165 offset:33792
	ds_read_b128 v[176:179], v165 offset:34816
	ds_read_b128 v[180:183], v165 offset:35840
	ds_read_b128 v[184:187], v165 offset:36864
	ds_read_b128 v[188:191], v165 offset:37888
	ds_read_b128 v[196:199], v165 offset:38912
	ds_read_b128 v[200:203], v165 offset:39936
	s_add_u32 s52, s52, 0x20000
	s_addc_u32 s53, s53, 0
	s_mov_b32 m0, s57
	v_lshl_add_u64 v[204:205], s[52:53], 0, v[136:137]
	global_load_lds_dwordx4 v[204:205], off
	v_lshl_add_u64 v[204:205], s[52:53], 0, v[140:141]
	s_mov_b32 m0, s58
	s_nop 0
	global_load_lds_dwordx4 v[204:205], off
	s_waitcnt lgkmcnt(8)
	s_barrier
	s_waitcnt lgkmcnt(0)
	v_mfma_f32_16x16x32_bf16 v[124:127], v[128:131], v[168:171], v[124:127]
	v_mfma_f32_16x16x32_bf16 v[120:123], v[152:155], v[168:171], v[120:123]
	v_mfma_f32_16x16x32_bf16 v[108:111], v[128:131], v[176:179], v[108:111]
	v_mfma_f32_16x16x32_bf16 v[104:107], v[152:155], v[176:179], v[104:107]
	v_mfma_f32_16x16x32_bf16 v[92:95], v[128:131], v[184:187], v[92:95]
	v_mfma_f32_16x16x32_bf16 v[88:91], v[152:155], v[184:187], v[88:91]
	v_mfma_f32_16x16x32_bf16 v[76:79], v[128:131], v[196:199], v[76:79]
	v_mfma_f32_16x16x32_bf16 v[72:75], v[152:155], v[196:199], v[72:75]
	v_mfma_f32_16x16x32_bf16 v[124:127], v[132:135], v[172:175], v[124:127]
	v_mfma_f32_16x16x32_bf16 v[120:123], v[156:159], v[172:175], v[120:123]
	v_mfma_f32_16x16x32_bf16 v[108:111], v[132:135], v[180:183], v[108:111]
	v_mfma_f32_16x16x32_bf16 v[104:107], v[156:159], v[180:183], v[104:107]
	v_mfma_f32_16x16x32_bf16 v[92:95], v[132:135], v[188:191], v[92:95]
	v_mfma_f32_16x16x32_bf16 v[88:91], v[156:159], v[188:191], v[88:91]
	v_mfma_f32_16x16x32_bf16 v[76:79], v[132:135], v[200:203], v[76:79]
	v_mfma_f32_16x16x32_bf16 v[72:75], v[156:159], v[200:203], v[72:75]
	s_barrier
	s_add_i32 s29, 0, 0x1c000
	s_add_i32 s28, s28, s54
	v_add_u32_e32 v195, s29, v161
	v_lshl_add_u64 v[220:221], v[220:221], 0, s[36:37]
	s_mov_b32 m0, s28
	ds_read_b128 v[204:207], v195
	ds_read_b128 v[208:211], v195 offset:1024
	ds_read_b128 v[212:215], v195 offset:2048
	ds_read_b128 v[216:219], v195 offset:3072
	global_load_lds_dwordx4 v[220:221], off
	v_lshl_add_u64 v[220:221], v[222:223], 0, s[36:37]
	s_add_i32 m0, s28, 0x2000
	s_nop 0
	global_load_lds_dwordx4 v[220:221], off
	s_barrier
	s_waitcnt lgkmcnt(0)
	v_mfma_f32_16x16x32_bf16 v[116:119], v[204:207], v[168:171], v[116:119]
	v_mfma_f32_16x16x32_bf16 v[112:115], v[212:215], v[168:171], v[112:115]
	v_mfma_f32_16x16x32_bf16 v[100:103], v[204:207], v[176:179], v[100:103]
	v_mfma_f32_16x16x32_bf16 v[96:99], v[212:215], v[176:179], v[96:99]
	v_mfma_f32_16x16x32_bf16 v[84:87], v[204:207], v[184:187], v[84:87]
	v_mfma_f32_16x16x32_bf16 v[80:83], v[212:215], v[184:187], v[80:83]
	v_mfma_f32_16x16x32_bf16 v[68:71], v[204:207], v[196:199], v[68:71]
	v_mfma_f32_16x16x32_bf16 v[64:67], v[212:215], v[196:199], v[64:67]
	v_mfma_f32_16x16x32_bf16 v[116:119], v[208:211], v[172:175], v[116:119]
	v_mfma_f32_16x16x32_bf16 v[112:115], v[216:219], v[172:175], v[112:115]
	v_mfma_f32_16x16x32_bf16 v[100:103], v[208:211], v[180:183], v[100:103]
	v_mfma_f32_16x16x32_bf16 v[96:99], v[216:219], v[180:183], v[96:99]
	v_mfma_f32_16x16x32_bf16 v[84:87], v[208:211], v[188:191], v[84:87]
	v_mfma_f32_16x16x32_bf16 v[80:83], v[216:219], v[188:191], v[80:83]
	v_mfma_f32_16x16x32_bf16 v[68:71], v[208:211], v[200:203], v[68:71]
	v_mfma_f32_16x16x32_bf16 v[64:67], v[216:219], v[200:203], v[64:67]
	s_mov_b32 m0, s62
	v_lshl_add_u64 v[220:221], v[224:225], 0, s[36:37]
	s_barrier
	ds_read_b128 v[168:171], v165 offset:49152
	ds_read_b128 v[172:175], v165 offset:50176
	ds_read_b128 v[176:179], v165 offset:51200
	ds_read_b128 v[180:183], v165 offset:52224
	ds_read_b128 v[184:187], v165 offset:53248
	ds_read_b128 v[188:191], v165 offset:54272
	ds_read_b128 v[196:199], v165 offset:55296
	ds_read_b128 v[200:203], v165 offset:56320
	global_load_lds_dwordx4 v[220:221], off
	v_lshl_add_u64 v[220:221], v[226:227], 0, s[36:37]
	s_mov_b32 m0, s63
	s_nop 0
	global_load_lds_dwordx4 v[220:221], off
	s_barrier
	s_waitcnt lgkmcnt(0)
	v_mfma_f32_16x16x32_bf16 v[60:63], v[128:131], v[168:171], v[60:63]
	v_mfma_f32_16x16x32_bf16 v[56:59], v[152:155], v[168:171], v[56:59]
	v_mfma_f32_16x16x32_bf16 v[44:47], v[128:131], v[176:179], v[44:47]
	v_mfma_f32_16x16x32_bf16 v[40:43], v[152:155], v[176:179], v[40:43]
	v_mfma_f32_16x16x32_bf16 v[28:31], v[128:131], v[184:187], v[28:31]
	v_mfma_f32_16x16x32_bf16 v[24:27], v[152:155], v[184:187], v[24:27]
	v_mfma_f32_16x16x32_bf16 v[12:15], v[128:131], v[196:199], v[12:15]
	v_mfma_f32_16x16x32_bf16 v[8:11], v[152:155], v[196:199], v[8:11]
	v_mfma_f32_16x16x32_bf16 v[60:63], v[132:135], v[172:175], v[60:63]
	v_mfma_f32_16x16x32_bf16 v[56:59], v[156:159], v[172:175], v[56:59]
	v_mfma_f32_16x16x32_bf16 v[44:47], v[132:135], v[180:183], v[44:47]
	v_mfma_f32_16x16x32_bf16 v[40:43], v[156:159], v[180:183], v[40:43]
	v_mfma_f32_16x16x32_bf16 v[28:31], v[132:135], v[188:191], v[28:31]
	v_mfma_f32_16x16x32_bf16 v[24:27], v[156:159], v[188:191], v[24:27]
	v_mfma_f32_16x16x32_bf16 v[12:15], v[132:135], v[200:203], v[12:15]
	v_mfma_f32_16x16x32_bf16 v[8:11], v[156:159], v[200:203], v[8:11]
	s_barrier
	s_add_u32 s50, s50, 0x8080
	s_addc_u32 s51, s51, 0
	s_add_i32 s28, s29, s54
	v_lshl_add_u64 v[128:129], s[50:51], 0, v[138:139]
	s_mov_b32 m0, s28
	s_nop 0
	global_load_lds_dwordx4 v[128:129], off
	v_lshl_add_u64 v[128:129], s[50:51], 0, v[142:143]
	s_add_i32 m0, s28, 0x2000
	s_nop 0
	global_load_lds_dwordx4 v[128:129], off
	s_waitcnt vmcnt(6)
	s_barrier
	v_mfma_f32_16x16x32_bf16 v[52:55], v[204:207], v[168:171], v[52:55]
	v_mfma_f32_16x16x32_bf16 v[48:51], v[212:215], v[168:171], v[48:51]
	v_mfma_f32_16x16x32_bf16 v[36:39], v[204:207], v[176:179], v[36:39]
	v_mfma_f32_16x16x32_bf16 v[32:35], v[212:215], v[176:179], v[32:35]
	v_mfma_f32_16x16x32_bf16 v[20:23], v[204:207], v[184:187], v[20:23]
	v_mfma_f32_16x16x32_bf16 v[16:19], v[212:215], v[184:187], v[16:19]
	v_mfma_f32_16x16x32_bf16 v[4:7], v[204:207], v[196:199], v[4:7]
	v_mfma_f32_16x16x32_bf16 v[0:3], v[212:215], v[196:199], v[0:3]
	v_mfma_f32_16x16x32_bf16 v[52:55], v[208:211], v[172:175], v[52:55]
	v_mfma_f32_16x16x32_bf16 v[48:51], v[216:219], v[172:175], v[48:51]
	v_mfma_f32_16x16x32_bf16 v[36:39], v[208:211], v[180:183], v[36:39]
	v_mfma_f32_16x16x32_bf16 v[32:35], v[216:219], v[180:183], v[32:35]
	v_mfma_f32_16x16x32_bf16 v[20:23], v[208:211], v[188:191], v[20:23]
	v_mfma_f32_16x16x32_bf16 v[16:19], v[216:219], v[188:191], v[16:19]
	v_mfma_f32_16x16x32_bf16 v[4:7], v[208:211], v[200:203], v[4:7]
	v_mfma_f32_16x16x32_bf16 v[0:3], v[216:219], v[200:203], v[0:3]
	s_add_i32 s79, s79, 2
	s_add_u32 s48, s48, 0x100
	s_addc_u32 s49, s49, 0
	s_add_u32 s77, s77, 0x100
	s_addc_u32 s78, s78, 0
	s_cmp_gt_u32 s79, 5
	s_barrier
	s_cbranch_scc0 .LBB0_997
	v_lshl_add_u32 v152, s8, 8, v160
	v_lshl_or_b32 v156, s10, 8, v162
	v_ashrrev_i32_e32 v153, 31, v152
	v_lshlrev_b64 v[128:129], 11, v[152:153]
	v_ashrrev_i32_e32 v157, 31, v156
	v_lshl_add_u64 v[128:129], s[42:43], 0, v[128:129]
	v_lshlrev_b64 v[130:131], 1, v[156:157]
	v_or_b32_e32 v158, 16, v152
	v_lshl_add_u64 v[128:129], v[128:129], 0, v[130:131]
	v_ashrrev_i32_e32 v159, 31, v158
	global_load_dwordx4 v[168:171], v[128:129], off
	global_load_dwordx4 v[172:175], v[128:129], off offset:64
	v_lshlrev_b64 v[128:129], 11, v[158:159]
	v_lshl_add_u64 v[128:129], s[42:43], 0, v[128:129]
	v_lshl_add_u64 v[128:129], v[128:129], 0, v[130:131]
	global_load_dwordx4 v[132:135], v[128:129], off
	s_nop 0
	global_load_dwordx4 v[128:131], v[128:129], off offset:64
	v_cndmask_b32_e64 v155, 0, 1, s[12:13]
	v_or_b32_e32 v154, v156, v163
	v_cmp_ne_u32_e64 s[8:9], 1, v155
	v_ashrrev_i32_e32 v155, 31, v154
	s_andn2_b64 vcc, exec, s[12:13]
	v_lshlrev_b64 v[154:155], 1, v[154:155]
	s_waitcnt vmcnt(0)
	v_lshlrev_b32_e32 v176, 16, v168
	v_and_b32_e32 v177, 0xffff0000, v168
	v_lshlrev_b32_e32 v168, 16, v169
	v_and_b32_e32 v169, 0xffff0000, v169
	v_lshlrev_b32_e32 v178, 16, v170
	v_and_b32_e32 v179, 0xffff0000, v170
	v_lshlrev_b32_e32 v170, 16, v171
	v_and_b32_e32 v171, 0xffff0000, v171
	v_lshlrev_b32_e32 v180, 16, v172
	v_and_b32_e32 v181, 0xffff0000, v172
	v_lshlrev_b32_e32 v172, 16, v173
	v_and_b32_e32 v173, 0xffff0000, v173
	v_lshlrev_b32_e32 v182, 16, v174
	v_and_b32_e32 v183, 0xffff0000, v174
	v_lshlrev_b32_e32 v174, 16, v175
	v_and_b32_e32 v175, 0xffff0000, v175
	v_pk_add_f32 v[126:127], v[126:127], v[168:169]
	v_pk_add_f32 v[124:125], v[124:125], v[176:177]
	v_pk_add_f32 v[122:123], v[122:123], v[170:171]
	v_pk_add_f32 v[120:121], v[120:121], v[178:179]
	v_pk_add_f32 v[118:119], v[118:119], v[172:173]
	v_pk_add_f32 v[116:117], v[116:117], v[180:181]
	v_pk_add_f32 v[114:115], v[114:115], v[174:175]
	v_pk_add_f32 v[112:113], v[112:113], v[182:183]
	v_add_u32_e32 v169, 8, v152
	s_cbranch_vccnz .LBB0_1000
	v_cvt_pk_bf16_f32 v168, v124, v125
	v_cvt_pk_bf16_f32 v174, v116, v117
	v_cvt_pk_bf16_f32 v170, v126, v127
	v_cvt_pk_bf16_f32 v171, v120, v121
	v_cvt_pk_bf16_f32 v175, v118, v119
	v_cvt_pk_bf16_f32 v176, v112, v113
	v_cndmask_b32_e64 v173, v168, v174, s[4:5]
	v_mov_b32_e32 v178, 0
	v_cvt_pk_bf16_f32 v172, v122, v123
	v_cvt_pk_bf16_f32 v177, v114, v115
	v_mov_b32_dpp v178, v173 row_ror:8 row_mask:0xf bank_mask:0xf
	v_cndmask_b32_e64 v173, v170, v175, s[4:5]
	v_mov_b32_e32 v179, 0
	v_cndmask_b32_e64 v180, v171, v176, s[4:5]
	v_mov_b32_e32 v181, 0
	v_mov_b32_dpp v179, v173 row_ror:8 row_mask:0xf bank_mask:0xf
	v_cndmask_b32_e64 v173, v172, v177, s[4:5]
	v_mov_b32_dpp v181, v180 row_ror:8 row_mask:0xf bank_mask:0xf
	v_mov_b32_e32 v180, 0
	v_cndmask_b32_e64 v174, v174, v178, s[4:5]
	v_cndmask_b32_e64 v175, v175, v179, s[4:5]
	v_mov_b32_dpp v180, v173 row_ror:8 row_mask:0xf bank_mask:0xf
	v_cndmask_b32_e64 v173, v180, v172, s[4:5]
	v_cndmask_b32_e64 v172, v181, v171, s[4:5]
	v_cndmask_b32_e64 v171, v179, v170, s[4:5]
	v_cndmask_b32_e64 v170, v178, v168, s[4:5]
	v_add_u32_e32 v168, -8, v152
	v_cndmask_b32_e64 v178, v168, v152, s[4:5]
	v_ashrrev_i32_e32 v179, 31, v178
	v_lshlrev_b64 v[178:179], 11, v[178:179]
	v_lshl_add_u64 v[178:179], s[68:69], 0, v[178:179]
	v_lshl_add_u64 v[178:179], v[178:179], 0, v[154:155]
	global_store_dwordx4 v[178:179], v[170:173], off
	v_cndmask_b32_e64 v177, v177, v180, s[4:5]
	v_cndmask_b32_e64 v176, v176, v181, s[4:5]
	v_cndmask_b32_e64 v170, v152, v169, s[4:5]
	v_ashrrev_i32_e32 v171, 31, v170
	v_lshlrev_b64 v[170:171], 11, v[170:171]
	v_lshl_add_u64 v[170:171], s[68:69], 0, v[170:171]
	v_lshl_add_u64 v[170:171], v[170:171], 0, v[154:155]
	global_store_dwordx4 v[170:171], v[174:177], off

.LBB0_1092:
	s_ashr_i32 s37, s36, 31
	v_cmp_lt_i64_e32 vcc, s[0:1], v[142:143]
	s_lshl_b64 s[0:1], s[36:37], 19
	s_add_u32 s38, s68, s0
	s_addc_u32 s39, s69, s1
	s_and_b64 s[0:1], vcc, exec
	s_cselect_b32 s37, s39, s45
	s_cselect_b32 s60, s38, s44
	s_ashr_i32 s13, s12, 31
	s_lshl_b64 s[0:1], s[12:13], 19
	s_add_u32 s40, s70, s0
	s_addc_u32 s41, s71, s1
	s_and_b64 s[0:1], vcc, exec
	s_cselect_b32 s13, s41, s43
	s_cselect_b32 s61, s40, s42
	s_add_u32 s0, s44, 0x40080
	s_addc_u32 s1, s45, 0
	s_add_u32 s62, s42, 0x100
	s_addc_u32 s63, s43, 0
	s_mov_b32 s64, -2
	ds_read_b128 v[146:149], v167
	ds_read_b128 v[150:153], v167 offset:1024
	ds_read_b128 v[178:181], v167 offset:2048
	ds_read_b128 v[182:185], v167 offset:3072
	ds_read_b128 v[186:189], v171
	ds_read_b128 v[196:199], v171 offset:1024
	ds_read_b128 v[200:203], v171 offset:2048
	ds_read_b128 v[204:207], v171 offset:3072
	ds_read_b128 v[208:211], v171 offset:4096
	ds_read_b128 v[212:215], v171 offset:5120
	ds_read_b128 v[216:219], v171 offset:6144
	ds_read_b128 v[220:223], v171 offset:7168
	s_add_u32 s28, s0, 0xfffc0080
	s_addc_u32 s29, s1, -1
	s_cmp_eq_u32 s64, 12
	s_cselect_b32 s45, s37, s29
	s_cselect_b32 s44, s60, s28
	s_cselect_b32 s43, s13, s63
	s_cselect_b32 s42, s61, s62
	v_lshl_add_u64 v[156:157], s[0:1], 0, v[138:139]
	s_add_i32 m0, s47, 0xc000
	global_load_lds_dwordx4 v[156:157], off
	v_lshl_add_u64 v[156:157], s[0:1], 0, v[140:141]
	s_add_i32 m0, s47, 0xe000
	s_nop 0
	global_load_lds_dwordx4 v[156:157], off
	s_waitcnt lgkmcnt(8)
	s_barrier
	s_waitcnt lgkmcnt(0)
	v_mfma_f32_16x16x32_bf16 v[124:127], v[146:149], v[186:189], 0
	v_mfma_f32_16x16x32_bf16 v[120:123], v[178:181], v[186:189], 0
	v_mfma_f32_16x16x32_bf16 v[108:111], v[146:149], v[200:203], 0
	v_mfma_f32_16x16x32_bf16 v[104:107], v[178:181], v[200:203], 0
	v_mfma_f32_16x16x32_bf16 v[92:95], v[146:149], v[208:211], 0
	v_mfma_f32_16x16x32_bf16 v[88:91], v[178:181], v[208:211], 0
	v_mfma_f32_16x16x32_bf16 v[76:79], v[146:149], v[216:219], 0
	v_mfma_f32_16x16x32_bf16 v[72:75], v[178:181], v[216:219], 0
	v_mfma_f32_16x16x32_bf16 v[124:127], v[150:153], v[196:199], v[124:127]
	v_mfma_f32_16x16x32_bf16 v[120:123], v[182:185], v[196:199], v[120:123]
	v_mfma_f32_16x16x32_bf16 v[108:111], v[150:153], v[204:207], v[108:111]
	v_mfma_f32_16x16x32_bf16 v[104:107], v[182:185], v[204:207], v[104:107]
	v_mfma_f32_16x16x32_bf16 v[92:95], v[150:153], v[212:215], v[92:95]
	v_mfma_f32_16x16x32_bf16 v[88:91], v[182:185], v[212:215], v[88:91]
	v_mfma_f32_16x16x32_bf16 v[76:79], v[150:153], v[220:223], v[76:79]
	v_mfma_f32_16x16x32_bf16 v[72:75], v[182:185], v[220:223], v[72:75]
	s_barrier
	s_add_i32 s28, s56, s11
	v_lshl_add_u64 v[156:157], s[42:43], 0, v[132:133]
	s_mov_b32 m0, s28
	ds_read_b128 v[224:227], v175
	ds_read_b128 v[228:231], v175 offset:1024
	ds_read_b128 v[232:235], v175 offset:2048
	ds_read_b128 v[236:239], v175 offset:3072
	global_load_lds_dwordx4 v[156:157], off
	v_lshl_add_u64 v[160:161], s[42:43], 0, v[128:129]
	s_add_i32 m0, s28, 0x2000
	s_nop 0
	global_load_lds_dwordx4 v[160:161], off
	s_barrier
	s_waitcnt lgkmcnt(0)
	v_mfma_f32_16x16x32_bf16 v[116:119], v[224:227], v[186:189], 0
	v_mfma_f32_16x16x32_bf16 v[112:115], v[232:235], v[186:189], 0
	v_mfma_f32_16x16x32_bf16 v[100:103], v[224:227], v[200:203], 0
	v_mfma_f32_16x16x32_bf16 v[96:99], v[232:235], v[200:203], 0
	v_mfma_f32_16x16x32_bf16 v[84:87], v[224:227], v[208:211], 0
	v_mfma_f32_16x16x32_bf16 v[80:83], v[232:235], v[208:211], 0
	v_mfma_f32_16x16x32_bf16 v[68:71], v[224:227], v[216:219], 0
	v_mfma_f32_16x16x32_bf16 v[64:67], v[232:235], v[216:219], 0
	v_mfma_f32_16x16x32_bf16 v[116:119], v[228:231], v[196:199], v[116:119]
	v_mfma_f32_16x16x32_bf16 v[112:115], v[236:239], v[196:199], v[112:115]
	v_mfma_f32_16x16x32_bf16 v[100:103], v[228:231], v[204:207], v[100:103]
	v_mfma_f32_16x16x32_bf16 v[96:99], v[236:239], v[204:207], v[96:99]
	v_mfma_f32_16x16x32_bf16 v[84:87], v[228:231], v[212:215], v[84:87]
	v_mfma_f32_16x16x32_bf16 v[80:83], v[236:239], v[212:215], v[80:83]
	v_mfma_f32_16x16x32_bf16 v[68:71], v[228:231], v[220:223], v[68:71]
	v_mfma_f32_16x16x32_bf16 v[64:67], v[236:239], v[220:223], v[64:67]
	s_mov_b32 m0, s47
	v_lshl_add_u64 v[164:165], s[44:45], 0, v[134:135]
	s_barrier
	ds_read_b128 v[186:189], v171 offset:16384
	ds_read_b128 v[196:199], v171 offset:17408
	ds_read_b128 v[200:203], v171 offset:18432
	ds_read_b128 v[204:207], v171 offset:19456
	ds_read_b128 v[208:211], v171 offset:20480
	ds_read_b128 v[212:215], v171 offset:21504
	ds_read_b128 v[216:219], v171 offset:22528
	ds_read_b128 v[220:223], v171 offset:23552
	global_load_lds_dwordx4 v[164:165], off
	v_lshl_add_u64 v[168:169], s[44:45], 0, v[130:131]
	s_mov_b32 m0, s48
	s_nop 0
	global_load_lds_dwordx4 v[168:169], off
	s_barrier
	s_waitcnt lgkmcnt(0)
	v_mfma_f32_16x16x32_bf16 v[60:63], v[146:149], v[186:189], 0
	v_mfma_f32_16x16x32_bf16 v[56:59], v[178:181], v[186:189], 0
	v_mfma_f32_16x16x32_bf16 v[44:47], v[146:149], v[200:203], 0
	v_mfma_f32_16x16x32_bf16 v[40:43], v[178:181], v[200:203], 0
	v_mfma_f32_16x16x32_bf16 v[28:31], v[146:149], v[208:211], 0
	v_mfma_f32_16x16x32_bf16 v[24:27], v[178:181], v[208:211], 0
	v_mfma_f32_16x16x32_bf16 v[12:15], v[146:149], v[216:219], 0
	v_mfma_f32_16x16x32_bf16 v[8:11], v[178:181], v[216:219], 0
	v_mfma_f32_16x16x32_bf16 v[60:63], v[150:153], v[196:199], v[60:63]
	v_mfma_f32_16x16x32_bf16 v[56:59], v[182:185], v[196:199], v[56:59]
	v_mfma_f32_16x16x32_bf16 v[44:47], v[150:153], v[204:207], v[44:47]
	v_mfma_f32_16x16x32_bf16 v[40:43], v[182:185], v[204:207], v[40:43]
	v_mfma_f32_16x16x32_bf16 v[28:31], v[150:153], v[212:215], v[28:31]
	v_mfma_f32_16x16x32_bf16 v[24:27], v[182:185], v[212:215], v[24:27]
	v_mfma_f32_16x16x32_bf16 v[12:15], v[150:153], v[220:223], v[12:15]
	v_mfma_f32_16x16x32_bf16 v[8:11], v[182:185], v[220:223], v[8:11]
	s_barrier
	s_add_u32 s66, s42, 0x40000
	s_addc_u32 s67, s43, 0
	s_add_i32 s28, s57, s11
	v_lshl_add_u64 v[146:147], s[66:67], 0, v[132:133]
	s_mov_b32 m0, s28
	s_nop 0
	global_load_lds_dwordx4 v[146:147], off
	v_lshl_add_u64 v[146:147], s[66:67], 0, v[128:129]
	s_add_i32 m0, s28, 0x2000
	s_nop 0
	global_load_lds_dwordx4 v[146:147], off
	s_waitcnt vmcnt(6)
	s_barrier
	v_mfma_f32_16x16x32_bf16 v[52:55], v[224:227], v[186:189], 0
	v_mfma_f32_16x16x32_bf16 v[48:51], v[232:235], v[186:189], 0
	v_mfma_f32_16x16x32_bf16 v[36:39], v[224:227], v[200:203], 0
	v_mfma_f32_16x16x32_bf16 v[32:35], v[232:235], v[200:203], 0
	v_mfma_f32_16x16x32_bf16 v[20:23], v[224:227], v[208:211], 0
	v_mfma_f32_16x16x32_bf16 v[16:19], v[232:235], v[208:211], 0
	v_mfma_f32_16x16x32_bf16 v[4:7], v[224:227], v[216:219], 0
	v_mfma_f32_16x16x32_bf16 v[0:3], v[232:235], v[216:219], 0
	v_mfma_f32_16x16x32_bf16 v[52:55], v[228:231], v[196:199], v[52:55]
	v_mfma_f32_16x16x32_bf16 v[48:51], v[236:239], v[196:199], v[48:51]
	v_mfma_f32_16x16x32_bf16 v[36:39], v[228:231], v[204:207], v[36:39]
	v_mfma_f32_16x16x32_bf16 v[32:35], v[236:239], v[204:207], v[32:35]
	v_mfma_f32_16x16x32_bf16 v[20:23], v[228:231], v[212:215], v[20:23]
	v_mfma_f32_16x16x32_bf16 v[16:19], v[236:239], v[212:215], v[16:19]
	v_mfma_f32_16x16x32_bf16 v[4:7], v[228:231], v[220:223], v[4:7]
	v_mfma_f32_16x16x32_bf16 v[0:3], v[236:239], v[220:223], v[0:3]
	s_add_i32 s28, 0, 0x18000
	v_add_u32_e32 v154, s28, v159
	s_barrier
	ds_read_b128 v[146:149], v154
	ds_read_b128 v[150:153], v154 offset:1024
	ds_read_b128 v[178:181], v154 offset:2048
	ds_read_b128 v[182:185], v154 offset:3072
	ds_read_b128 v[186:189], v171 offset:32768
	ds_read_b128 v[196:199], v171 offset:33792
	ds_read_b128 v[200:203], v171 offset:34816
	ds_read_b128 v[204:207], v171 offset:35840
	ds_read_b128 v[208:211], v171 offset:36864
	ds_read_b128 v[212:215], v171 offset:37888
	ds_read_b128 v[216:219], v171 offset:38912
	ds_read_b128 v[220:223], v171 offset:39936
	s_add_u32 s44, s44, 0x40000
	s_addc_u32 s45, s45, 0
	s_mov_b32 m0, s49
	v_lshl_add_u64 v[172:173], s[44:45], 0, v[134:135]
	global_load_lds_dwordx4 v[172:173], off
	v_lshl_add_u64 v[172:173], s[44:45], 0, v[130:131]
	s_mov_b32 m0, s50
	s_nop 0
	global_load_lds_dwordx4 v[172:173], off
	s_waitcnt lgkmcnt(8)
	s_barrier
	s_waitcnt lgkmcnt(0)
	v_mfma_f32_16x16x32_bf16 v[124:127], v[146:149], v[186:189], v[124:127]
	v_mfma_f32_16x16x32_bf16 v[120:123], v[178:181], v[186:189], v[120:123]
	v_mfma_f32_16x16x32_bf16 v[108:111], v[146:149], v[200:203], v[108:111]
	v_mfma_f32_16x16x32_bf16 v[104:107], v[178:181], v[200:203], v[104:107]
	v_mfma_f32_16x16x32_bf16 v[92:95], v[146:149], v[208:211], v[92:95]
	v_mfma_f32_16x16x32_bf16 v[88:91], v[178:181], v[208:211], v[88:91]
	v_mfma_f32_16x16x32_bf16 v[76:79], v[146:149], v[216:219], v[76:79]
	v_mfma_f32_16x16x32_bf16 v[72:75], v[178:181], v[216:219], v[72:75]
	v_mfma_f32_16x16x32_bf16 v[124:127], v[150:153], v[196:199], v[124:127]
	v_mfma_f32_16x16x32_bf16 v[120:123], v[182:185], v[196:199], v[120:123]
	v_mfma_f32_16x16x32_bf16 v[108:111], v[150:153], v[204:207], v[108:111]
	v_mfma_f32_16x16x32_bf16 v[104:107], v[182:185], v[204:207], v[104:107]
	v_mfma_f32_16x16x32_bf16 v[92:95], v[150:153], v[212:215], v[92:95]
	v_mfma_f32_16x16x32_bf16 v[88:91], v[182:185], v[212:215], v[88:91]
	v_mfma_f32_16x16x32_bf16 v[76:79], v[150:153], v[220:223], v[76:79]
	v_mfma_f32_16x16x32_bf16 v[72:75], v[182:185], v[220:223], v[72:75]
	s_barrier
	s_add_i32 s29, 0, 0x1c000
	s_add_i32 s28, s28, s11
	v_add_u32_e32 v154, s29, v159
	v_lshl_add_u64 v[156:157], v[156:157], 0, s[6:7]
	s_mov_b32 m0, s28
	ds_read_b128 v[224:227], v154
	ds_read_b128 v[228:231], v154 offset:1024
	ds_read_b128 v[232:235], v154 offset:2048
	ds_read_b128 v[236:239], v154 offset:3072
	global_load_lds_dwordx4 v[156:157], off
	v_lshl_add_u64 v[156:157], v[160:161], 0, s[6:7]
	s_add_i32 m0, s28, 0x2000
	s_nop 0
	global_load_lds_dwordx4 v[156:157], off
	s_barrier
	s_waitcnt lgkmcnt(0)
	v_mfma_f32_16x16x32_bf16 v[116:119], v[224:227], v[186:189], v[116:119]
	v_mfma_f32_16x16x32_bf16 v[112:115], v[232:235], v[186:189], v[112:115]
	v_mfma_f32_16x16x32_bf16 v[100:103], v[224:227], v[200:203], v[100:103]
	v_mfma_f32_16x16x32_bf16 v[96:99], v[232:235], v[200:203], v[96:99]
	v_mfma_f32_16x16x32_bf16 v[84:87], v[224:227], v[208:211], v[84:87]
	v_mfma_f32_16x16x32_bf16 v[80:83], v[232:235], v[208:211], v[80:83]
	v_mfma_f32_16x16x32_bf16 v[68:71], v[224:227], v[216:219], v[68:71]
	v_mfma_f32_16x16x32_bf16 v[64:67], v[232:235], v[216:219], v[64:67]
	v_mfma_f32_16x16x32_bf16 v[116:119], v[228:231], v[196:199], v[116:119]
	v_mfma_f32_16x16x32_bf16 v[112:115], v[236:239], v[196:199], v[112:115]
	v_mfma_f32_16x16x32_bf16 v[100:103], v[228:231], v[204:207], v[100:103]
	v_mfma_f32_16x16x32_bf16 v[96:99], v[236:239], v[204:207], v[96:99]
	v_mfma_f32_16x16x32_bf16 v[84:87], v[228:231], v[212:215], v[84:87]
	v_mfma_f32_16x16x32_bf16 v[80:83], v[236:239], v[212:215], v[80:83]
	v_mfma_f32_16x16x32_bf16 v[68:71], v[228:231], v[220:223], v[68:71]
	v_mfma_f32_16x16x32_bf16 v[64:67], v[236:239], v[220:223], v[64:67]
	s_mov_b32 m0, s53
	v_lshl_add_u64 v[156:157], v[164:165], 0, s[6:7]
	s_barrier
	ds_read_b128 v[186:189], v171 offset:49152
	ds_read_b128 v[196:199], v171 offset:50176
	ds_read_b128 v[200:203], v171 offset:51200
	ds_read_b128 v[204:207], v171 offset:52224
	ds_read_b128 v[208:211], v171 offset:53248
	ds_read_b128 v[212:215], v171 offset:54272
	ds_read_b128 v[216:219], v171 offset:55296
	ds_read_b128 v[220:223], v171 offset:56320
	global_load_lds_dwordx4 v[156:157], off
	v_lshl_add_u64 v[156:157], v[168:169], 0, s[6:7]
	s_mov_b32 m0, s54
	s_nop 0
	global_load_lds_dwordx4 v[156:157], off
	s_barrier
	s_waitcnt lgkmcnt(0)
	v_mfma_f32_16x16x32_bf16 v[60:63], v[146:149], v[186:189], v[60:63]
	v_mfma_f32_16x16x32_bf16 v[56:59], v[178:181], v[186:189], v[56:59]
	v_mfma_f32_16x16x32_bf16 v[44:47], v[146:149], v[200:203], v[44:47]
	v_mfma_f32_16x16x32_bf16 v[40:43], v[178:181], v[200:203], v[40:43]
	v_mfma_f32_16x16x32_bf16 v[28:31], v[146:149], v[208:211], v[28:31]
	v_mfma_f32_16x16x32_bf16 v[24:27], v[178:181], v[208:211], v[24:27]
	v_mfma_f32_16x16x32_bf16 v[12:15], v[146:149], v[216:219], v[12:15]
	v_mfma_f32_16x16x32_bf16 v[8:11], v[178:181], v[216:219], v[8:11]
	v_mfma_f32_16x16x32_bf16 v[60:63], v[150:153], v[196:199], v[60:63]
	v_mfma_f32_16x16x32_bf16 v[56:59], v[182:185], v[196:199], v[56:59]
	v_mfma_f32_16x16x32_bf16 v[44:47], v[150:153], v[204:207], v[44:47]
	v_mfma_f32_16x16x32_bf16 v[40:43], v[182:185], v[204:207], v[40:43]
	v_mfma_f32_16x16x32_bf16 v[28:31], v[150:153], v[212:215], v[28:31]
	v_mfma_f32_16x16x32_bf16 v[24:27], v[182:185], v[212:215], v[24:27]
	v_mfma_f32_16x16x32_bf16 v[12:15], v[150:153], v[220:223], v[12:15]
	v_mfma_f32_16x16x32_bf16 v[8:11], v[182:185], v[220:223], v[8:11]
	s_barrier
	s_add_u32 s42, s42, 0x40080
	s_addc_u32 s43, s43, 0
	s_add_i32 s28, s29, s11
	v_lshl_add_u64 v[146:147], s[42:43], 0, v[132:133]
	s_mov_b32 m0, s28
	s_nop 0
	global_load_lds_dwordx4 v[146:147], off
	v_lshl_add_u64 v[146:147], s[42:43], 0, v[128:129]
	s_add_i32 m0, s28, 0x2000
	s_nop 0
	global_load_lds_dwordx4 v[146:147], off
	s_waitcnt vmcnt(6)
	s_barrier
	v_mfma_f32_16x16x32_bf16 v[52:55], v[224:227], v[186:189], v[52:55]
	v_mfma_f32_16x16x32_bf16 v[48:51], v[232:235], v[186:189], v[48:51]
	v_mfma_f32_16x16x32_bf16 v[36:39], v[224:227], v[200:203], v[36:39]
	v_mfma_f32_16x16x32_bf16 v[32:35], v[232:235], v[200:203], v[32:35]
	v_mfma_f32_16x16x32_bf16 v[20:23], v[224:227], v[208:211], v[20:23]
	v_mfma_f32_16x16x32_bf16 v[16:19], v[232:235], v[208:211], v[16:19]
	v_mfma_f32_16x16x32_bf16 v[4:7], v[224:227], v[216:219], v[4:7]
	v_mfma_f32_16x16x32_bf16 v[0:3], v[232:235], v[216:219], v[0:3]
	v_mfma_f32_16x16x32_bf16 v[52:55], v[228:231], v[196:199], v[52:55]
	v_mfma_f32_16x16x32_bf16 v[48:51], v[236:239], v[196:199], v[48:51]
	v_mfma_f32_16x16x32_bf16 v[36:39], v[228:231], v[204:207], v[36:39]
	v_mfma_f32_16x16x32_bf16 v[32:35], v[236:239], v[204:207], v[32:35]
	v_mfma_f32_16x16x32_bf16 v[20:23], v[228:231], v[212:215], v[20:23]
	v_mfma_f32_16x16x32_bf16 v[16:19], v[236:239], v[212:215], v[16:19]
	v_mfma_f32_16x16x32_bf16 v[4:7], v[228:231], v[220:223], v[4:7]
	v_mfma_f32_16x16x32_bf16 v[0:3], v[236:239], v[220:223], v[0:3]
	s_add_i32 s64, s64, 2
	s_add_u32 s0, s0, 0x100
	s_addc_u32 s1, s1, 0
	s_add_u32 s62, s62, 0x100
	s_addc_u32 s63, s63, 0
	s_cmp_gt_u32 s64, 13
	s_barrier
	s_cbranch_scc0 .LBB0_1093
.LBB0_1093:
	ds_read_b128 v[146:149], v167
	ds_read_b128 v[150:153], v167 offset:1024
	ds_read_b128 v[178:181], v167 offset:2048
	ds_read_b128 v[182:185], v167 offset:3072
	ds_read_b128 v[186:189], v171
	ds_read_b128 v[196:199], v171 offset:1024
	ds_read_b128 v[200:203], v171 offset:2048
	ds_read_b128 v[204:207], v171 offset:3072
	ds_read_b128 v[208:211], v171 offset:4096
	ds_read_b128 v[212:215], v171 offset:5120
	ds_read_b128 v[216:219], v171 offset:6144
	ds_read_b128 v[220:223], v171 offset:7168
	s_add_u32 s28, s0, 0xfffc0080
	s_addc_u32 s29, s1, -1
	s_cmp_eq_u32 s64, 12
	s_cselect_b32 s45, s37, s29
	s_cselect_b32 s44, s60, s28
	s_cselect_b32 s43, s13, s63
	s_cselect_b32 s42, s61, s62
	v_lshl_add_u64 v[156:157], s[0:1], 0, v[138:139]
	s_add_i32 m0, s47, 0xc000
	global_load_lds_dwordx4 v[156:157], off
	v_lshl_add_u64 v[156:157], s[0:1], 0, v[140:141]
	s_add_i32 m0, s47, 0xe000
	s_nop 0
	global_load_lds_dwordx4 v[156:157], off
	s_waitcnt lgkmcnt(8)
	s_barrier
	s_waitcnt lgkmcnt(0)
	v_mfma_f32_16x16x32_bf16 v[124:127], v[146:149], v[186:189], v[124:127]
	v_mfma_f32_16x16x32_bf16 v[120:123], v[178:181], v[186:189], v[120:123]
	v_mfma_f32_16x16x32_bf16 v[108:111], v[146:149], v[200:203], v[108:111]
	v_mfma_f32_16x16x32_bf16 v[104:107], v[178:181], v[200:203], v[104:107]
	v_mfma_f32_16x16x32_bf16 v[92:95], v[146:149], v[208:211], v[92:95]
	v_mfma_f32_16x16x32_bf16 v[88:91], v[178:181], v[208:211], v[88:91]
	v_mfma_f32_16x16x32_bf16 v[76:79], v[146:149], v[216:219], v[76:79]
	v_mfma_f32_16x16x32_bf16 v[72:75], v[178:181], v[216:219], v[72:75]
	v_mfma_f32_16x16x32_bf16 v[124:127], v[150:153], v[196:199], v[124:127]
	v_mfma_f32_16x16x32_bf16 v[120:123], v[182:185], v[196:199], v[120:123]
	v_mfma_f32_16x16x32_bf16 v[108:111], v[150:153], v[204:207], v[108:111]
	v_mfma_f32_16x16x32_bf16 v[104:107], v[182:185], v[204:207], v[104:107]
	v_mfma_f32_16x16x32_bf16 v[92:95], v[150:153], v[212:215], v[92:95]
	v_mfma_f32_16x16x32_bf16 v[88:91], v[182:185], v[212:215], v[88:91]
	v_mfma_f32_16x16x32_bf16 v[76:79], v[150:153], v[220:223], v[76:79]
	v_mfma_f32_16x16x32_bf16 v[72:75], v[182:185], v[220:223], v[72:75]
	s_barrier
	s_add_i32 s28, s56, s11
	v_lshl_add_u64 v[156:157], s[42:43], 0, v[132:133]
	s_mov_b32 m0, s28
	ds_read_b128 v[224:227], v175
	ds_read_b128 v[228:231], v175 offset:1024
	ds_read_b128 v[232:235], v175 offset:2048
	ds_read_b128 v[236:239], v175 offset:3072
	global_load_lds_dwordx4 v[156:157], off
	v_lshl_add_u64 v[160:161], s[42:43], 0, v[128:129]
	s_add_i32 m0, s28, 0x2000
	s_nop 0
	global_load_lds_dwordx4 v[160:161], off
	s_barrier
	s_waitcnt lgkmcnt(0)
	v_mfma_f32_16x16x32_bf16 v[116:119], v[224:227], v[186:189], v[116:119]
	v_mfma_f32_16x16x32_bf16 v[112:115], v[232:235], v[186:189], v[112:115]
	v_mfma_f32_16x16x32_bf16 v[100:103], v[224:227], v[200:203], v[100:103]
	v_mfma_f32_16x16x32_bf16 v[96:99], v[232:235], v[200:203], v[96:99]
	v_mfma_f32_16x16x32_bf16 v[84:87], v[224:227], v[208:211], v[84:87]
	v_mfma_f32_16x16x32_bf16 v[80:83], v[232:235], v[208:211], v[80:83]
	v_mfma_f32_16x16x32_bf16 v[68:71], v[224:227], v[216:219], v[68:71]
	v_mfma_f32_16x16x32_bf16 v[64:67], v[232:235], v[216:219], v[64:67]
	v_mfma_f32_16x16x32_bf16 v[116:119], v[228:231], v[196:199], v[116:119]
	v_mfma_f32_16x16x32_bf16 v[112:115], v[236:239], v[196:199], v[112:115]
	v_mfma_f32_16x16x32_bf16 v[100:103], v[228:231], v[204:207], v[100:103]
	v_mfma_f32_16x16x32_bf16 v[96:99], v[236:239], v[204:207], v[96:99]
	v_mfma_f32_16x16x32_bf16 v[84:87], v[228:231], v[212:215], v[84:87]
	v_mfma_f32_16x16x32_bf16 v[80:83], v[236:239], v[212:215], v[80:83]
	v_mfma_f32_16x16x32_bf16 v[68:71], v[228:231], v[220:223], v[68:71]
	v_mfma_f32_16x16x32_bf16 v[64:67], v[236:239], v[220:223], v[64:67]
	s_mov_b32 m0, s47
	v_lshl_add_u64 v[164:165], s[44:45], 0, v[134:135]
	s_barrier
	ds_read_b128 v[186:189], v171 offset:16384
	ds_read_b128 v[196:199], v171 offset:17408
	ds_read_b128 v[200:203], v171 offset:18432
	ds_read_b128 v[204:207], v171 offset:19456
	ds_read_b128 v[208:211], v171 offset:20480
	ds_read_b128 v[212:215], v171 offset:21504
	ds_read_b128 v[216:219], v171 offset:22528
	ds_read_b128 v[220:223], v171 offset:23552
	global_load_lds_dwordx4 v[164:165], off
	v_lshl_add_u64 v[168:169], s[44:45], 0, v[130:131]
	s_mov_b32 m0, s48
	s_nop 0
	global_load_lds_dwordx4 v[168:169], off
	s_barrier
	s_waitcnt lgkmcnt(0)
	v_mfma_f32_16x16x32_bf16 v[60:63], v[146:149], v[186:189], v[60:63]
	v_mfma_f32_16x16x32_bf16 v[56:59], v[178:181], v[186:189], v[56:59]
	v_mfma_f32_16x16x32_bf16 v[44:47], v[146:149], v[200:203], v[44:47]
	v_mfma_f32_16x16x32_bf16 v[40:43], v[178:181], v[200:203], v[40:43]
	v_mfma_f32_16x16x32_bf16 v[28:31], v[146:149], v[208:211], v[28:31]
	v_mfma_f32_16x16x32_bf16 v[24:27], v[178:181], v[208:211], v[24:27]
	v_mfma_f32_16x16x32_bf16 v[12:15], v[146:149], v[216:219], v[12:15]
	v_mfma_f32_16x16x32_bf16 v[8:11], v[178:181], v[216:219], v[8:11]
	v_mfma_f32_16x16x32_bf16 v[60:63], v[150:153], v[196:199], v[60:63]
	v_mfma_f32_16x16x32_bf16 v[56:59], v[182:185], v[196:199], v[56:59]
	v_mfma_f32_16x16x32_bf16 v[44:47], v[150:153], v[204:207], v[44:47]
	v_mfma_f32_16x16x32_bf16 v[40:43], v[182:185], v[204:207], v[40:43]
	v_mfma_f32_16x16x32_bf16 v[28:31], v[150:153], v[212:215], v[28:31]
	v_mfma_f32_16x16x32_bf16 v[24:27], v[182:185], v[212:215], v[24:27]
	v_mfma_f32_16x16x32_bf16 v[12:15], v[150:153], v[220:223], v[12:15]
	v_mfma_f32_16x16x32_bf16 v[8:11], v[182:185], v[220:223], v[8:11]
	s_barrier
	s_add_u32 s66, s42, 0x40000
	s_addc_u32 s67, s43, 0
	s_add_i32 s28, s57, s11
	v_lshl_add_u64 v[146:147], s[66:67], 0, v[132:133]
	s_mov_b32 m0, s28
	s_nop 0
	global_load_lds_dwordx4 v[146:147], off
	v_lshl_add_u64 v[146:147], s[66:67], 0, v[128:129]
	s_add_i32 m0, s28, 0x2000
	s_nop 0
	global_load_lds_dwordx4 v[146:147], off
	s_waitcnt vmcnt(6)
	s_barrier
	v_mfma_f32_16x16x32_bf16 v[52:55], v[224:227], v[186:189], v[52:55]
	v_mfma_f32_16x16x32_bf16 v[48:51], v[232:235], v[186:189], v[48:51]
	v_mfma_f32_16x16x32_bf16 v[36:39], v[224:227], v[200:203], v[36:39]
	v_mfma_f32_16x16x32_bf16 v[32:35], v[232:235], v[200:203], v[32:35]
	v_mfma_f32_16x16x32_bf16 v[20:23], v[224:227], v[208:211], v[20:23]
	v_mfma_f32_16x16x32_bf16 v[16:19], v[232:235], v[208:211], v[16:19]
	v_mfma_f32_16x16x32_bf16 v[4:7], v[224:227], v[216:219], v[4:7]
	v_mfma_f32_16x16x32_bf16 v[0:3], v[232:235], v[216:219], v[0:3]
	v_mfma_f32_16x16x32_bf16 v[52:55], v[228:231], v[196:199], v[52:55]
	v_mfma_f32_16x16x32_bf16 v[48:51], v[236:239], v[196:199], v[48:51]
	v_mfma_f32_16x16x32_bf16 v[36:39], v[228:231], v[204:207], v[36:39]
	v_mfma_f32_16x16x32_bf16 v[32:35], v[236:239], v[204:207], v[32:35]
	v_mfma_f32_16x16x32_bf16 v[20:23], v[228:231], v[212:215], v[20:23]
	v_mfma_f32_16x16x32_bf16 v[16:19], v[236:239], v[212:215], v[16:19]
	v_mfma_f32_16x16x32_bf16 v[4:7], v[228:231], v[220:223], v[4:7]
	v_mfma_f32_16x16x32_bf16 v[0:3], v[236:239], v[220:223], v[0:3]
	s_add_i32 s28, 0, 0x18000
	v_add_u32_e32 v154, s28, v159
	s_barrier
	ds_read_b128 v[146:149], v154
	ds_read_b128 v[150:153], v154 offset:1024
	ds_read_b128 v[178:181], v154 offset:2048
	ds_read_b128 v[182:185], v154 offset:3072
	ds_read_b128 v[186:189], v171 offset:32768
	ds_read_b128 v[196:199], v171 offset:33792
	ds_read_b128 v[200:203], v171 offset:34816
	ds_read_b128 v[204:207], v171 offset:35840
	ds_read_b128 v[208:211], v171 offset:36864
	ds_read_b128 v[212:215], v171 offset:37888
	ds_read_b128 v[216:219], v171 offset:38912
	ds_read_b128 v[220:223], v171 offset:39936
	s_add_u32 s44, s44, 0x40000
	s_addc_u32 s45, s45, 0
	s_mov_b32 m0, s49
	v_lshl_add_u64 v[172:173], s[44:45], 0, v[134:135]
	global_load_lds_dwordx4 v[172:173], off
	v_lshl_add_u64 v[172:173], s[44:45], 0, v[130:131]
	s_mov_b32 m0, s50
	s_nop 0
	global_load_lds_dwordx4 v[172:173], off
	s_waitcnt lgkmcnt(8)
	s_barrier
	s_waitcnt lgkmcnt(0)
	v_mfma_f32_16x16x32_bf16 v[124:127], v[146:149], v[186:189], v[124:127]
	v_mfma_f32_16x16x32_bf16 v[120:123], v[178:181], v[186:189], v[120:123]
	v_mfma_f32_16x16x32_bf16 v[108:111], v[146:149], v[200:203], v[108:111]
	v_mfma_f32_16x16x32_bf16 v[104:107], v[178:181], v[200:203], v[104:107]
	v_mfma_f32_16x16x32_bf16 v[92:95], v[146:149], v[208:211], v[92:95]
	v_mfma_f32_16x16x32_bf16 v[88:91], v[178:181], v[208:211], v[88:91]
	v_mfma_f32_16x16x32_bf16 v[76:79], v[146:149], v[216:219], v[76:79]
	v_mfma_f32_16x16x32_bf16 v[72:75], v[178:181], v[216:219], v[72:75]
	v_mfma_f32_16x16x32_bf16 v[124:127], v[150:153], v[196:199], v[124:127]
	v_mfma_f32_16x16x32_bf16 v[120:123], v[182:185], v[196:199], v[120:123]
	v_mfma_f32_16x16x32_bf16 v[108:111], v[150:153], v[204:207], v[108:111]
	v_mfma_f32_16x16x32_bf16 v[104:107], v[182:185], v[204:207], v[104:107]
	v_mfma_f32_16x16x32_bf16 v[92:95], v[150:153], v[212:215], v[92:95]
	v_mfma_f32_16x16x32_bf16 v[88:91], v[182:185], v[212:215], v[88:91]
	v_mfma_f32_16x16x32_bf16 v[76:79], v[150:153], v[220:223], v[76:79]
	v_mfma_f32_16x16x32_bf16 v[72:75], v[182:185], v[220:223], v[72:75]
	s_barrier
	s_add_i32 s29, 0, 0x1c000
	s_add_i32 s28, s28, s11
	v_add_u32_e32 v154, s29, v159
	v_lshl_add_u64 v[156:157], v[156:157], 0, s[6:7]
	s_mov_b32 m0, s28
	ds_read_b128 v[224:227], v154
	ds_read_b128 v[228:231], v154 offset:1024
	ds_read_b128 v[232:235], v154 offset:2048
	ds_read_b128 v[236:239], v154 offset:3072
	global_load_lds_dwordx4 v[156:157], off
	v_lshl_add_u64 v[156:157], v[160:161], 0, s[6:7]
	s_add_i32 m0, s28, 0x2000
	s_nop 0
	global_load_lds_dwordx4 v[156:157], off
	s_barrier
	s_waitcnt lgkmcnt(0)
	v_mfma_f32_16x16x32_bf16 v[116:119], v[224:227], v[186:189], v[116:119]
	v_mfma_f32_16x16x32_bf16 v[112:115], v[232:235], v[186:189], v[112:115]
	v_mfma_f32_16x16x32_bf16 v[100:103], v[224:227], v[200:203], v[100:103]
	v_mfma_f32_16x16x32_bf16 v[96:99], v[232:235], v[200:203], v[96:99]
	v_mfma_f32_16x16x32_bf16 v[84:87], v[224:227], v[208:211], v[84:87]
	v_mfma_f32_16x16x32_bf16 v[80:83], v[232:235], v[208:211], v[80:83]
	v_mfma_f32_16x16x32_bf16 v[68:71], v[224:227], v[216:219], v[68:71]
	v_mfma_f32_16x16x32_bf16 v[64:67], v[232:235], v[216:219], v[64:67]
	v_mfma_f32_16x16x32_bf16 v[116:119], v[228:231], v[196:199], v[116:119]
	v_mfma_f32_16x16x32_bf16 v[112:115], v[236:239], v[196:199], v[112:115]
	v_mfma_f32_16x16x32_bf16 v[100:103], v[228:231], v[204:207], v[100:103]
	v_mfma_f32_16x16x32_bf16 v[96:99], v[236:239], v[204:207], v[96:99]
	v_mfma_f32_16x16x32_bf16 v[84:87], v[228:231], v[212:215], v[84:87]
	v_mfma_f32_16x16x32_bf16 v[80:83], v[236:239], v[212:215], v[80:83]
	v_mfma_f32_16x16x32_bf16 v[68:71], v[228:231], v[220:223], v[68:71]
	v_mfma_f32_16x16x32_bf16 v[64:67], v[236:239], v[220:223], v[64:67]
	s_mov_b32 m0, s53
	v_lshl_add_u64 v[156:157], v[164:165], 0, s[6:7]
	s_barrier
	ds_read_b128 v[186:189], v171 offset:49152
	ds_read_b128 v[196:199], v171 offset:50176
	ds_read_b128 v[200:203], v171 offset:51200
	ds_read_b128 v[204:207], v171 offset:52224
	ds_read_b128 v[208:211], v171 offset:53248
	ds_read_b128 v[212:215], v171 offset:54272
	ds_read_b128 v[216:219], v171 offset:55296
	ds_read_b128 v[220:223], v171 offset:56320
	global_load_lds_dwordx4 v[156:157], off
	v_lshl_add_u64 v[156:157], v[168:169], 0, s[6:7]
	s_mov_b32 m0, s54
	s_nop 0
	global_load_lds_dwordx4 v[156:157], off
	s_barrier
	s_waitcnt lgkmcnt(0)
	v_mfma_f32_16x16x32_bf16 v[60:63], v[146:149], v[186:189], v[60:63]
	v_mfma_f32_16x16x32_bf16 v[56:59], v[178:181], v[186:189], v[56:59]
	v_mfma_f32_16x16x32_bf16 v[44:47], v[146:149], v[200:203], v[44:47]
	v_mfma_f32_16x16x32_bf16 v[40:43], v[178:181], v[200:203], v[40:43]
	v_mfma_f32_16x16x32_bf16 v[28:31], v[146:149], v[208:211], v[28:31]
	v_mfma_f32_16x16x32_bf16 v[24:27], v[178:181], v[208:211], v[24:27]
	v_mfma_f32_16x16x32_bf16 v[12:15], v[146:149], v[216:219], v[12:15]
	v_mfma_f32_16x16x32_bf16 v[8:11], v[178:181], v[216:219], v[8:11]
	v_mfma_f32_16x16x32_bf16 v[60:63], v[150:153], v[196:199], v[60:63]
	v_mfma_f32_16x16x32_bf16 v[56:59], v[182:185], v[196:199], v[56:59]
	v_mfma_f32_16x16x32_bf16 v[44:47], v[150:153], v[204:207], v[44:47]
	v_mfma_f32_16x16x32_bf16 v[40:43], v[182:185], v[204:207], v[40:43]
	v_mfma_f32_16x16x32_bf16 v[28:31], v[150:153], v[212:215], v[28:31]
	v_mfma_f32_16x16x32_bf16 v[24:27], v[182:185], v[212:215], v[24:27]
	v_mfma_f32_16x16x32_bf16 v[12:15], v[150:153], v[220:223], v[12:15]
	v_mfma_f32_16x16x32_bf16 v[8:11], v[182:185], v[220:223], v[8:11]
	s_barrier
	s_add_u32 s42, s42, 0x40080
	s_addc_u32 s43, s43, 0
	s_add_i32 s28, s29, s11
	v_lshl_add_u64 v[146:147], s[42:43], 0, v[132:133]
	s_mov_b32 m0, s28
	s_nop 0
	global_load_lds_dwordx4 v[146:147], off
	v_lshl_add_u64 v[146:147], s[42:43], 0, v[128:129]
	s_add_i32 m0, s28, 0x2000
	s_nop 0
	global_load_lds_dwordx4 v[146:147], off
	s_waitcnt vmcnt(6)
	s_barrier
	v_mfma_f32_16x16x32_bf16 v[52:55], v[224:227], v[186:189], v[52:55]
	v_mfma_f32_16x16x32_bf16 v[48:51], v[232:235], v[186:189], v[48:51]
	v_mfma_f32_16x16x32_bf16 v[36:39], v[224:227], v[200:203], v[36:39]
	v_mfma_f32_16x16x32_bf16 v[32:35], v[232:235], v[200:203], v[32:35]
	v_mfma_f32_16x16x32_bf16 v[20:23], v[224:227], v[208:211], v[20:23]
	v_mfma_f32_16x16x32_bf16 v[16:19], v[232:235], v[208:211], v[16:19]
	v_mfma_f32_16x16x32_bf16 v[4:7], v[224:227], v[216:219], v[4:7]
	v_mfma_f32_16x16x32_bf16 v[0:3], v[232:235], v[216:219], v[0:3]
	v_mfma_f32_16x16x32_bf16 v[52:55], v[228:231], v[196:199], v[52:55]
	v_mfma_f32_16x16x32_bf16 v[48:51], v[236:239], v[196:199], v[48:51]
	v_mfma_f32_16x16x32_bf16 v[36:39], v[228:231], v[204:207], v[36:39]
	v_mfma_f32_16x16x32_bf16 v[32:35], v[236:239], v[204:207], v[32:35]
	v_mfma_f32_16x16x32_bf16 v[20:23], v[228:231], v[212:215], v[20:23]
	v_mfma_f32_16x16x32_bf16 v[16:19], v[236:239], v[212:215], v[16:19]
	v_mfma_f32_16x16x32_bf16 v[4:7], v[228:231], v[220:223], v[4:7]
	v_mfma_f32_16x16x32_bf16 v[0:3], v[236:239], v[220:223], v[0:3]
	s_add_i32 s64, s64, 2
	s_add_u32 s0, s0, 0x100
	s_addc_u32 s1, s1, 0
	s_add_u32 s62, s62, 0x100
	s_addc_u32 s63, s63, 0
	s_cmp_gt_u32 s64, 13
	s_barrier
	s_cbranch_scc0 .LBB0_1093
	v_lshl_add_u32 v168, s4, 8, v155
	v_or_b32_e32 v164, 16, v168
	v_or_b32_e32 v160, 32, v168
	v_or_b32_e32 v156, 48, v168
	v_add_u32_e32 v152, 0x80, v168
	v_add_u32_e32 v150, 0x90, v168
	v_add_u32_e32 v148, 0xa0, v168
	v_add_u32_e32 v146, 0xb0, v168
	v_lshl_or_b32 v172, s5, 7, v163
	v_mov_b32_e32 v178, v240
	v_mov_b32_e32 v179, v240
	v_mov_b32_e32 v154, v241
	s_and_b32 s0, s36, 0x7f
	v_lshl_add_u32 v228, s0, 8, v155
	v_mov_b32_e32 v229, 0
	v_lshlrev_b32_e32 v228, 6, v228
	v_lshl_add_u64 v[230:231], v[136:137], 0, v[228:229]
	v_mov_b32_e32 v228, 0x2000
	v_lshl_add_u64 v[232:233], v[230:231], 0, v[228:229]
	global_load_dwordx4 v[216:219], v[230:231], off
	global_load_dwordx4 v[220:223], v[230:231], off offset:1024
	global_load_dwordx4 v[224:227], v[230:231], off offset:2048
	global_load_dwordx4 v[196:199], v[230:231], off offset:3072
	global_load_dwordx4 v[200:203], v[232:233], off
	global_load_dwordx4 v[204:207], v[232:233], off offset:1024
	global_load_dwordx4 v[208:211], v[232:233], off offset:2048
	global_load_dwordx4 v[212:215], v[232:233], off offset:3072
	v_pk_mul_f32 v[124:125], v[124:125], v[178:179] op_sel_hi:[1,0]
	v_pk_mul_f32 v[126:127], v[126:127], v[178:179] op_sel_hi:[1,0]
	v_mul_f32_e32 v147, 0xbfb8aa3b, v124
	v_exp_f32_e32 v147, v147
	v_mul_f32_e32 v149, 0xbfb8aa3b, v125
	v_exp_f32_e32 v149, v149
	v_mul_f32_e32 v151, 0xbfb8aa3b, v127
	v_add_f32_e32 v147, 1.0, v147
	v_rcp_f32_e32 v180, v147
	v_add_f32_e32 v147, 1.0, v149
	v_mul_f32_e32 v149, 0xbfb8aa3b, v126
	v_exp_f32_e32 v149, v149
	v_exp_f32_e32 v151, v151
	v_rcp_f32_e32 v181, v147
	v_pk_mul_f32 v[116:117], v[116:117], v[178:179] op_sel_hi:[1,0]
	v_add_f32_e32 v147, 1.0, v149
	v_rcp_f32_e32 v182, v147
	v_add_f32_e32 v147, 1.0, v151
	v_rcp_f32_e32 v183, v147
	v_pk_mul_f32 v[124:125], v[124:125], v[180:181]
	v_pk_mul_f32 v[120:121], v[120:121], v[178:179] op_sel_hi:[1,0]
	v_pk_mul_f32 v[116:117], v[116:117], v[124:125]
	v_pk_mul_f32 v[124:125], v[126:127], v[182:183]
	v_mul_f32_e32 v126, 0xbfb8aa3b, v120
	v_exp_f32_e32 v126, v126
	v_pk_mul_f32 v[118:119], v[118:119], v[178:179] op_sel_hi:[1,0]
	v_pk_mul_f32 v[122:123], v[122:123], v[178:179] op_sel_hi:[1,0]
	v_pk_mul_f32 v[118:119], v[118:119], v[124:125]
	v_mul_f32_e32 v124, 0xbfb8aa3b, v121
	v_exp_f32_e32 v125, v124
	v_add_f32_e32 v124, 1.0, v126
	v_mul_f32_e32 v126, 0xbfb8aa3b, v122
	v_mul_f32_e32 v127, 0xbfb8aa3b, v123
	v_exp_f32_e32 v126, v126
	v_exp_f32_e32 v127, v127
	v_add_f32_e32 v125, 1.0, v125
	v_rcp_f32_e32 v124, v124
	v_rcp_f32_e32 v125, v125
	v_add_f32_e32 v126, 1.0, v126
	v_add_f32_e32 v127, 1.0, v127
	v_rcp_f32_e32 v126, v126
	v_rcp_f32_e32 v127, v127
	v_pk_mul_f32 v[112:113], v[112:113], v[178:179] op_sel_hi:[1,0]
	v_pk_mul_f32 v[120:121], v[120:121], v[124:125]
	v_pk_mul_f32 v[114:115], v[114:115], v[178:179] op_sel_hi:[1,0]
	v_pk_mul_f32 v[112:113], v[112:113], v[120:121]
	v_pk_mul_f32 v[120:121], v[122:123], v[126:127]
	v_ashrrev_i32_e32 v173, 31, v172
	v_pk_mul_f32 v[114:115], v[114:115], v[120:121]
	v_cvt_pk_bf16_f32 v116, v116, v117
	v_cvt_pk_bf16_f32 v117, v118, v119
	v_cvt_pk_bf16_f32 v118, v112, v113
	v_mov_b64_e32 v[112:113], s[20:21]
	v_cvt_pk_bf16_f32 v119, v114, v115
	v_mad_i64_i32 v[120:121], s[0:1], v168, s59, v[112:113]
	v_lshlrev_b64 v[114:115], 1, v[172:173]
	v_lshl_add_u64 v[120:121], v[120:121], 0, v[114:115]
	v_pk_mul_f32 v[108:109], v[108:109], v[176:177] op_sel_hi:[1,0]
	global_store_dwordx4 v[120:121], v[116:119], off
	v_mul_f32_e32 v122, 0xbfb8aa3b, v108
	v_pk_mul_f32 v[110:111], v[110:111], v[176:177] op_sel_hi:[1,0]
	v_mul_f32_e32 v116, 0xbfb8aa3b, v109
	v_exp_f32_e32 v122, v122
	v_exp_f32_e32 v117, v116
	v_mul_f32_e32 v118, 0xbfb8aa3b, v110
	v_mul_f32_e32 v119, 0xbfb8aa3b, v111
	v_exp_f32_e32 v118, v118
	v_exp_f32_e32 v119, v119
	v_add_f32_e32 v116, 1.0, v122
	v_add_f32_e32 v117, 1.0, v117
	v_rcp_f32_e32 v116, v116
	v_rcp_f32_e32 v117, v117
	v_add_f32_e32 v118, 1.0, v118
	v_add_f32_e32 v119, 1.0, v119
	v_rcp_f32_e32 v118, v118
	v_rcp_f32_e32 v119, v119
	v_pk_mul_f32 v[100:101], v[100:101], v[176:177] op_sel_hi:[1,0]
	v_pk_mul_f32 v[108:109], v[108:109], v[116:117]
	v_pk_mul_f32 v[104:105], v[104:105], v[176:177] op_sel_hi:[1,0]
	v_pk_mul_f32 v[100:101], v[100:101], v[108:109]
	v_pk_mul_f32 v[108:109], v[110:111], v[118:119]
	v_mul_f32_e32 v110, 0xbfb8aa3b, v104
	v_exp_f32_e32 v110, v110
	v_pk_mul_f32 v[102:103], v[102:103], v[176:177] op_sel_hi:[1,0]
	v_pk_mul_f32 v[106:107], v[106:107], v[176:177] op_sel_hi:[1,0]
	v_pk_mul_f32 v[102:103], v[102:103], v[108:109]
	v_mul_f32_e32 v108, 0xbfb8aa3b, v105
	v_exp_f32_e32 v109, v108
	v_add_f32_e32 v108, 1.0, v110
	v_mul_f32_e32 v110, 0xbfb8aa3b, v106
	v_mul_f32_e32 v111, 0xbfb8aa3b, v107
	v_exp_f32_e32 v110, v110
	v_exp_f32_e32 v111, v111
	v_add_f32_e32 v109, 1.0, v109
	v_rcp_f32_e32 v108, v108
	v_rcp_f32_e32 v109, v109
	v_add_f32_e32 v110, 1.0, v110
	v_add_f32_e32 v111, 1.0, v111
	v_rcp_f32_e32 v110, v110
	v_rcp_f32_e32 v111, v111
	v_pk_mul_f32 v[96:97], v[96:97], v[176:177] op_sel_hi:[1,0]
	v_pk_mul_f32 v[104:105], v[104:105], v[108:109]
	v_pk_mul_f32 v[92:93], v[92:93], v[174:175] op_sel_hi:[1,0]
	v_pk_mul_f32 v[104:105], v[96:97], v[104:105]
	v_pk_mul_f32 v[96:97], v[98:99], v[176:177] op_sel_hi:[1,0]
	v_pk_mul_f32 v[98:99], v[106:107], v[110:111]
	v_pk_mul_f32 v[94:95], v[94:95], v[174:175] op_sel_hi:[1,0]
	v_pk_mul_f32 v[106:107], v[96:97], v[98:99]
	v_cvt_pk_bf16_f32 v96, v100, v101
	v_mad_i64_i32 v[100:101], s[0:1], v164, s59, v[112:113]
	v_cvt_pk_bf16_f32 v97, v102, v103
	v_cvt_pk_bf16_f32 v98, v104, v105
	v_cvt_pk_bf16_f32 v99, v106, v107
	v_lshl_add_u64 v[100:101], v[100:101], 0, v[114:115]
	v_mul_f32_e32 v102, 0xbfb8aa3b, v92
	global_store_dwordx4 v[100:101], v[96:99], off
	v_exp_f32_e32 v102, v102
	v_pk_mul_f32 v[84:85], v[84:85], v[174:175] op_sel_hi:[1,0]
	v_mul_f32_e32 v96, 0xbfb8aa3b, v93
	v_exp_f32_e32 v97, v96
	v_mul_f32_e32 v98, 0xbfb8aa3b, v94
	v_mul_f32_e32 v99, 0xbfb8aa3b, v95
	v_exp_f32_e32 v98, v98
	v_exp_f32_e32 v99, v99
	v_add_f32_e32 v96, 1.0, v102
	v_add_f32_e32 v97, 1.0, v97
	v_rcp_f32_e32 v96, v96
	v_rcp_f32_e32 v97, v97
	v_add_f32_e32 v98, 1.0, v98
	v_add_f32_e32 v99, 1.0, v99
	v_rcp_f32_e32 v98, v98
	v_rcp_f32_e32 v99, v99
	v_pk_mul_f32 v[92:93], v[92:93], v[96:97]
	v_pk_mul_f32 v[88:89], v[88:89], v[174:175] op_sel_hi:[1,0]
	v_pk_mul_f32 v[84:85], v[84:85], v[92:93]
	v_pk_mul_f32 v[92:93], v[94:95], v[98:99]
	v_mul_f32_e32 v94, 0xbfb8aa3b, v88
	v_exp_f32_e32 v94, v94
	v_pk_mul_f32 v[86:87], v[86:87], v[174:175] op_sel_hi:[1,0]
	v_pk_mul_f32 v[90:91], v[90:91], v[174:175] op_sel_hi:[1,0]
	v_pk_mul_f32 v[86:87], v[86:87], v[92:93]
	v_mul_f32_e32 v92, 0xbfb8aa3b, v89
	v_exp_f32_e32 v93, v92
	v_add_f32_e32 v92, 1.0, v94
	v_mul_f32_e32 v94, 0xbfb8aa3b, v90
	v_mul_f32_e32 v95, 0xbfb8aa3b, v91
	v_exp_f32_e32 v94, v94
	v_exp_f32_e32 v95, v95
	v_add_f32_e32 v93, 1.0, v93
	v_rcp_f32_e32 v92, v92
	v_rcp_f32_e32 v93, v93
	v_add_f32_e32 v94, 1.0, v94
	v_add_f32_e32 v95, 1.0, v95
	v_rcp_f32_e32 v94, v94
	v_rcp_f32_e32 v95, v95
	v_pk_mul_f32 v[80:81], v[80:81], v[174:175] op_sel_hi:[1,0]
	v_pk_mul_f32 v[88:89], v[88:89], v[92:93]
	v_pk_mul_f32 v[76:77], v[76:77], v[170:171] op_sel_hi:[1,0]
	v_pk_mul_f32 v[88:89], v[80:81], v[88:89]
	v_pk_mul_f32 v[80:81], v[82:83], v[174:175] op_sel_hi:[1,0]
	v_pk_mul_f32 v[82:83], v[90:91], v[94:95]
	v_pk_mul_f32 v[78:79], v[78:79], v[170:171] op_sel_hi:[1,0]
	v_pk_mul_f32 v[90:91], v[80:81], v[82:83]
	v_cvt_pk_bf16_f32 v80, v84, v85
	v_mad_i64_i32 v[84:85], s[0:1], v160, s59, v[112:113]
	v_cvt_pk_bf16_f32 v81, v86, v87
	v_cvt_pk_bf16_f32 v82, v88, v89
	v_cvt_pk_bf16_f32 v83, v90, v91
	v_lshl_add_u64 v[84:85], v[84:85], 0, v[114:115]
	v_mul_f32_e32 v86, 0xbfb8aa3b, v76
	global_store_dwordx4 v[84:85], v[80:83], off
	v_exp_f32_e32 v86, v86
	v_pk_mul_f32 v[68:69], v[68:69], v[170:171] op_sel_hi:[1,0]
	v_mul_f32_e32 v80, 0xbfb8aa3b, v77
	v_exp_f32_e32 v81, v80
	v_mul_f32_e32 v82, 0xbfb8aa3b, v78
	v_mul_f32_e32 v83, 0xbfb8aa3b, v79
	v_exp_f32_e32 v82, v82
	v_exp_f32_e32 v83, v83
	v_add_f32_e32 v80, 1.0, v86
	v_add_f32_e32 v81, 1.0, v81
	v_rcp_f32_e32 v80, v80
	v_rcp_f32_e32 v81, v81
	v_add_f32_e32 v82, 1.0, v82
	v_add_f32_e32 v83, 1.0, v83
	v_rcp_f32_e32 v82, v82
	v_rcp_f32_e32 v83, v83
	v_pk_mul_f32 v[76:77], v[76:77], v[80:81]
	v_pk_mul_f32 v[72:73], v[72:73], v[170:171] op_sel_hi:[1,0]
	v_pk_mul_f32 v[68:69], v[68:69], v[76:77]
	v_pk_mul_f32 v[76:77], v[78:79], v[82:83]
	v_mul_f32_e32 v78, 0xbfb8aa3b, v72
	v_exp_f32_e32 v78, v78
	v_pk_mul_f32 v[70:71], v[70:71], v[170:171] op_sel_hi:[1,0]
	v_pk_mul_f32 v[74:75], v[74:75], v[170:171] op_sel_hi:[1,0]
	v_pk_mul_f32 v[70:71], v[70:71], v[76:77]
	v_mul_f32_e32 v76, 0xbfb8aa3b, v73
	v_exp_f32_e32 v77, v76
	v_add_f32_e32 v76, 1.0, v78
	v_mul_f32_e32 v78, 0xbfb8aa3b, v74
	v_mul_f32_e32 v79, 0xbfb8aa3b, v75
	v_exp_f32_e32 v78, v78
	v_exp_f32_e32 v79, v79
	v_add_f32_e32 v77, 1.0, v77
	v_rcp_f32_e32 v76, v76
	v_rcp_f32_e32 v77, v77
	v_add_f32_e32 v78, 1.0, v78
	v_add_f32_e32 v79, 1.0, v79
	v_rcp_f32_e32 v78, v78
	v_rcp_f32_e32 v79, v79
	v_pk_mul_f32 v[64:65], v[64:65], v[170:171] op_sel_hi:[1,0]
	v_pk_mul_f32 v[72:73], v[72:73], v[76:77]
	v_pk_mul_f32 v[60:61], v[60:61], v[166:167] op_sel_hi:[1,0]
	v_pk_mul_f32 v[72:73], v[64:65], v[72:73]
	v_pk_mul_f32 v[64:65], v[66:67], v[170:171] op_sel_hi:[1,0]
	v_pk_mul_f32 v[66:67], v[74:75], v[78:79]
	v_pk_mul_f32 v[62:63], v[62:63], v[166:167] op_sel_hi:[1,0]
	v_pk_mul_f32 v[74:75], v[64:65], v[66:67]
	v_cvt_pk_bf16_f32 v64, v68, v69
	v_mad_i64_i32 v[68:69], s[0:1], v156, s59, v[112:113]
	v_cvt_pk_bf16_f32 v65, v70, v71
	v_cvt_pk_bf16_f32 v66, v72, v73
	v_cvt_pk_bf16_f32 v67, v74, v75
	v_lshl_add_u64 v[68:69], v[68:69], 0, v[114:115]
	v_mul_f32_e32 v70, 0xbfb8aa3b, v60
	global_store_dwordx4 v[68:69], v[64:67], off
	v_exp_f32_e32 v70, v70
	v_pk_mul_f32 v[52:53], v[52:53], v[166:167] op_sel_hi:[1,0]
	v_mul_f32_e32 v64, 0xbfb8aa3b, v61
	v_exp_f32_e32 v65, v64
	v_mul_f32_e32 v66, 0xbfb8aa3b, v62
	v_mul_f32_e32 v67, 0xbfb8aa3b, v63
	v_exp_f32_e32 v66, v66
	v_exp_f32_e32 v67, v67
	v_add_f32_e32 v64, 1.0, v70
	v_add_f32_e32 v65, 1.0, v65
	v_rcp_f32_e32 v64, v64
	v_rcp_f32_e32 v65, v65
	v_add_f32_e32 v66, 1.0, v66
	v_add_f32_e32 v67, 1.0, v67
	v_rcp_f32_e32 v66, v66
	v_rcp_f32_e32 v67, v67
	v_pk_mul_f32 v[60:61], v[60:61], v[64:65]
	v_pk_mul_f32 v[56:57], v[56:57], v[166:167] op_sel_hi:[1,0]
	v_pk_mul_f32 v[52:53], v[52:53], v[60:61]
	v_pk_mul_f32 v[60:61], v[62:63], v[66:67]
	v_mul_f32_e32 v62, 0xbfb8aa3b, v56
	v_exp_f32_e32 v62, v62
	v_pk_mul_f32 v[54:55], v[54:55], v[166:167] op_sel_hi:[1,0]
	v_pk_mul_f32 v[58:59], v[58:59], v[166:167] op_sel_hi:[1,0]
	v_pk_mul_f32 v[54:55], v[54:55], v[60:61]
	v_mul_f32_e32 v60, 0xbfb8aa3b, v57
	v_exp_f32_e32 v61, v60
	v_add_f32_e32 v60, 1.0, v62
	v_mul_f32_e32 v62, 0xbfb8aa3b, v58
	v_mul_f32_e32 v63, 0xbfb8aa3b, v59
	v_exp_f32_e32 v62, v62
	v_exp_f32_e32 v63, v63
	v_add_f32_e32 v61, 1.0, v61
	v_rcp_f32_e32 v60, v60
	v_rcp_f32_e32 v61, v61
	v_add_f32_e32 v62, 1.0, v62
	v_add_f32_e32 v63, 1.0, v63
	v_rcp_f32_e32 v62, v62
	v_rcp_f32_e32 v63, v63
	v_pk_mul_f32 v[48:49], v[48:49], v[166:167] op_sel_hi:[1,0]
	v_pk_mul_f32 v[56:57], v[56:57], v[60:61]
	v_pk_mul_f32 v[44:45], v[44:45], v[162:163] op_sel_hi:[1,0]
	v_pk_mul_f32 v[56:57], v[48:49], v[56:57]
	v_pk_mul_f32 v[48:49], v[50:51], v[166:167] op_sel_hi:[1,0]
	v_pk_mul_f32 v[50:51], v[58:59], v[62:63]
	v_pk_mul_f32 v[46:47], v[46:47], v[162:163] op_sel_hi:[1,0]
	v_pk_mul_f32 v[58:59], v[48:49], v[50:51]
	v_cvt_pk_bf16_f32 v48, v52, v53
	v_mad_i64_i32 v[52:53], s[0:1], v152, s59, v[112:113]
	v_cvt_pk_bf16_f32 v49, v54, v55
	v_cvt_pk_bf16_f32 v50, v56, v57
	v_cvt_pk_bf16_f32 v51, v58, v59
	v_lshl_add_u64 v[52:53], v[52:53], 0, v[114:115]
	v_mul_f32_e32 v54, 0xbfb8aa3b, v44
	global_store_dwordx4 v[52:53], v[48:51], off
	v_exp_f32_e32 v54, v54
	v_pk_mul_f32 v[36:37], v[36:37], v[162:163] op_sel_hi:[1,0]
	v_mul_f32_e32 v48, 0xbfb8aa3b, v45
	v_exp_f32_e32 v49, v48
	v_mul_f32_e32 v50, 0xbfb8aa3b, v46
	v_mul_f32_e32 v51, 0xbfb8aa3b, v47
	v_exp_f32_e32 v50, v50
	v_exp_f32_e32 v51, v51
	v_add_f32_e32 v48, 1.0, v54
	v_add_f32_e32 v49, 1.0, v49
	v_rcp_f32_e32 v48, v48
	v_rcp_f32_e32 v49, v49
	v_add_f32_e32 v50, 1.0, v50
	v_add_f32_e32 v51, 1.0, v51
	v_rcp_f32_e32 v50, v50
	v_rcp_f32_e32 v51, v51
	v_pk_mul_f32 v[44:45], v[44:45], v[48:49]
	v_pk_mul_f32 v[40:41], v[40:41], v[162:163] op_sel_hi:[1,0]
	v_pk_mul_f32 v[36:37], v[36:37], v[44:45]
	v_pk_mul_f32 v[44:45], v[46:47], v[50:51]
	v_mul_f32_e32 v46, 0xbfb8aa3b, v40
	v_exp_f32_e32 v46, v46
	v_pk_mul_f32 v[38:39], v[38:39], v[162:163] op_sel_hi:[1,0]
	v_pk_mul_f32 v[42:43], v[42:43], v[162:163] op_sel_hi:[1,0]
	v_pk_mul_f32 v[38:39], v[38:39], v[44:45]
	v_mul_f32_e32 v44, 0xbfb8aa3b, v41
	v_exp_f32_e32 v45, v44
	v_add_f32_e32 v44, 1.0, v46
	v_mul_f32_e32 v46, 0xbfb8aa3b, v42
	v_mul_f32_e32 v47, 0xbfb8aa3b, v43
	v_exp_f32_e32 v46, v46
	v_exp_f32_e32 v47, v47
	v_add_f32_e32 v45, 1.0, v45
	v_rcp_f32_e32 v44, v44
	v_rcp_f32_e32 v45, v45
	v_add_f32_e32 v46, 1.0, v46
	v_add_f32_e32 v47, 1.0, v47
	v_rcp_f32_e32 v46, v46
	v_rcp_f32_e32 v47, v47
	v_pk_mul_f32 v[32:33], v[32:33], v[162:163] op_sel_hi:[1,0]
	v_pk_mul_f32 v[40:41], v[40:41], v[44:45]
	v_pk_mul_f32 v[28:29], v[28:29], v[158:159] op_sel_hi:[1,0]
	v_pk_mul_f32 v[40:41], v[32:33], v[40:41]
	v_pk_mul_f32 v[32:33], v[34:35], v[162:163] op_sel_hi:[1,0]
	v_pk_mul_f32 v[34:35], v[42:43], v[46:47]
	v_pk_mul_f32 v[30:31], v[30:31], v[158:159] op_sel_hi:[1,0]
	v_pk_mul_f32 v[42:43], v[32:33], v[34:35]
	v_cvt_pk_bf16_f32 v32, v36, v37
	v_mad_i64_i32 v[36:37], s[0:1], v150, s59, v[112:113]
	v_cvt_pk_bf16_f32 v33, v38, v39
	v_cvt_pk_bf16_f32 v34, v40, v41
	v_cvt_pk_bf16_f32 v35, v42, v43
	v_lshl_add_u64 v[36:37], v[36:37], 0, v[114:115]
	v_mul_f32_e32 v38, 0xbfb8aa3b, v28
	global_store_dwordx4 v[36:37], v[32:35], off
	v_exp_f32_e32 v38, v38
	v_pk_mul_f32 v[20:21], v[20:21], v[158:159] op_sel_hi:[1,0]
	v_mul_f32_e32 v32, 0xbfb8aa3b, v29
	v_exp_f32_e32 v33, v32
	v_mul_f32_e32 v34, 0xbfb8aa3b, v30
	v_mul_f32_e32 v35, 0xbfb8aa3b, v31
	v_exp_f32_e32 v34, v34
	v_exp_f32_e32 v35, v35
	v_add_f32_e32 v32, 1.0, v38
	v_add_f32_e32 v33, 1.0, v33
	v_rcp_f32_e32 v32, v32
	v_rcp_f32_e32 v33, v33
	v_add_f32_e32 v34, 1.0, v34
	v_add_f32_e32 v35, 1.0, v35
	v_rcp_f32_e32 v34, v34
	v_rcp_f32_e32 v35, v35
	v_pk_mul_f32 v[28:29], v[28:29], v[32:33]
	v_pk_mul_f32 v[24:25], v[24:25], v[158:159] op_sel_hi:[1,0]
	v_pk_mul_f32 v[20:21], v[20:21], v[28:29]
	v_pk_mul_f32 v[28:29], v[30:31], v[34:35]
	v_mul_f32_e32 v30, 0xbfb8aa3b, v24
	v_exp_f32_e32 v30, v30
	v_pk_mul_f32 v[22:23], v[22:23], v[158:159] op_sel_hi:[1,0]
	v_pk_mul_f32 v[26:27], v[26:27], v[158:159] op_sel_hi:[1,0]
	v_pk_mul_f32 v[22:23], v[22:23], v[28:29]
	v_mul_f32_e32 v28, 0xbfb8aa3b, v25
	v_exp_f32_e32 v29, v28
	v_add_f32_e32 v28, 1.0, v30
	v_mul_f32_e32 v30, 0xbfb8aa3b, v26
	v_mul_f32_e32 v31, 0xbfb8aa3b, v27
	v_exp_f32_e32 v30, v30
	v_exp_f32_e32 v31, v31
	v_add_f32_e32 v29, 1.0, v29
	v_rcp_f32_e32 v28, v28
	v_rcp_f32_e32 v29, v29
	v_add_f32_e32 v30, 1.0, v30
	v_add_f32_e32 v31, 1.0, v31
	v_rcp_f32_e32 v30, v30
	v_rcp_f32_e32 v31, v31
	v_pk_mul_f32 v[16:17], v[16:17], v[158:159] op_sel_hi:[1,0]
	v_pk_mul_f32 v[24:25], v[24:25], v[28:29]
	v_pk_mul_f32 v[12:13], v[12:13], v[154:155] op_sel_hi:[1,0]
	v_pk_mul_f32 v[24:25], v[16:17], v[24:25]
	v_pk_mul_f32 v[16:17], v[18:19], v[158:159] op_sel_hi:[1,0]
	v_pk_mul_f32 v[18:19], v[26:27], v[30:31]
	v_pk_mul_f32 v[14:15], v[14:15], v[154:155] op_sel_hi:[1,0]
	v_pk_mul_f32 v[26:27], v[16:17], v[18:19]
	v_cvt_pk_bf16_f32 v16, v20, v21
	v_mad_i64_i32 v[20:21], s[0:1], v148, s59, v[112:113]
	v_cvt_pk_bf16_f32 v17, v22, v23
	v_cvt_pk_bf16_f32 v18, v24, v25
	v_cvt_pk_bf16_f32 v19, v26, v27
	v_lshl_add_u64 v[20:21], v[20:21], 0, v[114:115]
	v_mul_f32_e32 v22, 0xbfb8aa3b, v12
	global_store_dwordx4 v[20:21], v[16:19], off
	v_exp_f32_e32 v22, v22
	v_pk_mul_f32 v[4:5], v[4:5], v[154:155] op_sel_hi:[1,0]
	v_mul_f32_e32 v16, 0xbfb8aa3b, v13
	v_exp_f32_e32 v17, v16
	v_mul_f32_e32 v18, 0xbfb8aa3b, v14
	v_mul_f32_e32 v19, 0xbfb8aa3b, v15
	v_exp_f32_e32 v18, v18
	v_exp_f32_e32 v19, v19
	v_add_f32_e32 v16, 1.0, v22
	v_add_f32_e32 v17, 1.0, v17
	v_rcp_f32_e32 v16, v16
	v_rcp_f32_e32 v17, v17
	v_add_f32_e32 v18, 1.0, v18
	v_add_f32_e32 v19, 1.0, v19
	v_rcp_f32_e32 v18, v18
	v_rcp_f32_e32 v19, v19
	v_pk_mul_f32 v[12:13], v[12:13], v[16:17]
	v_pk_mul_f32 v[8:9], v[8:9], v[154:155] op_sel_hi:[1,0]
	v_pk_mul_f32 v[4:5], v[4:5], v[12:13]
	v_pk_mul_f32 v[12:13], v[14:15], v[18:19]
	v_mul_f32_e32 v14, 0xbfb8aa3b, v8
	v_exp_f32_e32 v14, v14
	v_pk_mul_f32 v[6:7], v[6:7], v[154:155] op_sel_hi:[1,0]
	v_pk_mul_f32 v[10:11], v[10:11], v[154:155] op_sel_hi:[1,0]
	v_pk_mul_f32 v[6:7], v[6:7], v[12:13]
	v_mul_f32_e32 v12, 0xbfb8aa3b, v9
	v_exp_f32_e32 v13, v12
	v_add_f32_e32 v12, 1.0, v14
	v_mul_f32_e32 v14, 0xbfb8aa3b, v10
	v_mul_f32_e32 v15, 0xbfb8aa3b, v11
	v_exp_f32_e32 v14, v14
	v_exp_f32_e32 v15, v15
	v_add_f32_e32 v13, 1.0, v13
	v_rcp_f32_e32 v12, v12
	v_rcp_f32_e32 v13, v13
	v_add_f32_e32 v14, 1.0, v14
	v_add_f32_e32 v15, 1.0, v15
	v_rcp_f32_e32 v14, v14
	v_rcp_f32_e32 v15, v15
	v_pk_mul_f32 v[0:1], v[0:1], v[154:155] op_sel_hi:[1,0]
	v_pk_mul_f32 v[8:9], v[8:9], v[12:13]
	s_and_b64 vcc, exec, s[2:3]
	v_pk_mul_f32 v[8:9], v[0:1], v[8:9]
	v_pk_mul_f32 v[0:1], v[2:3], v[154:155] op_sel_hi:[1,0]
	v_pk_mul_f32 v[2:3], v[10:11], v[14:15]
	s_mov_b32 s5, s12
	v_pk_mul_f32 v[10:11], v[0:1], v[2:3]
	v_cvt_pk_bf16_f32 v0, v4, v5
	v_mad_i64_i32 v[4:5], s[0:1], v146, s59, v[112:113]
	v_cvt_pk_bf16_f32 v1, v6, v7
	v_cvt_pk_bf16_f32 v2, v8, v9
	v_cvt_pk_bf16_f32 v3, v10, v11
	v_lshl_add_u64 v[4:5], v[4:5], 0, v[114:115]
	s_mov_b32 s4, s36
	s_mov_b64 s[42:43], s[40:41]
	s_mov_b64 s[44:45], s[38:39]
	global_store_dwordx4 v[4:5], v[0:3], off
	s_waitcnt vmcnt(8)
	v_xor_b32_e32 v184, 16, v177
	v_xor_b32_e32 v185, 32, v177
	v_lshlrev_b32_e32 v184, 2, v184
	v_lshlrev_b32_e32 v185, 2, v185
	v_mov_b32_e32 v190, s10
	v_pk_add_f32 v[216:217], v[216:217], v[218:219]
	v_pk_add_f32 v[220:221], v[220:221], v[222:223]
	v_pk_add_f32 v[224:225], v[224:225], v[226:227]
	v_pk_add_f32 v[196:197], v[196:197], v[198:199]
	v_pk_add_f32 v[200:201], v[200:201], v[202:203]
	v_pk_add_f32 v[204:205], v[204:205], v[206:207]
	v_pk_add_f32 v[208:209], v[208:209], v[210:211]
	v_pk_add_f32 v[212:213], v[212:213], v[214:215]
	v_add_f32_e32 v216, v216, v217
	v_add_f32_e32 v220, v220, v221
	v_add_f32_e32 v224, v224, v225
	v_add_f32_e32 v196, v196, v197
	v_add_f32_e32 v200, v200, v201
	v_add_f32_e32 v204, v204, v205
	v_add_f32_e32 v208, v208, v209
	v_add_f32_e32 v212, v212, v213
	ds_bpermute_b32 v218, v184, v216
	ds_bpermute_b32 v219, v184, v220
	ds_bpermute_b32 v222, v184, v224
	ds_bpermute_b32 v223, v184, v196
	ds_bpermute_b32 v226, v184, v200
	ds_bpermute_b32 v227, v184, v204
	ds_bpermute_b32 v198, v184, v208
	ds_bpermute_b32 v199, v184, v212
	s_waitcnt lgkmcnt(0)
	v_add_f32_e32 v216, v216, v218
	v_add_f32_e32 v220, v220, v219
	v_add_f32_e32 v224, v224, v222
	v_add_f32_e32 v196, v196, v223
	v_add_f32_e32 v200, v200, v226
	v_add_f32_e32 v204, v204, v227
	v_add_f32_e32 v208, v208, v198
	v_add_f32_e32 v212, v212, v199
	ds_bpermute_b32 v218, v185, v216
	ds_bpermute_b32 v219, v185, v220
	ds_bpermute_b32 v222, v185, v224
	ds_bpermute_b32 v223, v185, v196
	ds_bpermute_b32 v226, v185, v200
	ds_bpermute_b32 v227, v185, v204
	ds_bpermute_b32 v198, v185, v208
	ds_bpermute_b32 v199, v185, v212
	s_waitcnt lgkmcnt(0)
	v_add_f32_e32 v216, v216, v218
	v_add_f32_e32 v220, v220, v219
	v_add_f32_e32 v224, v224, v222
	v_add_f32_e32 v196, v196, v223
	v_add_f32_e32 v200, v200, v226
	v_add_f32_e32 v204, v204, v227
	v_add_f32_e32 v208, v208, v198
	v_add_f32_e32 v212, v212, v199
	v_fma_f32 v216, v216, s8, v190
	v_fma_f32 v220, v220, s8, v190
	v_fma_f32 v224, v224, s8, v190
	v_fma_f32 v196, v196, s8, v190
	v_fma_f32 v200, v200, s8, v190
	v_fma_f32 v204, v204, s8, v190
	v_fma_f32 v208, v208, s8, v190
	v_fma_f32 v212, v212, s8, v190
	v_rsq_f32_e32 v240, v216
	v_rsq_f32_e32 v176, v220
	v_rsq_f32_e32 v174, v224
	v_rsq_f32_e32 v170, v196
	v_rsq_f32_e32 v166, v200
	v_rsq_f32_e32 v162, v204
	v_rsq_f32_e32 v158, v208
	v_rsq_f32_e32 v241, v212
	s_and_b64 vcc, exec, s[2:3]
	s_mov_b32 s5, s12
	s_mov_b32 s4, s36
	s_cbranch_vccz .LBB0_1090
	s_waitcnt vmcnt(0)
	s_cmpk_gt_u32 s9, 0xff
	s_cbranch_scc1 .LBB0_1097
	s_barrier

.LBB0_1169:
	ds_read_b128 v[128:131], v167
	ds_read_b128 v[132:135], v167 offset:1024
	ds_read_b128 v[136:139], v167 offset:2048
	ds_read_b128 v[156:159], v167 offset:3072
	ds_read_b128 v[160:163], v168
	ds_read_b128 v[172:175], v168 offset:1024
	ds_read_b128 v[176:179], v168 offset:2048
	ds_read_b128 v[180:183], v168 offset:3072
	ds_read_b128 v[184:187], v168 offset:4096
	ds_read_b128 v[188:191], v168 offset:5120
	ds_read_b128 v[194:197], v168 offset:6144
	ds_read_b128 v[198:201], v168 offset:7168
	s_add_u32 s6, s40, 0x100
	s_addc_u32 s7, s41, 0
	s_cmp_eq_u32 s65, 40
	s_cselect_b32 s45, s1, s7
	s_cselect_b32 s44, s0, s6
	s_cselect_b32 s43, s39, s64
	s_cselect_b32 s42, s38, s63
	v_lshl_add_u64 v[202:203], s[40:41], 0, v[148:149]
	s_add_i32 m0, s47, 0xc000
	global_load_lds_dwordx4 v[202:203], off
	v_lshl_add_u64 v[202:203], s[40:41], 0, v[150:151]
	s_add_i32 m0, s47, 0xe000
	s_nop 0
	global_load_lds_dwordx4 v[202:203], off
	s_waitcnt lgkmcnt(8)
	s_barrier
	s_waitcnt lgkmcnt(0)
	v_mfma_f32_16x16x32_bf16 v[124:127], v[128:131], v[160:163], v[124:127]
	v_mfma_f32_16x16x32_bf16 v[120:123], v[136:139], v[160:163], v[120:123]
	v_mfma_f32_16x16x32_bf16 v[108:111], v[128:131], v[176:179], v[108:111]
	v_mfma_f32_16x16x32_bf16 v[104:107], v[136:139], v[176:179], v[104:107]
	v_mfma_f32_16x16x32_bf16 v[92:95], v[128:131], v[184:187], v[92:95]
	v_mfma_f32_16x16x32_bf16 v[88:91], v[136:139], v[184:187], v[88:91]
	v_mfma_f32_16x16x32_bf16 v[76:79], v[128:131], v[194:197], v[76:79]
	v_mfma_f32_16x16x32_bf16 v[72:75], v[136:139], v[194:197], v[72:75]
	v_mfma_f32_16x16x32_bf16 v[124:127], v[132:135], v[172:175], v[124:127]
	v_mfma_f32_16x16x32_bf16 v[120:123], v[156:159], v[172:175], v[120:123]
	v_mfma_f32_16x16x32_bf16 v[108:111], v[132:135], v[180:183], v[108:111]
	v_mfma_f32_16x16x32_bf16 v[104:107], v[156:159], v[180:183], v[104:107]
	v_mfma_f32_16x16x32_bf16 v[92:95], v[132:135], v[188:191], v[92:95]
	v_mfma_f32_16x16x32_bf16 v[88:91], v[156:159], v[188:191], v[88:91]
	v_mfma_f32_16x16x32_bf16 v[76:79], v[132:135], v[198:201], v[76:79]
	v_mfma_f32_16x16x32_bf16 v[72:75], v[156:159], v[198:201], v[72:75]
	s_barrier
	s_add_i32 s28, s57, s46
	v_lshl_add_u64 v[218:219], s[42:43], 0, v[142:143]
	s_mov_b32 m0, s28
	ds_read_b128 v[202:205], v169
	ds_read_b128 v[206:209], v169 offset:1024
	ds_read_b128 v[210:213], v169 offset:2048
	ds_read_b128 v[214:217], v169 offset:3072
	global_load_lds_dwordx4 v[218:219], off
	v_lshl_add_u64 v[220:221], s[42:43], 0, v[146:147]
	s_add_i32 m0, s28, 0x2000
	s_nop 0
	global_load_lds_dwordx4 v[220:221], off
	s_barrier
	s_waitcnt lgkmcnt(0)
	v_mfma_f32_16x16x32_bf16 v[116:119], v[202:205], v[160:163], v[116:119]
	v_mfma_f32_16x16x32_bf16 v[112:115], v[210:213], v[160:163], v[112:115]
	v_mfma_f32_16x16x32_bf16 v[100:103], v[202:205], v[176:179], v[100:103]
	v_mfma_f32_16x16x32_bf16 v[96:99], v[210:213], v[176:179], v[96:99]
	v_mfma_f32_16x16x32_bf16 v[84:87], v[202:205], v[184:187], v[84:87]
	v_mfma_f32_16x16x32_bf16 v[80:83], v[210:213], v[184:187], v[80:83]
	v_mfma_f32_16x16x32_bf16 v[68:71], v[202:205], v[194:197], v[68:71]
	v_mfma_f32_16x16x32_bf16 v[64:67], v[210:213], v[194:197], v[64:67]
	v_mfma_f32_16x16x32_bf16 v[116:119], v[206:209], v[172:175], v[116:119]
	v_mfma_f32_16x16x32_bf16 v[112:115], v[214:217], v[172:175], v[112:115]
	v_mfma_f32_16x16x32_bf16 v[100:103], v[206:209], v[180:183], v[100:103]
	v_mfma_f32_16x16x32_bf16 v[96:99], v[214:217], v[180:183], v[96:99]
	v_mfma_f32_16x16x32_bf16 v[84:87], v[206:209], v[188:191], v[84:87]
	v_mfma_f32_16x16x32_bf16 v[80:83], v[214:217], v[188:191], v[80:83]
	v_mfma_f32_16x16x32_bf16 v[68:71], v[206:209], v[198:201], v[68:71]
	v_mfma_f32_16x16x32_bf16 v[64:67], v[214:217], v[198:201], v[64:67]
	s_mov_b32 m0, s47
	v_lshl_add_u64 v[222:223], s[44:45], 0, v[140:141]
	s_barrier
	ds_read_b128 v[160:163], v168 offset:16384
	ds_read_b128 v[172:175], v168 offset:17408
	ds_read_b128 v[176:179], v168 offset:18432
	ds_read_b128 v[180:183], v168 offset:19456
	ds_read_b128 v[184:187], v168 offset:20480
	ds_read_b128 v[188:191], v168 offset:21504
	ds_read_b128 v[194:197], v168 offset:22528
	ds_read_b128 v[198:201], v168 offset:23552
	global_load_lds_dwordx4 v[222:223], off
	v_lshl_add_u64 v[224:225], s[44:45], 0, v[144:145]
	s_mov_b32 m0, s48
	s_nop 0
	global_load_lds_dwordx4 v[224:225], off
	s_barrier
	s_waitcnt lgkmcnt(0)
	v_mfma_f32_16x16x32_bf16 v[60:63], v[128:131], v[160:163], v[60:63]
	v_mfma_f32_16x16x32_bf16 v[56:59], v[136:139], v[160:163], v[56:59]
	v_mfma_f32_16x16x32_bf16 v[44:47], v[128:131], v[176:179], v[44:47]
	v_mfma_f32_16x16x32_bf16 v[40:43], v[136:139], v[176:179], v[40:43]
	v_mfma_f32_16x16x32_bf16 v[28:31], v[128:131], v[184:187], v[28:31]
	v_mfma_f32_16x16x32_bf16 v[24:27], v[136:139], v[184:187], v[24:27]
	v_mfma_f32_16x16x32_bf16 v[12:15], v[128:131], v[194:197], v[12:15]
	v_mfma_f32_16x16x32_bf16 v[8:11], v[136:139], v[194:197], v[8:11]
	v_mfma_f32_16x16x32_bf16 v[60:63], v[132:135], v[172:175], v[60:63]
	v_mfma_f32_16x16x32_bf16 v[56:59], v[156:159], v[172:175], v[56:59]
	v_mfma_f32_16x16x32_bf16 v[44:47], v[132:135], v[180:183], v[44:47]
	v_mfma_f32_16x16x32_bf16 v[40:43], v[156:159], v[180:183], v[40:43]
	v_mfma_f32_16x16x32_bf16 v[28:31], v[132:135], v[188:191], v[28:31]
	v_mfma_f32_16x16x32_bf16 v[24:27], v[156:159], v[188:191], v[24:27]
	v_mfma_f32_16x16x32_bf16 v[12:15], v[132:135], v[198:201], v[12:15]
	v_mfma_f32_16x16x32_bf16 v[8:11], v[156:159], v[198:201], v[8:11]
	s_barrier
	s_add_u32 s40, s42, 0x2c000
	s_addc_u32 s41, s43, 0
	s_add_i32 s28, s58, s46
	v_lshl_add_u64 v[128:129], s[40:41], 0, v[142:143]
	s_mov_b32 m0, s28
	s_nop 0
	global_load_lds_dwordx4 v[128:129], off
	v_lshl_add_u64 v[128:129], s[40:41], 0, v[146:147]
	s_add_i32 m0, s28, 0x2000
	s_nop 0
	global_load_lds_dwordx4 v[128:129], off
	s_waitcnt vmcnt(6)
	s_barrier
	v_mfma_f32_16x16x32_bf16 v[52:55], v[202:205], v[160:163], v[52:55]
	v_mfma_f32_16x16x32_bf16 v[48:51], v[210:213], v[160:163], v[48:51]
	v_mfma_f32_16x16x32_bf16 v[36:39], v[202:205], v[176:179], v[36:39]
	v_mfma_f32_16x16x32_bf16 v[32:35], v[210:213], v[176:179], v[32:35]
	v_mfma_f32_16x16x32_bf16 v[20:23], v[202:205], v[184:187], v[20:23]
	v_mfma_f32_16x16x32_bf16 v[16:19], v[210:213], v[184:187], v[16:19]
	v_mfma_f32_16x16x32_bf16 v[4:7], v[202:205], v[194:197], v[4:7]
	v_mfma_f32_16x16x32_bf16 v[0:3], v[210:213], v[194:197], v[0:3]
	v_mfma_f32_16x16x32_bf16 v[52:55], v[206:209], v[172:175], v[52:55]
	v_mfma_f32_16x16x32_bf16 v[48:51], v[214:217], v[172:175], v[48:51]
	v_mfma_f32_16x16x32_bf16 v[36:39], v[206:209], v[180:183], v[36:39]
	v_mfma_f32_16x16x32_bf16 v[32:35], v[214:217], v[180:183], v[32:35]
	v_mfma_f32_16x16x32_bf16 v[20:23], v[206:209], v[188:191], v[20:23]
	v_mfma_f32_16x16x32_bf16 v[16:19], v[214:217], v[188:191], v[16:19]
	v_mfma_f32_16x16x32_bf16 v[4:7], v[206:209], v[198:201], v[4:7]
	v_mfma_f32_16x16x32_bf16 v[0:3], v[214:217], v[198:201], v[0:3]
	s_add_i32 s28, 0, 0x18000
	v_add_u32_e32 v156, s28, v165
	s_barrier
	ds_read_b128 v[128:131], v156
	ds_read_b128 v[132:135], v156 offset:1024
	ds_read_b128 v[136:139], v156 offset:2048
	ds_read_b128 v[156:159], v156 offset:3072
	ds_read_b128 v[160:163], v168 offset:32768
	ds_read_b128 v[172:175], v168 offset:33792
	ds_read_b128 v[176:179], v168 offset:34816
	ds_read_b128 v[180:183], v168 offset:35840
	ds_read_b128 v[184:187], v168 offset:36864
	ds_read_b128 v[188:191], v168 offset:37888
	ds_read_b128 v[194:197], v168 offset:38912
	ds_read_b128 v[198:201], v168 offset:39936
	s_add_u32 s40, s44, 0xb0000
	s_addc_u32 s41, s45, 0
	s_mov_b32 m0, s49
	v_lshl_add_u64 v[202:203], s[40:41], 0, v[140:141]
	global_load_lds_dwordx4 v[202:203], off
	v_lshl_add_u64 v[202:203], s[40:41], 0, v[144:145]
	s_mov_b32 m0, s50
	s_nop 0
	global_load_lds_dwordx4 v[202:203], off
	s_waitcnt lgkmcnt(8)
	s_barrier
	s_waitcnt lgkmcnt(0)
	v_mfma_f32_16x16x32_bf16 v[124:127], v[128:131], v[160:163], v[124:127]
	v_mfma_f32_16x16x32_bf16 v[120:123], v[136:139], v[160:163], v[120:123]
	v_mfma_f32_16x16x32_bf16 v[108:111], v[128:131], v[176:179], v[108:111]
	v_mfma_f32_16x16x32_bf16 v[104:107], v[136:139], v[176:179], v[104:107]
	v_mfma_f32_16x16x32_bf16 v[92:95], v[128:131], v[184:187], v[92:95]
	v_mfma_f32_16x16x32_bf16 v[88:91], v[136:139], v[184:187], v[88:91]
	v_mfma_f32_16x16x32_bf16 v[76:79], v[128:131], v[194:197], v[76:79]
	v_mfma_f32_16x16x32_bf16 v[72:75], v[136:139], v[194:197], v[72:75]
	v_mfma_f32_16x16x32_bf16 v[124:127], v[132:135], v[172:175], v[124:127]
	v_mfma_f32_16x16x32_bf16 v[120:123], v[156:159], v[172:175], v[120:123]
	v_mfma_f32_16x16x32_bf16 v[108:111], v[132:135], v[180:183], v[108:111]
	v_mfma_f32_16x16x32_bf16 v[104:107], v[156:159], v[180:183], v[104:107]
	v_mfma_f32_16x16x32_bf16 v[92:95], v[132:135], v[188:191], v[92:95]
	v_mfma_f32_16x16x32_bf16 v[88:91], v[156:159], v[188:191], v[88:91]
	v_mfma_f32_16x16x32_bf16 v[76:79], v[132:135], v[198:201], v[76:79]
	v_mfma_f32_16x16x32_bf16 v[72:75], v[156:159], v[198:201], v[72:75]
	s_barrier
	s_add_i32 s29, 0, 0x1c000
	s_add_i32 s28, s28, s46
	v_add_u32_e32 v171, s29, v165
	v_lshl_add_u64 v[218:219], v[218:219], 0, s[36:37]
	s_mov_b32 m0, s28
	ds_read_b128 v[202:205], v171
	ds_read_b128 v[206:209], v171 offset:1024
	ds_read_b128 v[210:213], v171 offset:2048
	ds_read_b128 v[214:217], v171 offset:3072
	global_load_lds_dwordx4 v[218:219], off
	v_lshl_add_u64 v[218:219], v[220:221], 0, s[36:37]
	s_add_i32 m0, s28, 0x2000
	s_nop 0
	global_load_lds_dwordx4 v[218:219], off
	s_barrier
	s_waitcnt lgkmcnt(0)
	v_mfma_f32_16x16x32_bf16 v[116:119], v[202:205], v[160:163], v[116:119]
	v_mfma_f32_16x16x32_bf16 v[112:115], v[210:213], v[160:163], v[112:115]
	v_mfma_f32_16x16x32_bf16 v[100:103], v[202:205], v[176:179], v[100:103]
	v_mfma_f32_16x16x32_bf16 v[96:99], v[210:213], v[176:179], v[96:99]
	v_mfma_f32_16x16x32_bf16 v[84:87], v[202:205], v[184:187], v[84:87]
	v_mfma_f32_16x16x32_bf16 v[80:83], v[210:213], v[184:187], v[80:83]
	v_mfma_f32_16x16x32_bf16 v[68:71], v[202:205], v[194:197], v[68:71]
	v_mfma_f32_16x16x32_bf16 v[64:67], v[210:213], v[194:197], v[64:67]
	v_mfma_f32_16x16x32_bf16 v[116:119], v[206:209], v[172:175], v[116:119]
	v_mfma_f32_16x16x32_bf16 v[112:115], v[214:217], v[172:175], v[112:115]
	v_mfma_f32_16x16x32_bf16 v[100:103], v[206:209], v[180:183], v[100:103]
	v_mfma_f32_16x16x32_bf16 v[96:99], v[214:217], v[180:183], v[96:99]
	v_mfma_f32_16x16x32_bf16 v[84:87], v[206:209], v[188:191], v[84:87]
	v_mfma_f32_16x16x32_bf16 v[80:83], v[214:217], v[188:191], v[80:83]
	v_mfma_f32_16x16x32_bf16 v[68:71], v[206:209], v[198:201], v[68:71]
	v_mfma_f32_16x16x32_bf16 v[64:67], v[214:217], v[198:201], v[64:67]
	s_mov_b32 m0, s54
	v_lshl_add_u64 v[218:219], v[222:223], 0, s[36:37]
	s_barrier
	ds_read_b128 v[160:163], v168 offset:49152
	ds_read_b128 v[172:175], v168 offset:50176
	ds_read_b128 v[176:179], v168 offset:51200
	ds_read_b128 v[180:183], v168 offset:52224
	ds_read_b128 v[184:187], v168 offset:53248
	ds_read_b128 v[188:191], v168 offset:54272
	ds_read_b128 v[194:197], v168 offset:55296
	ds_read_b128 v[198:201], v168 offset:56320
	global_load_lds_dwordx4 v[218:219], off
	v_lshl_add_u64 v[218:219], v[224:225], 0, s[36:37]
	s_mov_b32 m0, s55
	s_nop 0
	global_load_lds_dwordx4 v[218:219], off
	s_barrier
	s_waitcnt lgkmcnt(0)
	v_mfma_f32_16x16x32_bf16 v[60:63], v[128:131], v[160:163], v[60:63]
	v_mfma_f32_16x16x32_bf16 v[56:59], v[136:139], v[160:163], v[56:59]
	v_mfma_f32_16x16x32_bf16 v[44:47], v[128:131], v[176:179], v[44:47]
	v_mfma_f32_16x16x32_bf16 v[40:43], v[136:139], v[176:179], v[40:43]
	v_mfma_f32_16x16x32_bf16 v[28:31], v[128:131], v[184:187], v[28:31]
	v_mfma_f32_16x16x32_bf16 v[24:27], v[136:139], v[184:187], v[24:27]
	v_mfma_f32_16x16x32_bf16 v[12:15], v[128:131], v[194:197], v[12:15]
	v_mfma_f32_16x16x32_bf16 v[8:11], v[136:139], v[194:197], v[8:11]
	v_mfma_f32_16x16x32_bf16 v[60:63], v[132:135], v[172:175], v[60:63]
	v_mfma_f32_16x16x32_bf16 v[56:59], v[156:159], v[172:175], v[56:59]
	v_mfma_f32_16x16x32_bf16 v[44:47], v[132:135], v[180:183], v[44:47]
	v_mfma_f32_16x16x32_bf16 v[40:43], v[156:159], v[180:183], v[40:43]
	v_mfma_f32_16x16x32_bf16 v[28:31], v[132:135], v[188:191], v[28:31]
	v_mfma_f32_16x16x32_bf16 v[24:27], v[156:159], v[188:191], v[24:27]
	v_mfma_f32_16x16x32_bf16 v[12:15], v[132:135], v[198:201], v[12:15]
	v_mfma_f32_16x16x32_bf16 v[8:11], v[156:159], v[198:201], v[8:11]
	s_barrier
	s_add_u32 s40, s42, 0x2c080
	s_addc_u32 s41, s43, 0
	s_add_i32 s28, s29, s46
	v_lshl_add_u64 v[128:129], s[40:41], 0, v[142:143]
	s_mov_b32 m0, s28
	s_nop 0
	global_load_lds_dwordx4 v[128:129], off
	v_lshl_add_u64 v[128:129], s[40:41], 0, v[146:147]
	s_add_i32 m0, s28, 0x2000
	s_nop 0
	global_load_lds_dwordx4 v[128:129], off
	s_waitcnt vmcnt(6)
	s_barrier
	v_mfma_f32_16x16x32_bf16 v[52:55], v[202:205], v[160:163], v[52:55]
	v_mfma_f32_16x16x32_bf16 v[48:51], v[210:213], v[160:163], v[48:51]
	v_mfma_f32_16x16x32_bf16 v[36:39], v[202:205], v[176:179], v[36:39]
	v_mfma_f32_16x16x32_bf16 v[32:35], v[210:213], v[176:179], v[32:35]
	v_mfma_f32_16x16x32_bf16 v[20:23], v[202:205], v[184:187], v[20:23]
	v_mfma_f32_16x16x32_bf16 v[16:19], v[210:213], v[184:187], v[16:19]
	v_mfma_f32_16x16x32_bf16 v[4:7], v[202:205], v[194:197], v[4:7]
	v_mfma_f32_16x16x32_bf16 v[0:3], v[210:213], v[194:197], v[0:3]
	v_mfma_f32_16x16x32_bf16 v[52:55], v[206:209], v[172:175], v[52:55]
	v_mfma_f32_16x16x32_bf16 v[48:51], v[214:217], v[172:175], v[48:51]
	v_mfma_f32_16x16x32_bf16 v[36:39], v[206:209], v[180:183], v[36:39]
	v_mfma_f32_16x16x32_bf16 v[32:35], v[214:217], v[180:183], v[32:35]
	v_mfma_f32_16x16x32_bf16 v[20:23], v[206:209], v[188:191], v[20:23]
	v_mfma_f32_16x16x32_bf16 v[16:19], v[214:217], v[188:191], v[16:19]
	v_mfma_f32_16x16x32_bf16 v[4:7], v[206:209], v[198:201], v[4:7]
	v_mfma_f32_16x16x32_bf16 v[0:3], v[214:217], v[198:201], v[0:3]
	s_add_i32 s65, s65, 2
	s_add_u32 s63, s63, 0x100
	s_addc_u32 s64, s64, 0
	s_cmp_gt_u32 s65, 41
	s_mov_b64 s[40:41], s[6:7]
	s_barrier
	s_cbranch_scc0 .LBB0_1169
	v_lshl_add_u32 v171, s62, 8, v164
	v_lshl_or_b32 v188, s10, 8, v166
	s_mov_b32 s63, 0xffff0000
	v_lshlrev_b32_e32 v128, 11, v171
	v_lshl_add_u32 v128, v188, 1, v128
	v_lshlrev_b32_e32 v129, 12, v171
	v_lshl_add_u32 v129, v188, 2, v129
	v_lshlrev_b32_e32 v132, 2, v188
	s_mov_b64 s[70:71], s[68:69]
	global_load_dwordx4 v[194:197], v128, s[70:71]
	global_load_dwordx4 v[198:201], v128, s[70:71] offset:64
	s_add_u32 s70, s70, 0x8000
	s_addc_u32 s71, s71, 0
	global_load_dwordx4 v[202:205], v128, s[70:71]
	global_load_dwordx4 v[206:209], v128, s[70:71] offset:64
	s_add_u32 s70, s70, 0x8000
	s_addc_u32 s71, s71, 0
	global_load_dwordx4 v[210:213], v128, s[70:71]
	global_load_dwordx4 v[214:217], v128, s[70:71] offset:64
	s_add_u32 s70, s70, 0x8000
	s_addc_u32 s71, s71, 0
	global_load_dwordx4 v[218:221], v128, s[70:71]
	global_load_dwordx4 v[222:225], v128, s[70:71] offset:64
	s_add_u32 s70, s70, 0x28000
	s_addc_u32 s71, s71, 0
	global_load_dwordx4 v[226:229], v128, s[70:71]
	global_load_dwordx4 v[230:233], v128, s[70:71] offset:64
	s_add_u32 s70, s70, 0x8000
	s_addc_u32 s71, s71, 0
	global_load_dwordx4 v[234:237], v128, s[70:71]
	global_load_dwordx4 v[238:241], v128, s[70:71] offset:64
	s_add_u32 s70, s70, 0x8000
	s_addc_u32 s71, s71, 0
	global_load_dwordx4 v[172:175], v128, s[70:71]
	global_load_dwordx4 v[176:179], v128, s[70:71] offset:64
	s_add_u32 s70, s70, 0x8000
	s_addc_u32 s71, s71, 0
	global_load_dwordx4 v[180:183], v128, s[70:71]
	global_load_dwordx4 v[184:187], v128, s[70:71] offset:64
	s_bfe_u32 s42, s17, 0x20006
	s_lshl_b32 s43, s10, 4
	s_lshl_b32 s42, s42, 2
	s_add_i32 s43, s43, s42
	v_lshl_add_u32 v130, v171, 6, s43
	v_and_b32_e32 v131, 48, v170
	v_lshl_add_u32 v131, v171, 6, v131
	v_xor_b32_e32 v134, 16, v170
	v_xor_b32_e32 v135, 32, v170
	v_lshlrev_b32_e32 v134, 2, v134
	v_lshlrev_b32_e32 v135, 2, v135
	v_cmp_gt_u32_e64 s[64:65], 16, v170
	s_add_u32 s74, s8, 0x2000
	s_addc_u32 s75, s9, 0
	s_lshl_b32 s42, s62, 7
	s_add_u32 s78, s26, 0x3c08000
	s_addc_u32 s79, s27, 0
	s_add_u32 s78, s78, s42
	s_addc_u32 s79, s79, 0
	s_waitcnt vmcnt(14)
	v_lshlrev_b32_e32 v136, 16, v194
	v_and_b32_e32 v137, s63, v194
	v_pk_add_f32 v[124:125], v[124:125], v[136:137]
	v_lshlrev_b32_e32 v138, 16, v195
	v_and_b32_e32 v139, s63, v195
	v_pk_add_f32 v[126:127], v[126:127], v[138:139]
	v_lshlrev_b32_e32 v190, 16, v196
	v_and_b32_e32 v191, s63, v196
	v_pk_add_f32 v[120:121], v[120:121], v[190:191]
	v_lshlrev_b32_e32 v136, 16, v197
	v_and_b32_e32 v137, s63, v197
	v_pk_add_f32 v[122:123], v[122:123], v[136:137]
	v_lshlrev_b32_e32 v138, 16, v198
	v_and_b32_e32 v139, s63, v198
	v_pk_add_f32 v[116:117], v[116:117], v[138:139]
	v_lshlrev_b32_e32 v190, 16, v199
	v_and_b32_e32 v191, s63, v199
	v_pk_add_f32 v[118:119], v[118:119], v[190:191]
	v_lshlrev_b32_e32 v136, 16, v200
	v_and_b32_e32 v137, s63, v200
	v_pk_add_f32 v[112:113], v[112:113], v[136:137]
	v_lshlrev_b32_e32 v138, 16, v201
	v_and_b32_e32 v139, s63, v201
	v_pk_add_f32 v[114:115], v[114:115], v[138:139]
	v_mul_f32_e32 v156, v120, v120
	v_mul_f32_e32 v189, v112, v112
	v_fmac_f32_e32 v156, v121, v121
	v_fmac_f32_e32 v189, v113, v113
	v_fmac_f32_e32 v156, v122, v122
	v_fmac_f32_e32 v189, v114, v114
	v_fmac_f32_e32 v156, v123, v123
	v_fmac_f32_e32 v189, v115, v115
	v_fmac_f32_e32 v156, v124, v124
	v_fmac_f32_e32 v189, v116, v116
	v_fmac_f32_e32 v156, v125, v125
	v_fmac_f32_e32 v189, v117, v117
	v_fmac_f32_e32 v156, v126, v126
	v_fmac_f32_e32 v189, v118, v118
	v_fmac_f32_e32 v156, v127, v127
	v_fmac_f32_e32 v189, v119, v119
	v_add_f32_e32 v156, v156, v189
	s_waitcnt vmcnt(12)
	v_lshlrev_b32_e32 v190, 16, v202
	v_and_b32_e32 v191, s63, v202
	v_pk_add_f32 v[108:109], v[108:109], v[190:191]
	v_lshlrev_b32_e32 v136, 16, v203
	v_and_b32_e32 v137, s63, v203
	v_pk_add_f32 v[110:111], v[110:111], v[136:137]
	v_lshlrev_b32_e32 v138, 16, v204
	v_and_b32_e32 v139, s63, v204
	v_pk_add_f32 v[104:105], v[104:105], v[138:139]
	v_lshlrev_b32_e32 v190, 16, v205
	v_and_b32_e32 v191, s63, v205
	v_pk_add_f32 v[106:107], v[106:107], v[190:191]
	v_lshlrev_b32_e32 v136, 16, v206
	v_and_b32_e32 v137, s63, v206
	v_pk_add_f32 v[100:101], v[100:101], v[136:137]
	v_lshlrev_b32_e32 v138, 16, v207
	v_and_b32_e32 v139, s63, v207
	v_pk_add_f32 v[102:103], v[102:103], v[138:139]
	v_lshlrev_b32_e32 v190, 16, v208
	v_and_b32_e32 v191, s63, v208
	v_pk_add_f32 v[96:97], v[96:97], v[190:191]
	v_lshlrev_b32_e32 v136, 16, v209
	v_and_b32_e32 v137, s63, v209
	v_pk_add_f32 v[98:99], v[98:99], v[136:137]
	v_mul_f32_e32 v157, v104, v104
	v_mul_f32_e32 v189, v96, v96
	v_fmac_f32_e32 v157, v105, v105
	v_fmac_f32_e32 v189, v97, v97
	v_fmac_f32_e32 v157, v106, v106
	v_fmac_f32_e32 v189, v98, v98
	v_fmac_f32_e32 v157, v107, v107
	v_fmac_f32_e32 v189, v99, v99
	v_fmac_f32_e32 v157, v108, v108
	v_fmac_f32_e32 v189, v100, v100
	v_fmac_f32_e32 v157, v109, v109
	v_fmac_f32_e32 v189, v101, v101
	v_fmac_f32_e32 v157, v110, v110
	v_fmac_f32_e32 v189, v102, v102
	v_fmac_f32_e32 v157, v111, v111
	v_fmac_f32_e32 v189, v103, v103
	v_add_f32_e32 v157, v157, v189
	s_waitcnt vmcnt(10)
	v_lshlrev_b32_e32 v138, 16, v210
	v_and_b32_e32 v139, s63, v210
	v_pk_add_f32 v[92:93], v[92:93], v[138:139]
	v_lshlrev_b32_e32 v190, 16, v211
	v_and_b32_e32 v191, s63, v211
	v_pk_add_f32 v[94:95], v[94:95], v[190:191]
	v_lshlrev_b32_e32 v136, 16, v212
	v_and_b32_e32 v137, s63, v212
	v_pk_add_f32 v[88:89], v[88:89], v[136:137]
	v_lshlrev_b32_e32 v138, 16, v213
	v_and_b32_e32 v139, s63, v213
	v_pk_add_f32 v[90:91], v[90:91], v[138:139]
	v_lshlrev_b32_e32 v190, 16, v214
	v_and_b32_e32 v191, s63, v214
	v_pk_add_f32 v[84:85], v[84:85], v[190:191]
	v_lshlrev_b32_e32 v136, 16, v215
	v_and_b32_e32 v137, s63, v215
	v_pk_add_f32 v[86:87], v[86:87], v[136:137]
	v_lshlrev_b32_e32 v138, 16, v216
	v_and_b32_e32 v139, s63, v216
	v_pk_add_f32 v[80:81], v[80:81], v[138:139]
	v_lshlrev_b32_e32 v190, 16, v217
	v_and_b32_e32 v191, s63, v217
	v_pk_add_f32 v[82:83], v[82:83], v[190:191]
	v_mul_f32_e32 v158, v88, v88
	v_mul_f32_e32 v189, v80, v80
	v_fmac_f32_e32 v158, v89, v89
	v_fmac_f32_e32 v189, v81, v81
	v_fmac_f32_e32 v158, v90, v90
	v_fmac_f32_e32 v189, v82, v82
	v_fmac_f32_e32 v158, v91, v91
	v_fmac_f32_e32 v189, v83, v83
	v_fmac_f32_e32 v158, v92, v92
	v_fmac_f32_e32 v189, v84, v84
	v_fmac_f32_e32 v158, v93, v93
	v_fmac_f32_e32 v189, v85, v85
	v_fmac_f32_e32 v158, v94, v94
	v_fmac_f32_e32 v189, v86, v86
	v_fmac_f32_e32 v158, v95, v95
	v_fmac_f32_e32 v189, v87, v87
	v_add_f32_e32 v158, v158, v189
	s_waitcnt vmcnt(8)
	v_lshlrev_b32_e32 v136, 16, v218
	v_and_b32_e32 v137, s63, v218
	v_pk_add_f32 v[76:77], v[76:77], v[136:137]
	v_lshlrev_b32_e32 v138, 16, v219
	v_and_b32_e32 v139, s63, v219
	v_pk_add_f32 v[78:79], v[78:79], v[138:139]
	v_lshlrev_b32_e32 v190, 16, v220
	v_and_b32_e32 v191, s63, v220
	v_pk_add_f32 v[72:73], v[72:73], v[190:191]
	v_lshlrev_b32_e32 v136, 16, v221
	v_and_b32_e32 v137, s63, v221
	v_pk_add_f32 v[74:75], v[74:75], v[136:137]
	v_lshlrev_b32_e32 v138, 16, v222
	v_and_b32_e32 v139, s63, v222
	v_pk_add_f32 v[68:69], v[68:69], v[138:139]
	v_lshlrev_b32_e32 v190, 16, v223
	v_and_b32_e32 v191, s63, v223
	v_pk_add_f32 v[70:71], v[70:71], v[190:191]
	v_lshlrev_b32_e32 v136, 16, v224
	v_and_b32_e32 v137, s63, v224
	v_pk_add_f32 v[64:65], v[64:65], v[136:137]
	v_lshlrev_b32_e32 v138, 16, v225
	v_and_b32_e32 v139, s63, v225
	v_pk_add_f32 v[66:67], v[66:67], v[138:139]
	v_mul_f32_e32 v159, v72, v72
	v_mul_f32_e32 v189, v64, v64
	v_fmac_f32_e32 v159, v73, v73
	v_fmac_f32_e32 v189, v65, v65
	v_fmac_f32_e32 v159, v74, v74
	v_fmac_f32_e32 v189, v66, v66
	v_fmac_f32_e32 v159, v75, v75
	v_fmac_f32_e32 v189, v67, v67
	v_fmac_f32_e32 v159, v76, v76
	v_fmac_f32_e32 v189, v68, v68
	v_fmac_f32_e32 v159, v77, v77
	v_fmac_f32_e32 v189, v69, v69
	v_fmac_f32_e32 v159, v78, v78
	v_fmac_f32_e32 v189, v70, v70
	v_fmac_f32_e32 v159, v79, v79
	v_fmac_f32_e32 v189, v71, v71
	v_add_f32_e32 v159, v159, v189
	s_waitcnt vmcnt(6)
	v_lshlrev_b32_e32 v190, 16, v226
	v_and_b32_e32 v191, s63, v226
	v_pk_add_f32 v[60:61], v[60:61], v[190:191]
	v_lshlrev_b32_e32 v136, 16, v227
	v_and_b32_e32 v137, s63, v227
	v_pk_add_f32 v[62:63], v[62:63], v[136:137]
	v_lshlrev_b32_e32 v138, 16, v228
	v_and_b32_e32 v139, s63, v228
	v_pk_add_f32 v[56:57], v[56:57], v[138:139]
	v_lshlrev_b32_e32 v190, 16, v229
	v_and_b32_e32 v191, s63, v229
	v_pk_add_f32 v[58:59], v[58:59], v[190:191]
	v_lshlrev_b32_e32 v136, 16, v230
	v_and_b32_e32 v137, s63, v230
	v_pk_add_f32 v[52:53], v[52:53], v[136:137]
	v_lshlrev_b32_e32 v138, 16, v231
	v_and_b32_e32 v139, s63, v231
	v_pk_add_f32 v[54:55], v[54:55], v[138:139]
	v_lshlrev_b32_e32 v190, 16, v232
	v_and_b32_e32 v191, s63, v232
	v_pk_add_f32 v[48:49], v[48:49], v[190:191]
	v_lshlrev_b32_e32 v136, 16, v233
	v_and_b32_e32 v137, s63, v233
	v_pk_add_f32 v[50:51], v[50:51], v[136:137]
	v_mul_f32_e32 v160, v56, v56
	v_mul_f32_e32 v189, v48, v48
	v_fmac_f32_e32 v160, v57, v57
	v_fmac_f32_e32 v189, v49, v49
	v_fmac_f32_e32 v160, v58, v58
	v_fmac_f32_e32 v189, v50, v50
	v_fmac_f32_e32 v160, v59, v59
	v_fmac_f32_e32 v189, v51, v51
	v_fmac_f32_e32 v160, v60, v60
	v_fmac_f32_e32 v189, v52, v52
	v_fmac_f32_e32 v160, v61, v61
	v_fmac_f32_e32 v189, v53, v53
	v_fmac_f32_e32 v160, v62, v62
	v_fmac_f32_e32 v189, v54, v54
	v_fmac_f32_e32 v160, v63, v63
	v_fmac_f32_e32 v189, v55, v55
	v_add_f32_e32 v160, v160, v189
	s_waitcnt vmcnt(4)
	v_lshlrev_b32_e32 v138, 16, v234
	v_and_b32_e32 v139, s63, v234
	v_pk_add_f32 v[44:45], v[44:45], v[138:139]
	v_lshlrev_b32_e32 v190, 16, v235
	v_and_b32_e32 v191, s63, v235
	v_pk_add_f32 v[46:47], v[46:47], v[190:191]
	v_lshlrev_b32_e32 v136, 16, v236
	v_and_b32_e32 v137, s63, v236
	v_pk_add_f32 v[40:41], v[40:41], v[136:137]
	v_lshlrev_b32_e32 v138, 16, v237
	v_and_b32_e32 v139, s63, v237
	v_pk_add_f32 v[42:43], v[42:43], v[138:139]
	v_lshlrev_b32_e32 v190, 16, v238
	v_and_b32_e32 v191, s63, v238
	v_pk_add_f32 v[36:37], v[36:37], v[190:191]
	v_lshlrev_b32_e32 v136, 16, v239
	v_and_b32_e32 v137, s63, v239
	v_pk_add_f32 v[38:39], v[38:39], v[136:137]
	v_lshlrev_b32_e32 v138, 16, v240
	v_and_b32_e32 v139, s63, v240
	v_pk_add_f32 v[32:33], v[32:33], v[138:139]
	v_lshlrev_b32_e32 v190, 16, v241
	v_and_b32_e32 v191, s63, v241
	v_pk_add_f32 v[34:35], v[34:35], v[190:191]
	v_mul_f32_e32 v161, v40, v40
	v_mul_f32_e32 v189, v32, v32
	v_fmac_f32_e32 v161, v41, v41
	v_fmac_f32_e32 v189, v33, v33
	v_fmac_f32_e32 v161, v42, v42
	v_fmac_f32_e32 v189, v34, v34
	v_fmac_f32_e32 v161, v43, v43
	v_fmac_f32_e32 v189, v35, v35
	v_fmac_f32_e32 v161, v44, v44
	v_fmac_f32_e32 v189, v36, v36
	v_fmac_f32_e32 v161, v45, v45
	v_fmac_f32_e32 v189, v37, v37
	v_fmac_f32_e32 v161, v46, v46
	v_fmac_f32_e32 v189, v38, v38
	v_fmac_f32_e32 v161, v47, v47
	v_fmac_f32_e32 v189, v39, v39
	v_add_f32_e32 v161, v161, v189
	s_waitcnt vmcnt(2)
	v_lshlrev_b32_e32 v136, 16, v172
	v_and_b32_e32 v137, s63, v172
	v_pk_add_f32 v[28:29], v[28:29], v[136:137]
	v_lshlrev_b32_e32 v138, 16, v173
	v_and_b32_e32 v139, s63, v173
	v_pk_add_f32 v[30:31], v[30:31], v[138:139]
	v_lshlrev_b32_e32 v190, 16, v174
	v_and_b32_e32 v191, s63, v174
	v_pk_add_f32 v[24:25], v[24:25], v[190:191]
	v_lshlrev_b32_e32 v136, 16, v175
	v_and_b32_e32 v137, s63, v175
	v_pk_add_f32 v[26:27], v[26:27], v[136:137]
	v_lshlrev_b32_e32 v138, 16, v176
	v_and_b32_e32 v139, s63, v176
	v_pk_add_f32 v[20:21], v[20:21], v[138:139]
	v_lshlrev_b32_e32 v190, 16, v177
	v_and_b32_e32 v191, s63, v177
	v_pk_add_f32 v[22:23], v[22:23], v[190:191]
	v_lshlrev_b32_e32 v136, 16, v178
	v_and_b32_e32 v137, s63, v178
	v_pk_add_f32 v[16:17], v[16:17], v[136:137]
	v_lshlrev_b32_e32 v138, 16, v179
	v_and_b32_e32 v139, s63, v179
	v_pk_add_f32 v[18:19], v[18:19], v[138:139]
	v_mul_f32_e32 v162, v24, v24
	v_mul_f32_e32 v189, v16, v16
	v_fmac_f32_e32 v162, v25, v25
	v_fmac_f32_e32 v189, v17, v17
	v_fmac_f32_e32 v162, v26, v26
	v_fmac_f32_e32 v189, v18, v18
	v_fmac_f32_e32 v162, v27, v27
	v_fmac_f32_e32 v189, v19, v19
	v_fmac_f32_e32 v162, v28, v28
	v_fmac_f32_e32 v189, v20, v20
	v_fmac_f32_e32 v162, v29, v29
	v_fmac_f32_e32 v189, v21, v21
	v_fmac_f32_e32 v162, v30, v30
	v_fmac_f32_e32 v189, v22, v22
	v_fmac_f32_e32 v162, v31, v31
	v_fmac_f32_e32 v189, v23, v23
	v_add_f32_e32 v162, v162, v189
	s_waitcnt vmcnt(0)
	v_lshlrev_b32_e32 v190, 16, v180
	v_and_b32_e32 v191, s63, v180
	v_pk_add_f32 v[12:13], v[12:13], v[190:191]
	v_lshlrev_b32_e32 v136, 16, v181
	v_and_b32_e32 v137, s63, v181
	v_pk_add_f32 v[14:15], v[14:15], v[136:137]
	v_lshlrev_b32_e32 v138, 16, v182
	v_and_b32_e32 v139, s63, v182
	v_pk_add_f32 v[8:9], v[8:9], v[138:139]
	v_lshlrev_b32_e32 v190, 16, v183
	v_and_b32_e32 v191, s63, v183
	v_pk_add_f32 v[10:11], v[10:11], v[190:191]
	v_lshlrev_b32_e32 v136, 16, v184
	v_and_b32_e32 v137, s63, v184
	v_pk_add_f32 v[4:5], v[4:5], v[136:137]
	v_lshlrev_b32_e32 v138, 16, v185
	v_and_b32_e32 v139, s63, v185
	v_pk_add_f32 v[6:7], v[6:7], v[138:139]
	v_lshlrev_b32_e32 v190, 16, v186
	v_and_b32_e32 v191, s63, v186
	v_pk_add_f32 v[0:1], v[0:1], v[190:191]
	v_lshlrev_b32_e32 v136, 16, v187
	v_and_b32_e32 v137, s63, v187
	v_pk_add_f32 v[2:3], v[2:3], v[136:137]
	v_mul_f32_e32 v163, v8, v8
	v_mul_f32_e32 v189, v0, v0
	v_fmac_f32_e32 v163, v9, v9
	v_fmac_f32_e32 v189, v1, v1
	v_fmac_f32_e32 v163, v10, v10
	v_fmac_f32_e32 v189, v2, v2
	v_fmac_f32_e32 v163, v11, v11
	v_fmac_f32_e32 v189, v3, v3
	v_fmac_f32_e32 v163, v12, v12
	v_fmac_f32_e32 v189, v4, v4
	v_fmac_f32_e32 v163, v13, v13
	v_fmac_f32_e32 v189, v5, v5
	v_fmac_f32_e32 v163, v14, v14
	v_fmac_f32_e32 v189, v6, v6
	v_fmac_f32_e32 v163, v15, v15
	v_fmac_f32_e32 v189, v7, v7
	v_add_f32_e32 v163, v163, v189
	ds_bpermute_b32 v136, v134, v156
	ds_bpermute_b32 v137, v134, v157
	ds_bpermute_b32 v138, v134, v158
	ds_bpermute_b32 v139, v134, v159
	ds_bpermute_b32 v188, v134, v160
	ds_bpermute_b32 v189, v134, v161
	ds_bpermute_b32 v190, v134, v162
	ds_bpermute_b32 v191, v134, v163
	s_waitcnt lgkmcnt(0)
	v_add_f32_e32 v156, v156, v136
	v_add_f32_e32 v157, v157, v137
	v_add_f32_e32 v158, v158, v138
	v_add_f32_e32 v159, v159, v139
	v_add_f32_e32 v160, v160, v188
	v_add_f32_e32 v161, v161, v189
	v_add_f32_e32 v162, v162, v190
	v_add_f32_e32 v163, v163, v191
	ds_bpermute_b32 v136, v135, v156
	ds_bpermute_b32 v137, v135, v157
	ds_bpermute_b32 v138, v135, v158
	ds_bpermute_b32 v139, v135, v159
	ds_bpermute_b32 v188, v135, v160
	ds_bpermute_b32 v189, v135, v161
	ds_bpermute_b32 v190, v135, v162
	ds_bpermute_b32 v191, v135, v163
	s_waitcnt lgkmcnt(0)
	v_add_f32_e32 v156, v156, v136
	v_add_f32_e32 v157, v157, v137
	v_add_f32_e32 v158, v158, v138
	v_add_f32_e32 v159, v159, v139
	v_add_f32_e32 v160, v160, v188
	v_add_f32_e32 v161, v161, v189
	v_add_f32_e32 v162, v162, v190
	v_add_f32_e32 v163, v163, v191
	s_and_saveexec_b64 s[66:67], s[64:65]
	global_store_dword v130, v156, s[8:9] sc1
	global_store_dword v130, v157, s[8:9] offset:1024 sc1
	global_store_dword v130, v158, s[8:9] offset:2048 sc1
	global_store_dword v130, v159, s[8:9] offset:3072 sc1
	global_store_dword v130, v160, s[74:75] sc1
	global_store_dword v130, v161, s[74:75] offset:1024 sc1
	global_store_dword v130, v162, s[74:75] offset:2048 sc1
	global_store_dword v130, v163, s[74:75] offset:3072 sc1
	s_or_b64 exec, exec, s[66:67]
	global_load_dwordx4 v[210:213], v132, s[22:23]
	global_load_dwordx4 v[214:217], v132, s[22:23] offset:16
	global_load_dwordx4 v[218:221], v132, s[22:23] offset:128
	global_load_dwordx4 v[222:225], v132, s[22:23] offset:144
	s_waitcnt vmcnt(0)
	s_barrier
	s_barrier
	s_cmpk_gt_u32 s17, 0xff
	s_cbranch_scc1 .Lf11_w1_a
	s_and_saveexec_b64 s[40:41], s[14:15]
	s_cbranch_execz .Lf11_t0_done
	v_mov_b32_e32 v133, 0
	v_mov_b32_e32 v189, 1
	global_atomic_add v133, v189, s[78:79]
	s_mov_b32 s80, 0
